# K-loop scalar bookkeeping after each phase-closing barrier (m0/base adds, loop counter and compare) moved into the preceding MFMA block, one per MFMA gap, in all eight GEMM K-loops; on top of v62
# speedup vs baseline: 1.0092x; 1.0092x over previous
; #define PG8_STAGE(bufoff, gbase, voff) do { _Pragma("unroll") for (int _i = 0; _i < 2; ++_i) \
;         __builtin_amdgcn_global_load_lds((const unsigned*)((const char*)(gbase) + (voff)[_i]), (PG8_LAS unsigned*)(lds + (bufoff) + ldsw + _i * 8192), 16, 0, 0); } while (0)
; #define PG8_LDA(dst, b, h) do { _Pragma("unroll") for (int m = 0; m < 4; ++m) _Pragma("unroll") for (int k = 0; k < 2; ++k) dst[m][k] = *(const PG8_LAS bf16x8*)(lds + PG8_SA(b, h) + aoff + m * 2048 + k * 1024); } while (0)
; #define PG8_LDB(dst, b, h) do { _Pragma("unroll") for (int n = 0; n < 2; ++n) _Pragma("unroll") for (int k = 0; k < 2; ++k) dst[n][k] = *(const PG8_LAS bf16x8*)(lds + PG8_SB(b, h) + boff + n * 2048 + k * 1024); } while (0)
; #define PG8_MMA(ai, bj, At, Bt) do { __builtin_amdgcn_s_setprio(1); _Pragma("unroll") for (int m = 0; m < 4; ++m) _Pragma("unroll") for (int n = 0; n < 2; ++n) _Pragma("unroll") for (int k = 0; k < 2; ++k) \
;         acc[ai][bj][m][n] = __builtin_amdgcn_mfma_f32_16x16x32_bf16(Bt[n][k], At[m][k], acc[ai][bj][m][n], 0, 0, 0); __builtin_amdgcn_s_setprio(0); } while (0)
; #define PG8_WAIT_V(n) asm volatile("s_waitcnt vmcnt(" #n ")" ::: "memory")
; #define PG8_WAIT_L(n) asm volatile("s_waitcnt lgkmcnt(" #n ")" ::: "memory")
; #define PG8_BAR __builtin_amdgcn_s_barrier()
; template <class Epi, bool ALIGN_EPI, bool ABLK = false>
; __device__ __forceinline__ void gemm_phase(PG8_LAS unsigned char* lds, const Gemm g, const StaticOrder& S, const Epi& E) {
;     ...
;         for (int t = 0; t < nt; t += 2) {
;             const bool last = (t == nt - 2);
;             const char* a1 = cA + (size_t)(t + 1) * kstepA;
;             const char* a2 = last ? nA : cA + (size_t)(t + 2) * kstepA; const char* b2 = last ? nB : cB + (size_t)(t + 2) * kstepB;
;             const char* a3 = a2 + kstepA; const char* b3 = b2 + kstepB;
;             PG8_LDB(B0, 0, 0); PG8_LDB(B1, 0, 1); PG8_SCHED; PG8_LDA(At, 0, 0); PG8_STAGE(PG8_SA(1, 1), a1 + hstepA, voffA);
;             PG8_WAIT_V(8); PG8_WAIT_L(0); PG8_BAR; PG8_MMA(0, 0, At, B0); PG8_MMA(0, 1, At, B1); PG8_BAR; PG8_SCHED;
;             PG8_LDA(At, 0, 1); PG8_STAGE(PG8_SB(0, 0), b2, voffB); PG8_STAGE(PG8_SB(0, 1), b2 + hstepB, voffB); PG8_STAGE(PG8_SA(0, 0), a2, voffA);
;             PG8_WAIT_V(8); PG8_WAIT_L(0); PG8_BAR; PG8_MMA(1, 0, At, B0); PG8_MMA(1, 1, At, B1); PG8_BAR; PG8_SCHED;
.LBB0_402:
	ds_read_b128 v[132:135], v251
	ds_read_b128 v[136:139], v251 offset:1024
	ds_read_b128 v[140:143], v251 offset:2048
	ds_read_b128 v[186:189], v251 offset:3072
	ds_read_b128 v[190:193], v251 offset:16384
	ds_read_b128 v[194:197], v251 offset:17408
	ds_read_b128 v[198:201], v251 offset:18432
	ds_read_b128 v[202:205], v251 offset:19456
	s_add_u32 s48, s24, s46
	s_addc_u32 s49, s25, s47
	s_cmp_eq_u32 s70, 12
	s_cselect_b32 s85, s41, s49
	s_cselect_b32 s84, s66, s48
	s_cselect_b32 s49, s39, s69
	s_cselect_b32 s48, s67, s68
	s_mov_b64 s[74:75], 0xc000
	s_add_i32 m0, s55, 0xc000
	s_mov_b64 s[74:75], 0xe000
	ds_read_b128 v[206:209], v183
	ds_read_b128 v[210:213], v183 offset:1024
	ds_read_b128 v[214:217], v183 offset:2048
	ds_read_b128 v[218:221], v183 offset:3072
	ds_read_b128 v[222:225], v183 offset:4096
	ds_read_b128 v[226:229], v183 offset:5120
	ds_read_b128 v[230:233], v183 offset:6144
	ds_read_b128 v[234:237], v183 offset:7168
	global_load_lds_dwordx4 v249, s[82:83]
	s_add_i32 m0, s55, 0xe000
	s_nop 0
	global_load_lds_dwordx4 v250, s[82:83]
	s_waitcnt vmcnt(8)
	s_waitcnt lgkmcnt(0)
	s_barrier
	s_setprio 1
	s_waitcnt lgkmcnt(0)
	v_mfma_f32_16x16x32_bf16 v[126:129], v[132:135], v[206:209], v[126:129]
	v_mfma_f32_16x16x32_bf16 v[122:125], v[140:143], v[206:209], v[122:125]
	v_mfma_f32_16x16x32_bf16 v[118:121], v[132:135], v[214:217], v[118:121]
	v_mfma_f32_16x16x32_bf16 v[114:117], v[140:143], v[214:217], v[114:117]
	v_mfma_f32_16x16x32_bf16 v[110:113], v[132:135], v[222:225], v[110:113]
	v_mfma_f32_16x16x32_bf16 v[106:109], v[140:143], v[222:225], v[106:109]
	v_mfma_f32_16x16x32_bf16 v[102:105], v[132:135], v[230:233], v[102:105]
	v_mfma_f32_16x16x32_bf16 v[98:101], v[140:143], v[230:233], v[98:101]
	v_mfma_f32_16x16x32_bf16 v[126:129], v[136:139], v[210:213], v[126:129]
	v_mfma_f32_16x16x32_bf16 v[122:125], v[186:189], v[210:213], v[122:125]
	v_mfma_f32_16x16x32_bf16 v[118:121], v[136:139], v[218:221], v[118:121]
	v_mfma_f32_16x16x32_bf16 v[114:117], v[186:189], v[218:221], v[114:117]
	v_mfma_f32_16x16x32_bf16 v[110:113], v[136:139], v[226:229], v[110:113]
	v_mfma_f32_16x16x32_bf16 v[106:109], v[186:189], v[226:229], v[106:109]
	v_mfma_f32_16x16x32_bf16 v[102:105], v[136:139], v[234:237], v[102:105]
	v_mfma_f32_16x16x32_bf16 v[98:101], v[186:189], v[234:237], v[98:101]
	s_setprio 0
	s_setprio 1
	v_mfma_f32_16x16x32_bf16 v[94:97], v[190:193], v[206:209], v[94:97]
	s_add_i32 s71, s64, s9
	v_mfma_f32_16x16x32_bf16 v[90:93], v[198:201], v[206:209], v[90:93]
	s_mov_b32 m0, s71
	v_mfma_f32_16x16x32_bf16 v[86:89], v[190:193], v[214:217], v[86:89]
	v_mfma_f32_16x16x32_bf16 v[82:85], v[198:201], v[214:217], v[82:85]
	v_mfma_f32_16x16x32_bf16 v[78:81], v[190:193], v[222:225], v[78:81]
	v_mfma_f32_16x16x32_bf16 v[74:77], v[198:201], v[222:225], v[74:77]
	v_mfma_f32_16x16x32_bf16 v[70:73], v[190:193], v[230:233], v[70:73]
	v_mfma_f32_16x16x32_bf16 v[66:69], v[198:201], v[230:233], v[66:69]
	v_mfma_f32_16x16x32_bf16 v[94:97], v[194:197], v[210:213], v[94:97]
	v_mfma_f32_16x16x32_bf16 v[90:93], v[202:205], v[210:213], v[90:93]
	v_mfma_f32_16x16x32_bf16 v[86:89], v[194:197], v[218:221], v[86:89]
	v_mfma_f32_16x16x32_bf16 v[82:85], v[202:205], v[218:221], v[82:85]
	v_mfma_f32_16x16x32_bf16 v[78:81], v[194:197], v[226:229], v[78:81]
	v_mfma_f32_16x16x32_bf16 v[74:77], v[202:205], v[226:229], v[74:77]
	v_mfma_f32_16x16x32_bf16 v[70:73], v[194:197], v[234:237], v[70:73]
	v_mfma_f32_16x16x32_bf16 v[66:69], v[202:205], v[234:237], v[66:69]
	s_setprio 0
	s_barrier
	ds_read_b128 v[206:209], v183 offset:16384
	ds_read_b128 v[210:213], v183 offset:17408
	ds_read_b128 v[214:217], v183 offset:18432
	ds_read_b128 v[218:221], v183 offset:19456
	ds_read_b128 v[222:225], v183 offset:20480
	ds_read_b128 v[226:229], v183 offset:21504
	ds_read_b128 v[230:233], v183 offset:22528
	ds_read_b128 v[234:237], v183 offset:23552
	global_load_lds_dwordx4 v148, s[48:49]
	s_add_i32 m0, s71, 0x2000
	s_add_u32 s74, s48, 0x40000
	s_addc_u32 s75, s49, 0
	s_add_i32 s71, s65, s9
	global_load_lds_dwordx4 v150, s[48:49]
	s_mov_b32 m0, s71
	s_nop 0
	global_load_lds_dwordx4 v148, s[74:75]
	s_add_i32 m0, s71, 0x2000
	s_nop 0
	global_load_lds_dwordx4 v150, s[74:75]
	s_mov_b32 m0, s55
	s_mov_b64 s[72:73], 0x2000
	global_load_lds_dwordx4 v146, s[84:85]
	s_mov_b32 m0, s56
	s_nop 0
	global_load_lds_dwordx4 v244, s[84:85]
	s_waitcnt vmcnt(8)
	s_waitcnt lgkmcnt(0)
	s_barrier
	s_setprio 1
	s_waitcnt lgkmcnt(0)
	v_mfma_f32_16x16x32_bf16 v[62:65], v[132:135], v[206:209], v[62:65]
	v_mfma_f32_16x16x32_bf16 v[58:61], v[140:143], v[206:209], v[58:61]
	v_mfma_f32_16x16x32_bf16 v[54:57], v[132:135], v[214:217], v[54:57]
	v_mfma_f32_16x16x32_bf16 v[50:53], v[140:143], v[214:217], v[50:53]
	v_mfma_f32_16x16x32_bf16 v[46:49], v[132:135], v[222:225], v[46:49]
	v_mfma_f32_16x16x32_bf16 v[42:45], v[140:143], v[222:225], v[42:45]
	v_mfma_f32_16x16x32_bf16 v[38:41], v[132:135], v[230:233], v[38:41]
	v_mfma_f32_16x16x32_bf16 v[34:37], v[140:143], v[230:233], v[34:37]
	v_mfma_f32_16x16x32_bf16 v[62:65], v[136:139], v[210:213], v[62:65]
	v_mfma_f32_16x16x32_bf16 v[58:61], v[186:189], v[210:213], v[58:61]
	v_mfma_f32_16x16x32_bf16 v[54:57], v[136:139], v[218:221], v[54:57]
	v_mfma_f32_16x16x32_bf16 v[50:53], v[186:189], v[218:221], v[50:53]
	v_mfma_f32_16x16x32_bf16 v[46:49], v[136:139], v[226:229], v[46:49]
	v_mfma_f32_16x16x32_bf16 v[42:45], v[186:189], v[226:229], v[42:45]
	v_mfma_f32_16x16x32_bf16 v[38:41], v[136:139], v[234:237], v[38:41]
	v_mfma_f32_16x16x32_bf16 v[34:37], v[186:189], v[234:237], v[34:37]
	s_setprio 0
	s_setprio 1
	v_mfma_f32_16x16x32_bf16 v[30:33], v[190:193], v[206:209], v[30:33]
	s_add_i32 s71, 0, 0x18000
	v_mfma_f32_16x16x32_bf16 v[26:29], v[198:201], v[206:209], v[26:29]
	s_add_i32 s74, 0, 0x1c000
	v_mfma_f32_16x16x32_bf16 v[22:25], v[190:193], v[214:217], v[22:25]
	v_mfma_f32_16x16x32_bf16 v[18:21], v[198:201], v[214:217], v[18:21]
	v_mfma_f32_16x16x32_bf16 v[14:17], v[190:193], v[222:225], v[14:17]
	v_mfma_f32_16x16x32_bf16 v[10:13], v[198:201], v[222:225], v[10:13]
	v_mfma_f32_16x16x32_bf16 v[6:9], v[190:193], v[230:233], v[6:9]
	v_mfma_f32_16x16x32_bf16 v[2:5], v[198:201], v[230:233], v[2:5]
	v_mfma_f32_16x16x32_bf16 v[30:33], v[194:197], v[210:213], v[30:33]
	v_mfma_f32_16x16x32_bf16 v[26:29], v[202:205], v[210:213], v[26:29]
	v_mfma_f32_16x16x32_bf16 v[22:25], v[194:197], v[218:221], v[22:25]
	v_mfma_f32_16x16x32_bf16 v[18:21], v[202:205], v[218:221], v[18:21]
	v_mfma_f32_16x16x32_bf16 v[14:17], v[194:197], v[226:229], v[14:17]
	v_mfma_f32_16x16x32_bf16 v[10:13], v[202:205], v[226:229], v[10:13]
	v_mfma_f32_16x16x32_bf16 v[6:9], v[194:197], v[234:237], v[6:9]
	v_mfma_f32_16x16x32_bf16 v[2:5], v[202:205], v[234:237], v[2:5]
	s_setprio 0
	s_barrier
; #define PG8_STAGE(bufoff, gbase, voff) do { _Pragma("unroll") for (int _i = 0; _i < 2; ++_i) \
;         __builtin_amdgcn_global_load_lds((const unsigned*)((const char*)(gbase) + (voff)[_i]), (PG8_LAS unsigned*)(lds + (bufoff) + ldsw + _i * 8192), 16, 0, 0); } while (0)
; #define PG8_LDA(dst, b, h) do { _Pragma("unroll") for (int m = 0; m < 4; ++m) _Pragma("unroll") for (int k = 0; k < 2; ++k) dst[m][k] = *(const PG8_LAS bf16x8*)(lds + PG8_SA(b, h) + aoff + m * 2048 + k * 1024); } while (0)
; #define PG8_LDB(dst, b, h) do { _Pragma("unroll") for (int n = 0; n < 2; ++n) _Pragma("unroll") for (int k = 0; k < 2; ++k) dst[n][k] = *(const PG8_LAS bf16x8*)(lds + PG8_SB(b, h) + boff + n * 2048 + k * 1024); } while (0)
; #define PG8_MMA(ai, bj, At, Bt) do { __builtin_amdgcn_s_setprio(1); _Pragma("unroll") for (int m = 0; m < 4; ++m) _Pragma("unroll") for (int n = 0; n < 2; ++n) _Pragma("unroll") for (int k = 0; k < 2; ++k) \
;         acc[ai][bj][m][n] = __builtin_amdgcn_mfma_f32_16x16x32_bf16(Bt[n][k], At[m][k], acc[ai][bj][m][n], 0, 0, 0); __builtin_amdgcn_s_setprio(0); } while (0)
; #define PG8_WAIT_V(n) asm volatile("s_waitcnt vmcnt(" #n ")" ::: "memory")
; #define PG8_WAIT_L(n) asm volatile("s_waitcnt lgkmcnt(" #n ")" ::: "memory")
; #define PG8_BAR __builtin_amdgcn_s_barrier()
; #define PG8_SCHED __builtin_amdgcn_sched_barrier(0)
; template <class Epi, bool ALIGN_EPI, bool ABLK = false>
; __device__ __forceinline__ void gemm_phase(PG8_LAS unsigned char* lds, const Gemm g, const StaticOrder& S, const Epi& E) {
;     ...
;             PG8_LDB(B0, 1, 0); PG8_LDB(B1, 1, 1); PG8_SCHED; PG8_LDA(At, 1, 0); PG8_STAGE(PG8_SA(0, 1), a2 + hstepA, voffA);
;             PG8_WAIT_V(8); PG8_WAIT_L(0); PG8_BAR; PG8_MMA(0, 0, At, B0); PG8_MMA(0, 1, At, B1); PG8_BAR; PG8_SCHED;
;             PG8_LDA(At, 1, 1); PG8_STAGE(PG8_SB(1, 0), b3, voffB); PG8_STAGE(PG8_SB(1, 1), b3 + hstepB, voffB); PG8_STAGE(PG8_SA(1, 0), a3, voffA);
;             PG8_WAIT_V(8); PG8_WAIT_L(0); PG8_BAR; PG8_MMA(1, 0, At, B0); PG8_MMA(1, 1, At, B1); PG8_BAR; PG8_SCHED;
;         }
	ds_read_b128 v[132:135], v251 offset:32768
	ds_read_b128 v[136:139], v251 offset:33792
	ds_read_b128 v[140:143], v251 offset:34816
	ds_read_b128 v[186:189], v251 offset:35840
	ds_read_b128 v[190:193], v251 offset:49152
	ds_read_b128 v[194:197], v251 offset:50176
	ds_read_b128 v[198:201], v251 offset:51200
	ds_read_b128 v[202:205], v251 offset:52224
	s_mov_b64 s[72:73], 0x4000
	s_mov_b32 m0, s57
	s_mov_b64 s[72:73], 0x6000
	ds_read_b128 v[206:209], v183 offset:32768
	ds_read_b128 v[210:213], v183 offset:33792
	ds_read_b128 v[214:217], v183 offset:34816
	ds_read_b128 v[218:221], v183 offset:35840
	ds_read_b128 v[222:225], v183 offset:36864
	ds_read_b128 v[226:229], v183 offset:37888
	ds_read_b128 v[230:233], v183 offset:38912
	ds_read_b128 v[234:237], v183 offset:39936
	global_load_lds_dwordx4 v245, s[84:85]
	s_mov_b32 m0, s58
	s_nop 0
	global_load_lds_dwordx4 v246, s[84:85]
	s_waitcnt vmcnt(8)
	s_waitcnt lgkmcnt(0)
	s_barrier
	s_setprio 1
	s_waitcnt lgkmcnt(0)
	v_mfma_f32_16x16x32_bf16 v[126:129], v[132:135], v[206:209], v[126:129]
	v_mfma_f32_16x16x32_bf16 v[122:125], v[140:143], v[206:209], v[122:125]
	v_mfma_f32_16x16x32_bf16 v[118:121], v[132:135], v[214:217], v[118:121]
	v_mfma_f32_16x16x32_bf16 v[114:117], v[140:143], v[214:217], v[114:117]
	v_mfma_f32_16x16x32_bf16 v[110:113], v[132:135], v[222:225], v[110:113]
	v_mfma_f32_16x16x32_bf16 v[106:109], v[140:143], v[222:225], v[106:109]
	v_mfma_f32_16x16x32_bf16 v[102:105], v[132:135], v[230:233], v[102:105]
	v_mfma_f32_16x16x32_bf16 v[98:101], v[140:143], v[230:233], v[98:101]
	v_mfma_f32_16x16x32_bf16 v[126:129], v[136:139], v[210:213], v[126:129]
	v_mfma_f32_16x16x32_bf16 v[122:125], v[186:189], v[210:213], v[122:125]
	v_mfma_f32_16x16x32_bf16 v[118:121], v[136:139], v[218:221], v[118:121]
	v_mfma_f32_16x16x32_bf16 v[114:117], v[186:189], v[218:221], v[114:117]
	v_mfma_f32_16x16x32_bf16 v[110:113], v[136:139], v[226:229], v[110:113]
	v_mfma_f32_16x16x32_bf16 v[106:109], v[186:189], v[226:229], v[106:109]
	v_mfma_f32_16x16x32_bf16 v[102:105], v[136:139], v[234:237], v[102:105]
	v_mfma_f32_16x16x32_bf16 v[98:101], v[186:189], v[234:237], v[98:101]
	s_setprio 0
	s_setprio 1
	v_mfma_f32_16x16x32_bf16 v[94:97], v[190:193], v[206:209], v[94:97]
	s_add_i32 s71, s71, s9
	v_mfma_f32_16x16x32_bf16 v[90:93], v[198:201], v[206:209], v[90:93]
	s_add_u32 s86, s48, s28
	v_mfma_f32_16x16x32_bf16 v[86:89], v[190:193], v[214:217], v[86:89]
	s_addc_u32 s87, s49, s29
	v_mfma_f32_16x16x32_bf16 v[82:85], v[198:201], v[214:217], v[82:85]
	s_mov_b32 m0, s71
	v_mfma_f32_16x16x32_bf16 v[78:81], v[190:193], v[222:225], v[78:81]
	v_mfma_f32_16x16x32_bf16 v[74:77], v[198:201], v[222:225], v[74:77]
	v_mfma_f32_16x16x32_bf16 v[70:73], v[190:193], v[230:233], v[70:73]
	v_mfma_f32_16x16x32_bf16 v[66:69], v[198:201], v[230:233], v[66:69]
	v_mfma_f32_16x16x32_bf16 v[94:97], v[194:197], v[210:213], v[94:97]
	v_mfma_f32_16x16x32_bf16 v[90:93], v[202:205], v[210:213], v[90:93]
	v_mfma_f32_16x16x32_bf16 v[86:89], v[194:197], v[218:221], v[86:89]
	v_mfma_f32_16x16x32_bf16 v[82:85], v[202:205], v[218:221], v[82:85]
	v_mfma_f32_16x16x32_bf16 v[78:81], v[194:197], v[226:229], v[78:81]
	v_mfma_f32_16x16x32_bf16 v[74:77], v[202:205], v[226:229], v[74:77]
	v_mfma_f32_16x16x32_bf16 v[70:73], v[194:197], v[234:237], v[70:73]
	v_mfma_f32_16x16x32_bf16 v[66:69], v[202:205], v[234:237], v[66:69]
	s_setprio 0
	s_barrier
	ds_read_b128 v[206:209], v183 offset:49152
	ds_read_b128 v[210:213], v183 offset:50176
	ds_read_b128 v[214:217], v183 offset:51200
	ds_read_b128 v[218:221], v183 offset:52224
	ds_read_b128 v[222:225], v183 offset:53248
	ds_read_b128 v[226:229], v183 offset:54272
	ds_read_b128 v[230:233], v183 offset:55296
	ds_read_b128 v[234:237], v183 offset:56320
	global_load_lds_dwordx4 v148, s[86:87]
	s_add_i32 m0, s71, 0x2000
	s_add_u32 s48, s48, 0x40080
	s_addc_u32 s49, s49, 0
	s_add_i32 s71, s74, s9
	global_load_lds_dwordx4 v150, s[86:87]
	s_mov_b32 m0, s71
	s_nop 0
	global_load_lds_dwordx4 v148, s[48:49]
	s_add_i32 m0, s71, 0x2000
	s_nop 0
	global_load_lds_dwordx4 v150, s[48:49]
	s_mov_b32 m0, s59
	s_nop 0
	global_load_lds_dwordx4 v247, s[84:85]
	s_mov_b32 m0, s61
	s_nop 0
	global_load_lds_dwordx4 v248, s[84:85]
	s_waitcnt vmcnt(8)
	s_waitcnt lgkmcnt(0)
	s_barrier
	s_setprio 1
	s_waitcnt lgkmcnt(0)
	v_mfma_f32_16x16x32_bf16 v[62:65], v[132:135], v[206:209], v[62:65]
	v_mfma_f32_16x16x32_bf16 v[58:61], v[140:143], v[206:209], v[58:61]
	v_mfma_f32_16x16x32_bf16 v[54:57], v[132:135], v[214:217], v[54:57]
	v_mfma_f32_16x16x32_bf16 v[50:53], v[140:143], v[214:217], v[50:53]
	v_mfma_f32_16x16x32_bf16 v[46:49], v[132:135], v[222:225], v[46:49]
	v_mfma_f32_16x16x32_bf16 v[42:45], v[140:143], v[222:225], v[42:45]
	v_mfma_f32_16x16x32_bf16 v[38:41], v[132:135], v[230:233], v[38:41]
	v_mfma_f32_16x16x32_bf16 v[34:37], v[140:143], v[230:233], v[34:37]
	v_mfma_f32_16x16x32_bf16 v[62:65], v[136:139], v[210:213], v[62:65]
	v_mfma_f32_16x16x32_bf16 v[58:61], v[186:189], v[210:213], v[58:61]
	v_mfma_f32_16x16x32_bf16 v[54:57], v[136:139], v[218:221], v[54:57]
	v_mfma_f32_16x16x32_bf16 v[50:53], v[186:189], v[218:221], v[50:53]
	v_mfma_f32_16x16x32_bf16 v[46:49], v[136:139], v[226:229], v[46:49]
	v_mfma_f32_16x16x32_bf16 v[42:45], v[186:189], v[226:229], v[42:45]
	v_mfma_f32_16x16x32_bf16 v[38:41], v[136:139], v[234:237], v[38:41]
	v_mfma_f32_16x16x32_bf16 v[34:37], v[186:189], v[234:237], v[34:37]
	s_setprio 0
	s_setprio 1
	v_mfma_f32_16x16x32_bf16 v[30:33], v[190:193], v[206:209], v[30:33]
	s_add_i32 s70, s70, 2
	v_mfma_f32_16x16x32_bf16 v[26:29], v[198:201], v[206:209], v[26:29]
	s_add_u32 s68, s68, 0x100
	v_mfma_f32_16x16x32_bf16 v[22:25], v[190:193], v[214:217], v[22:25]
	s_addc_u32 s69, s69, 0
	v_mfma_f32_16x16x32_bf16 v[18:21], v[198:201], v[214:217], v[18:21]
	s_add_u32 s46, s46, 0x10000
	v_mfma_f32_16x16x32_bf16 v[14:17], v[190:193], v[222:225], v[14:17]
	s_addc_u32 s47, s47, 0
	v_mfma_f32_16x16x32_bf16 v[10:13], v[198:201], v[222:225], v[10:13]
	s_add_u32 s82, s82, 0x10000
	v_mfma_f32_16x16x32_bf16 v[6:9], v[190:193], v[230:233], v[6:9]
	s_addc_u32 s83, s83, 0
	v_mfma_f32_16x16x32_bf16 v[2:5], v[198:201], v[230:233], v[2:5]
	s_mov_b64 s[48:49], 0x10000
	v_mfma_f32_16x16x32_bf16 v[30:33], v[194:197], v[210:213], v[30:33]
	s_cmp_gt_u32 s70, 13
	v_mfma_f32_16x16x32_bf16 v[26:29], v[202:205], v[210:213], v[26:29]
	v_mfma_f32_16x16x32_bf16 v[22:25], v[194:197], v[218:221], v[22:25]
	v_mfma_f32_16x16x32_bf16 v[18:21], v[202:205], v[218:221], v[18:21]
	v_mfma_f32_16x16x32_bf16 v[14:17], v[194:197], v[226:229], v[14:17]
	v_mfma_f32_16x16x32_bf16 v[10:13], v[202:205], v[226:229], v[10:13]
	v_mfma_f32_16x16x32_bf16 v[6:9], v[194:197], v[234:237], v[6:9]
	v_mfma_f32_16x16x32_bf16 v[2:5], v[202:205], v[234:237], v[2:5]
	s_setprio 0
	s_barrier
	s_cbranch_scc0 .LBB0_402
	s_and_b64 vcc, exec, s[36:37]
	s_cbranch_vccz .LBB0_405
	s_barrier

; #define PG8_STAGE(bufoff, gbase, voff) do { _Pragma("unroll") for (int _i = 0; _i < 2; ++_i) \
;         __builtin_amdgcn_global_load_lds((const unsigned*)((const char*)(gbase) + (voff)[_i]), (PG8_LAS unsigned*)(lds + (bufoff) + ldsw + _i * 8192), 16, 0, 0); } while (0)
; #define PG8_LDA(dst, b, h) do { _Pragma("unroll") for (int m = 0; m < 4; ++m) _Pragma("unroll") for (int k = 0; k < 2; ++k) dst[m][k] = *(const PG8_LAS bf16x8*)(lds + PG8_SA(b, h) + aoff + m * 2048 + k * 1024); } while (0)
; #define PG8_LDB(dst, b, h) do { _Pragma("unroll") for (int n = 0; n < 2; ++n) _Pragma("unroll") for (int k = 0; k < 2; ++k) dst[n][k] = *(const PG8_LAS bf16x8*)(lds + PG8_SB(b, h) + boff + n * 2048 + k * 1024); } while (0)
; #define PG8_MMA(ai, bj, At, Bt) do { __builtin_amdgcn_s_setprio(1); _Pragma("unroll") for (int m = 0; m < 4; ++m) _Pragma("unroll") for (int n = 0; n < 2; ++n) _Pragma("unroll") for (int k = 0; k < 2; ++k) \
;         acc[ai][bj][m][n] = __builtin_amdgcn_mfma_f32_16x16x32_bf16(Bt[n][k], At[m][k], acc[ai][bj][m][n], 0, 0, 0); __builtin_amdgcn_s_setprio(0); } while (0)
; #define PG8_WAIT_V(n) asm volatile("s_waitcnt vmcnt(" #n ")" ::: "memory")
; #define PG8_WAIT_L(n) asm volatile("s_waitcnt lgkmcnt(" #n ")" ::: "memory")
; #define PG8_BAR __builtin_amdgcn_s_barrier()
; template <class Epi, bool ALIGN_EPI, bool ABLK = false>
; __device__ __forceinline__ void gemm_phase(PG8_LAS unsigned char* lds, const Gemm g, const StaticOrder& S, const Epi& E) {
;     ...
;         for (int t = 0; t < nt; t += 2) {
;             const bool last = (t == nt - 2);
;             const char* a1 = cA + (size_t)(t + 1) * kstepA;
;             const char* a2 = last ? nA : cA + (size_t)(t + 2) * kstepA; const char* b2 = last ? nB : cB + (size_t)(t + 2) * kstepB;
;             const char* a3 = a2 + kstepA; const char* b3 = b2 + kstepB;
;             PG8_LDB(B0, 0, 0); PG8_LDB(B1, 0, 1); PG8_SCHED; PG8_LDA(At, 0, 0); PG8_STAGE(PG8_SA(1, 1), a1 + hstepA, voffA);
;             PG8_WAIT_V(8); PG8_WAIT_L(0); PG8_BAR; PG8_MMA(0, 0, At, B0); PG8_MMA(0, 1, At, B1); PG8_BAR; PG8_SCHED;
;             PG8_LDA(At, 0, 1); PG8_STAGE(PG8_SB(0, 0), b2, voffB); PG8_STAGE(PG8_SB(0, 1), b2 + hstepB, voffB); PG8_STAGE(PG8_SA(0, 0), a2, voffA);
;             PG8_WAIT_V(8); PG8_WAIT_L(0); PG8_BAR; PG8_MMA(1, 0, At, B0); PG8_MMA(1, 1, At, B1); PG8_BAR; PG8_SCHED;
.LBB0_540:
	ds_read_b128 v[98:101], v238
	ds_read_b128 v[110:113], v238 offset:1024
	ds_read_b128 v[122:125], v238 offset:2048
	ds_read_b128 v[126:129], v238 offset:3072
	ds_read_b128 v[134:137], v239
	ds_read_b128 v[142:145], v239 offset:1024
	ds_read_b128 v[146:149], v239 offset:2048
	ds_read_b128 v[150:153], v239 offset:3072
	s_cmp_eq_u32 s78, 40
	s_cselect_b32 s81, s9, s51
	s_cselect_b32 s80, s8, s50
	s_cselect_b32 s53, s49, s55
	s_cselect_b32 s52, s48, s54
	s_movk_i32 s82, 0xc000
	v_lshl_add_u64 v[242:243], s[50:51], 0, v[194:195]
	s_mov_b32 s83, -1
	v_lshl_add_u64 v[244:245], v[242:243], 0, s[82:83]
	s_movk_i32 s82, 0xe000
	s_add_i32 m0, s61, 0xc000
	s_mov_b32 s83, -1
	ds_read_b128 v[154:157], v240
	ds_read_b128 v[166:169], v240 offset:1024
	ds_read_b128 v[170:173], v240 offset:2048
	ds_read_b128 v[174:177], v240 offset:3072
	ds_read_b128 v[178:181], v240 offset:4096
	ds_read_b128 v[182:185], v240 offset:5120
	ds_read_b128 v[186:189], v240 offset:6144
	ds_read_b128 v[190:193], v240 offset:7168
	global_load_lds_dwordx4 v[244:245], off
	v_lshl_add_u64 v[242:243], v[242:243], 0, s[82:83]
	s_add_i32 m0, s61, 0xe000
	s_nop 0
	global_load_lds_dwordx4 v[242:243], off
	s_waitcnt vmcnt(8)
	s_waitcnt lgkmcnt(0)
	s_barrier
	s_setprio 1
	s_waitcnt lgkmcnt(0)
	v_mfma_f32_16x16x32_bf16 v[162:165], v[98:101], v[154:157], v[162:165]
	v_mfma_f32_16x16x32_bf16 v[158:161], v[122:125], v[154:157], v[158:161]
	v_mfma_f32_16x16x32_bf16 v[118:121], v[98:101], v[170:173], v[118:121]
	v_mfma_f32_16x16x32_bf16 v[114:117], v[122:125], v[170:173], v[114:117]
	v_mfma_f32_16x16x32_bf16 v[94:97], v[98:101], v[178:181], v[94:97]
	v_mfma_f32_16x16x32_bf16 v[90:93], v[122:125], v[178:181], v[90:93]
	v_mfma_f32_16x16x32_bf16 v[78:81], v[98:101], v[186:189], v[78:81]
	v_mfma_f32_16x16x32_bf16 v[74:77], v[122:125], v[186:189], v[74:77]
	v_mfma_f32_16x16x32_bf16 v[162:165], v[110:113], v[166:169], v[162:165]
	v_mfma_f32_16x16x32_bf16 v[158:161], v[126:129], v[166:169], v[158:161]
	v_mfma_f32_16x16x32_bf16 v[118:121], v[110:113], v[174:177], v[118:121]
	v_mfma_f32_16x16x32_bf16 v[114:117], v[126:129], v[174:177], v[114:117]
	v_mfma_f32_16x16x32_bf16 v[94:97], v[110:113], v[182:185], v[94:97]
	v_mfma_f32_16x16x32_bf16 v[90:93], v[126:129], v[182:185], v[90:93]
	v_mfma_f32_16x16x32_bf16 v[78:81], v[110:113], v[190:193], v[78:81]
	v_mfma_f32_16x16x32_bf16 v[74:77], v[126:129], v[190:193], v[74:77]
	s_setprio 0
	s_setprio 1
	v_mfma_f32_16x16x32_bf16 v[138:141], v[134:137], v[154:157], v[138:141]
	s_add_i32 s79, s73, s59
	v_mfma_f32_16x16x32_bf16 v[130:133], v[146:149], v[154:157], v[130:133]
	s_mov_b32 m0, s79
	v_mfma_f32_16x16x32_bf16 v[106:109], v[134:137], v[170:173], v[106:109]
	v_mfma_f32_16x16x32_bf16 v[102:105], v[146:149], v[170:173], v[102:105]
	v_mfma_f32_16x16x32_bf16 v[86:89], v[134:137], v[178:181], v[86:89]
	v_mfma_f32_16x16x32_bf16 v[82:85], v[146:149], v[178:181], v[82:85]
	v_mfma_f32_16x16x32_bf16 v[70:73], v[134:137], v[186:189], v[70:73]
	v_mfma_f32_16x16x32_bf16 v[66:69], v[146:149], v[186:189], v[66:69]
	v_mfma_f32_16x16x32_bf16 v[138:141], v[142:145], v[166:169], v[138:141]
	v_mfma_f32_16x16x32_bf16 v[130:133], v[150:153], v[166:169], v[130:133]
	v_mfma_f32_16x16x32_bf16 v[106:109], v[142:145], v[174:177], v[106:109]
	v_mfma_f32_16x16x32_bf16 v[102:105], v[150:153], v[174:177], v[102:105]
	v_mfma_f32_16x16x32_bf16 v[86:89], v[142:145], v[182:185], v[86:89]
	v_mfma_f32_16x16x32_bf16 v[82:85], v[150:153], v[182:185], v[82:85]
	v_mfma_f32_16x16x32_bf16 v[70:73], v[142:145], v[190:193], v[70:73]
	v_mfma_f32_16x16x32_bf16 v[66:69], v[150:153], v[190:193], v[66:69]
	s_setprio 0
	s_barrier
	v_lshl_add_u64 v[242:243], s[52:53], 0, v[196:197]
	ds_read_b128 v[154:157], v240 offset:16384
	ds_read_b128 v[166:169], v240 offset:17408
	ds_read_b128 v[170:173], v240 offset:18432
	ds_read_b128 v[174:177], v240 offset:19456
	ds_read_b128 v[178:181], v240 offset:20480
	ds_read_b128 v[182:185], v240 offset:21504
	ds_read_b128 v[186:189], v240 offset:22528
	ds_read_b128 v[190:193], v240 offset:23552
	global_load_lds_dwordx4 v[242:243], off
	s_add_i32 m0, s79, 0x2000
	s_add_u32 s82, s52, 0xb0000
	v_lshl_add_u64 v[244:245], s[52:53], 0, v[198:199]
	s_addc_u32 s83, s53, 0
	s_add_i32 s79, s74, s59
	global_load_lds_dwordx4 v[244:245], off
	v_lshl_add_u64 v[246:247], s[82:83], 0, v[196:197]
	s_mov_b32 m0, s79
	s_nop 0
	global_load_lds_dwordx4 v[246:247], off
	v_lshl_add_u64 v[246:247], s[82:83], 0, v[198:199]
	s_add_i32 m0, s79, 0x2000
	s_nop 0
	global_load_lds_dwordx4 v[246:247], off
	v_lshl_add_u64 v[246:247], s[80:81], 0, v[194:195]
	s_mov_b32 m0, s61
	v_lshl_add_u64 v[248:249], v[246:247], 0, s[10:11]
	global_load_lds_dwordx4 v[246:247], off
	s_mov_b32 m0, s62
	s_nop 0
	global_load_lds_dwordx4 v[248:249], off
	s_waitcnt vmcnt(8)
	s_waitcnt lgkmcnt(0)
	s_barrier
; #define PG8_STAGE(bufoff, gbase, voff) do { _Pragma("unroll") for (int _i = 0; _i < 2; ++_i) \
;         __builtin_amdgcn_global_load_lds((const unsigned*)((const char*)(gbase) + (voff)[_i]), (PG8_LAS unsigned*)(lds + (bufoff) + ldsw + _i * 8192), 16, 0, 0); } while (0)
; #define PG8_LDA(dst, b, h) do { _Pragma("unroll") for (int m = 0; m < 4; ++m) _Pragma("unroll") for (int k = 0; k < 2; ++k) dst[m][k] = *(const PG8_LAS bf16x8*)(lds + PG8_SA(b, h) + aoff + m * 2048 + k * 1024); } while (0)
; #define PG8_LDB(dst, b, h) do { _Pragma("unroll") for (int n = 0; n < 2; ++n) _Pragma("unroll") for (int k = 0; k < 2; ++k) dst[n][k] = *(const PG8_LAS bf16x8*)(lds + PG8_SB(b, h) + boff + n * 2048 + k * 1024); } while (0)
; #define PG8_MMA(ai, bj, At, Bt) do { __builtin_amdgcn_s_setprio(1); _Pragma("unroll") for (int m = 0; m < 4; ++m) _Pragma("unroll") for (int n = 0; n < 2; ++n) _Pragma("unroll") for (int k = 0; k < 2; ++k) \
;         acc[ai][bj][m][n] = __builtin_amdgcn_mfma_f32_16x16x32_bf16(Bt[n][k], At[m][k], acc[ai][bj][m][n], 0, 0, 0); __builtin_amdgcn_s_setprio(0); } while (0)
; #define PG8_WAIT_V(n) asm volatile("s_waitcnt vmcnt(" #n ")" ::: "memory")
; #define PG8_WAIT_L(n) asm volatile("s_waitcnt lgkmcnt(" #n ")" ::: "memory")
; #define PG8_BAR __builtin_amdgcn_s_barrier()
; #define PG8_SCHED __builtin_amdgcn_sched_barrier(0)
; template <class Epi, bool ALIGN_EPI, bool ABLK = false>
; __device__ __forceinline__ void gemm_phase(PG8_LAS unsigned char* lds, const Gemm g, const StaticOrder& S, const Epi& E) {
;     ...
;             PG8_WAIT_V(8); PG8_WAIT_L(0); PG8_BAR; PG8_MMA(1, 0, At, B0); PG8_MMA(1, 1, At, B1); PG8_BAR; PG8_SCHED;
;             PG8_LDB(B0, 1, 0); PG8_LDB(B1, 1, 1); PG8_SCHED; PG8_LDA(At, 1, 0); PG8_STAGE(PG8_SA(0, 1), a2 + hstepA, voffA);
;             PG8_WAIT_V(8); PG8_WAIT_L(0); PG8_BAR; PG8_MMA(0, 0, At, B0); PG8_MMA(0, 1, At, B1); PG8_BAR; PG8_SCHED;
	s_setprio 1
	s_waitcnt lgkmcnt(0)
	v_mfma_f32_16x16x32_bf16 v[62:65], v[98:101], v[154:157], v[62:65]
	v_mfma_f32_16x16x32_bf16 v[58:61], v[122:125], v[154:157], v[58:61]
	v_mfma_f32_16x16x32_bf16 v[46:49], v[98:101], v[170:173], v[46:49]
	v_mfma_f32_16x16x32_bf16 v[42:45], v[122:125], v[170:173], v[42:45]
	v_mfma_f32_16x16x32_bf16 v[30:33], v[98:101], v[178:181], v[30:33]
	v_mfma_f32_16x16x32_bf16 v[26:29], v[122:125], v[178:181], v[26:29]
	v_mfma_f32_16x16x32_bf16 v[14:17], v[98:101], v[186:189], v[14:17]
	v_mfma_f32_16x16x32_bf16 v[10:13], v[122:125], v[186:189], v[10:13]
	v_mfma_f32_16x16x32_bf16 v[62:65], v[110:113], v[166:169], v[62:65]
	v_mfma_f32_16x16x32_bf16 v[58:61], v[126:129], v[166:169], v[58:61]
	v_mfma_f32_16x16x32_bf16 v[46:49], v[110:113], v[174:177], v[46:49]
	v_mfma_f32_16x16x32_bf16 v[42:45], v[126:129], v[174:177], v[42:45]
	v_mfma_f32_16x16x32_bf16 v[30:33], v[110:113], v[182:185], v[30:33]
	v_mfma_f32_16x16x32_bf16 v[26:29], v[126:129], v[182:185], v[26:29]
	v_mfma_f32_16x16x32_bf16 v[14:17], v[110:113], v[190:193], v[14:17]
	v_mfma_f32_16x16x32_bf16 v[10:13], v[126:129], v[190:193], v[10:13]
	s_setprio 0
	s_setprio 1
	v_mfma_f32_16x16x32_bf16 v[54:57], v[134:137], v[154:157], v[54:57]
	s_add_i32 s79, 0, 0x18000
	v_mfma_f32_16x16x32_bf16 v[50:53], v[146:149], v[154:157], v[50:53]
	s_add_i32 s80, 0, 0x1c000
	v_mfma_f32_16x16x32_bf16 v[38:41], v[134:137], v[170:173], v[38:41]
	v_mfma_f32_16x16x32_bf16 v[34:37], v[146:149], v[170:173], v[34:37]
	v_mfma_f32_16x16x32_bf16 v[22:25], v[134:137], v[178:181], v[22:25]
	v_mfma_f32_16x16x32_bf16 v[18:21], v[146:149], v[178:181], v[18:21]
	v_mfma_f32_16x16x32_bf16 v[6:9], v[134:137], v[186:189], v[6:9]
	v_mfma_f32_16x16x32_bf16 v[2:5], v[146:149], v[186:189], v[2:5]
	v_mfma_f32_16x16x32_bf16 v[54:57], v[142:145], v[166:169], v[54:57]
	v_mfma_f32_16x16x32_bf16 v[50:53], v[150:153], v[166:169], v[50:53]
	v_mfma_f32_16x16x32_bf16 v[38:41], v[142:145], v[174:177], v[38:41]
	v_mfma_f32_16x16x32_bf16 v[34:37], v[150:153], v[174:177], v[34:37]
	v_mfma_f32_16x16x32_bf16 v[22:25], v[142:145], v[182:185], v[22:25]
	v_mfma_f32_16x16x32_bf16 v[18:21], v[150:153], v[182:185], v[18:21]
	v_mfma_f32_16x16x32_bf16 v[6:9], v[142:145], v[190:193], v[6:9]
	v_mfma_f32_16x16x32_bf16 v[2:5], v[150:153], v[190:193], v[2:5]
	s_setprio 0
	s_barrier
	v_add_u32_e32 v126, s79, v230
	v_add_u32_e32 v150, s80, v230
	ds_read_b128 v[98:101], v126
	ds_read_b128 v[110:113], v126 offset:1024
	ds_read_b128 v[122:125], v126 offset:2048
	ds_read_b128 v[126:129], v126 offset:3072
	ds_read_b128 v[134:137], v150
	ds_read_b128 v[142:145], v150 offset:1024
	ds_read_b128 v[146:149], v150 offset:2048
	ds_read_b128 v[150:153], v150 offset:3072
	s_mov_b32 m0, s63
	v_lshl_add_u64 v[248:249], v[246:247], 0, s[12:13]
	ds_read_b128 v[154:157], v240 offset:32768
	ds_read_b128 v[166:169], v240 offset:33792
	ds_read_b128 v[170:173], v240 offset:34816
	ds_read_b128 v[174:177], v240 offset:35840
	ds_read_b128 v[178:181], v240 offset:36864
	ds_read_b128 v[182:185], v240 offset:37888
	ds_read_b128 v[186:189], v240 offset:38912
	ds_read_b128 v[190:193], v240 offset:39936
	global_load_lds_dwordx4 v[248:249], off
	v_lshl_add_u64 v[248:249], v[246:247], 0, s[24:25]
	s_mov_b32 m0, s64
	s_nop 0
	global_load_lds_dwordx4 v[248:249], off
	s_waitcnt vmcnt(8)
	s_waitcnt lgkmcnt(0)
	s_barrier
	s_setprio 1
	s_waitcnt lgkmcnt(0)
	v_mfma_f32_16x16x32_bf16 v[162:165], v[98:101], v[154:157], v[162:165]
	v_mfma_f32_16x16x32_bf16 v[158:161], v[122:125], v[154:157], v[158:161]
	v_mfma_f32_16x16x32_bf16 v[118:121], v[98:101], v[170:173], v[118:121]
	v_mfma_f32_16x16x32_bf16 v[114:117], v[122:125], v[170:173], v[114:117]
	v_mfma_f32_16x16x32_bf16 v[94:97], v[98:101], v[178:181], v[94:97]
	v_mfma_f32_16x16x32_bf16 v[90:93], v[122:125], v[178:181], v[90:93]
	v_mfma_f32_16x16x32_bf16 v[78:81], v[98:101], v[186:189], v[78:81]
	v_mfma_f32_16x16x32_bf16 v[74:77], v[122:125], v[186:189], v[74:77]
	v_mfma_f32_16x16x32_bf16 v[162:165], v[110:113], v[166:169], v[162:165]
	v_mfma_f32_16x16x32_bf16 v[158:161], v[126:129], v[166:169], v[158:161]
	v_mfma_f32_16x16x32_bf16 v[118:121], v[110:113], v[174:177], v[118:121]
	v_mfma_f32_16x16x32_bf16 v[114:117], v[126:129], v[174:177], v[114:117]
	v_mfma_f32_16x16x32_bf16 v[94:97], v[110:113], v[182:185], v[94:97]
	v_mfma_f32_16x16x32_bf16 v[90:93], v[126:129], v[182:185], v[90:93]
	v_mfma_f32_16x16x32_bf16 v[78:81], v[110:113], v[190:193], v[78:81]
	v_mfma_f32_16x16x32_bf16 v[74:77], v[126:129], v[190:193], v[74:77]
	s_setprio 0
	s_setprio 1
	v_mfma_f32_16x16x32_bf16 v[138:141], v[134:137], v[154:157], v[138:141]
	s_add_i32 s79, s79, s59
	v_mfma_f32_16x16x32_bf16 v[130:133], v[146:149], v[154:157], v[130:133]
	s_mov_b32 m0, s79
	v_mfma_f32_16x16x32_bf16 v[106:109], v[134:137], v[170:173], v[106:109]
	v_mfma_f32_16x16x32_bf16 v[102:105], v[146:149], v[170:173], v[102:105]
	v_mfma_f32_16x16x32_bf16 v[86:89], v[134:137], v[178:181], v[86:89]
	v_mfma_f32_16x16x32_bf16 v[82:85], v[146:149], v[178:181], v[82:85]
	v_mfma_f32_16x16x32_bf16 v[70:73], v[134:137], v[186:189], v[70:73]
	v_mfma_f32_16x16x32_bf16 v[66:69], v[146:149], v[186:189], v[66:69]
	v_mfma_f32_16x16x32_bf16 v[138:141], v[142:145], v[166:169], v[138:141]
	v_mfma_f32_16x16x32_bf16 v[130:133], v[150:153], v[166:169], v[130:133]
	v_mfma_f32_16x16x32_bf16 v[106:109], v[142:145], v[174:177], v[106:109]
	v_mfma_f32_16x16x32_bf16 v[102:105], v[150:153], v[174:177], v[102:105]
	v_mfma_f32_16x16x32_bf16 v[86:89], v[142:145], v[182:185], v[86:89]
	v_mfma_f32_16x16x32_bf16 v[82:85], v[150:153], v[182:185], v[82:85]
	v_mfma_f32_16x16x32_bf16 v[70:73], v[142:145], v[190:193], v[70:73]
	v_mfma_f32_16x16x32_bf16 v[66:69], v[150:153], v[190:193], v[66:69]
	s_setprio 0
	s_barrier
; #define PG8_STAGE(bufoff, gbase, voff) do { _Pragma("unroll") for (int _i = 0; _i < 2; ++_i) \
;         __builtin_amdgcn_global_load_lds((const unsigned*)((const char*)(gbase) + (voff)[_i]), (PG8_LAS unsigned*)(lds + (bufoff) + ldsw + _i * 8192), 16, 0, 0); } while (0)
; #define PG8_LDA(dst, b, h) do { _Pragma("unroll") for (int m = 0; m < 4; ++m) _Pragma("unroll") for (int k = 0; k < 2; ++k) dst[m][k] = *(const PG8_LAS bf16x8*)(lds + PG8_SA(b, h) + aoff + m * 2048 + k * 1024); } while (0)
; #define PG8_MMA(ai, bj, At, Bt) do { __builtin_amdgcn_s_setprio(1); _Pragma("unroll") for (int m = 0; m < 4; ++m) _Pragma("unroll") for (int n = 0; n < 2; ++n) _Pragma("unroll") for (int k = 0; k < 2; ++k) \
;         acc[ai][bj][m][n] = __builtin_amdgcn_mfma_f32_16x16x32_bf16(Bt[n][k], At[m][k], acc[ai][bj][m][n], 0, 0, 0); __builtin_amdgcn_s_setprio(0); } while (0)
; #define PG8_WAIT_V(n) asm volatile("s_waitcnt vmcnt(" #n ")" ::: "memory")
; #define PG8_WAIT_L(n) asm volatile("s_waitcnt lgkmcnt(" #n ")" ::: "memory")
; #define PG8_BAR __builtin_amdgcn_s_barrier()
; #define PG8_SCHED __builtin_amdgcn_sched_barrier(0)
; template <class Epi, bool ALIGN_EPI, bool ABLK = false>
; __device__ __forceinline__ void gemm_phase(PG8_LAS unsigned char* lds, const Gemm g, const StaticOrder& S, const Epi& E) {
;     ...
;             PG8_LDA(At, 1, 1); PG8_STAGE(PG8_SB(1, 0), b3, voffB); PG8_STAGE(PG8_SB(1, 1), b3 + hstepB, voffB); PG8_STAGE(PG8_SA(1, 0), a3, voffA);
;             PG8_WAIT_V(8); PG8_WAIT_L(0); PG8_BAR; PG8_MMA(1, 0, At, B0); PG8_MMA(1, 1, At, B1); PG8_BAR; PG8_SCHED;
;         }
	v_lshl_add_u64 v[242:243], v[242:243], 0, s[34:35]
	ds_read_b128 v[154:157], v240 offset:49152
	ds_read_b128 v[166:169], v240 offset:50176
	ds_read_b128 v[170:173], v240 offset:51200
	ds_read_b128 v[174:177], v240 offset:52224
	ds_read_b128 v[178:181], v240 offset:53248
	ds_read_b128 v[182:185], v240 offset:54272
	ds_read_b128 v[186:189], v240 offset:55296
	ds_read_b128 v[190:193], v240 offset:56320
	global_load_lds_dwordx4 v[242:243], off
	s_add_i32 m0, s79, 0x2000
	s_add_u32 s52, s52, 0xb0080
	v_lshl_add_u64 v[242:243], v[244:245], 0, s[34:35]
	s_addc_u32 s53, s53, 0
	s_add_i32 s79, s80, s59
	global_load_lds_dwordx4 v[242:243], off
	v_lshl_add_u64 v[242:243], s[52:53], 0, v[196:197]
	s_mov_b32 m0, s79
	s_nop 0
	global_load_lds_dwordx4 v[242:243], off
	v_lshl_add_u64 v[242:243], s[52:53], 0, v[198:199]
	s_add_i32 m0, s79, 0x2000
	s_nop 0
	global_load_lds_dwordx4 v[242:243], off
	v_lshl_add_u64 v[242:243], v[246:247], 0, s[36:37]
	s_mov_b32 m0, s67
	s_nop 0
	global_load_lds_dwordx4 v[242:243], off
	v_lshl_add_u64 v[242:243], v[246:247], 0, s[38:39]
	s_mov_b32 m0, s68
	s_nop 0
	global_load_lds_dwordx4 v[242:243], off
	s_waitcnt vmcnt(8)
	s_waitcnt lgkmcnt(0)
	s_barrier
	s_setprio 1
	s_waitcnt lgkmcnt(0)
	v_mfma_f32_16x16x32_bf16 v[62:65], v[98:101], v[154:157], v[62:65]
	v_mfma_f32_16x16x32_bf16 v[58:61], v[122:125], v[154:157], v[58:61]
	v_mfma_f32_16x16x32_bf16 v[46:49], v[98:101], v[170:173], v[46:49]
	v_mfma_f32_16x16x32_bf16 v[42:45], v[122:125], v[170:173], v[42:45]
	v_mfma_f32_16x16x32_bf16 v[30:33], v[98:101], v[178:181], v[30:33]
	v_mfma_f32_16x16x32_bf16 v[26:29], v[122:125], v[178:181], v[26:29]
	v_mfma_f32_16x16x32_bf16 v[14:17], v[98:101], v[186:189], v[14:17]
	v_mfma_f32_16x16x32_bf16 v[10:13], v[122:125], v[186:189], v[10:13]
	v_mfma_f32_16x16x32_bf16 v[62:65], v[110:113], v[166:169], v[62:65]
	v_mfma_f32_16x16x32_bf16 v[58:61], v[126:129], v[166:169], v[58:61]
	v_mfma_f32_16x16x32_bf16 v[46:49], v[110:113], v[174:177], v[46:49]
	v_mfma_f32_16x16x32_bf16 v[42:45], v[126:129], v[174:177], v[42:45]
	v_mfma_f32_16x16x32_bf16 v[30:33], v[110:113], v[182:185], v[30:33]
	v_mfma_f32_16x16x32_bf16 v[26:29], v[126:129], v[182:185], v[26:29]
	v_mfma_f32_16x16x32_bf16 v[14:17], v[110:113], v[190:193], v[14:17]
	v_mfma_f32_16x16x32_bf16 v[10:13], v[126:129], v[190:193], v[10:13]
	s_setprio 0
	s_setprio 1
	v_mfma_f32_16x16x32_bf16 v[54:57], v[134:137], v[154:157], v[54:57]
	s_add_i32 s78, s78, 2
	v_mfma_f32_16x16x32_bf16 v[50:53], v[146:149], v[154:157], v[50:53]
	s_add_u32 s54, s54, 0x100
	v_mfma_f32_16x16x32_bf16 v[38:41], v[134:137], v[170:173], v[38:41]
	s_addc_u32 s55, s55, 0
	v_mfma_f32_16x16x32_bf16 v[34:37], v[146:149], v[170:173], v[34:37]
	s_add_u32 s50, s50, 0x10000
	v_mfma_f32_16x16x32_bf16 v[22:25], v[134:137], v[178:181], v[22:25]
	s_addc_u32 s51, s51, 0
	v_mfma_f32_16x16x32_bf16 v[18:21], v[146:149], v[178:181], v[18:21]
	s_cmp_gt_u32 s78, 41
	v_mfma_f32_16x16x32_bf16 v[6:9], v[134:137], v[186:189], v[6:9]
	v_mfma_f32_16x16x32_bf16 v[2:5], v[146:149], v[186:189], v[2:5]
	v_mfma_f32_16x16x32_bf16 v[54:57], v[142:145], v[166:169], v[54:57]
	v_mfma_f32_16x16x32_bf16 v[50:53], v[150:153], v[166:169], v[50:53]
	v_mfma_f32_16x16x32_bf16 v[38:41], v[142:145], v[174:177], v[38:41]
	v_mfma_f32_16x16x32_bf16 v[34:37], v[150:153], v[174:177], v[34:37]
	v_mfma_f32_16x16x32_bf16 v[22:25], v[142:145], v[182:185], v[22:25]
	v_mfma_f32_16x16x32_bf16 v[18:21], v[150:153], v[182:185], v[18:21]
	v_mfma_f32_16x16x32_bf16 v[6:9], v[142:145], v[190:193], v[6:9]
	v_mfma_f32_16x16x32_bf16 v[2:5], v[150:153], v[190:193], v[2:5]
	s_setprio 0
	s_barrier
	s_cbranch_scc0 .LBB0_540
	s_and_b64 vcc, exec, s[40:41]
	s_cbranch_vccz .LBB0_543
	s_barrier

; #define PG8_STAGE(bufoff, gbase, voff) do { _Pragma("unroll") for (int _i = 0; _i < 2; ++_i) \
;         __builtin_amdgcn_global_load_lds((const unsigned*)((const char*)(gbase) + (voff)[_i]), (PG8_LAS unsigned*)(lds + (bufoff) + ldsw + _i * 8192), 16, 0, 0); } while (0)
; #define PG8_LDA(dst, b, h) do { _Pragma("unroll") for (int m = 0; m < 4; ++m) _Pragma("unroll") for (int k = 0; k < 2; ++k) dst[m][k] = *(const PG8_LAS bf16x8*)(lds + PG8_SA(b, h) + aoff + m * 2048 + k * 1024); } while (0)
; #define PG8_LDB(dst, b, h) do { _Pragma("unroll") for (int n = 0; n < 2; ++n) _Pragma("unroll") for (int k = 0; k < 2; ++k) dst[n][k] = *(const PG8_LAS bf16x8*)(lds + PG8_SB(b, h) + boff + n * 2048 + k * 1024); } while (0)
; #define PG8_MMA(ai, bj, At, Bt) do { __builtin_amdgcn_s_setprio(1); _Pragma("unroll") for (int m = 0; m < 4; ++m) _Pragma("unroll") for (int n = 0; n < 2; ++n) _Pragma("unroll") for (int k = 0; k < 2; ++k) \
;         acc[ai][bj][m][n] = __builtin_amdgcn_mfma_f32_16x16x32_bf16(Bt[n][k], At[m][k], acc[ai][bj][m][n], 0, 0, 0); __builtin_amdgcn_s_setprio(0); } while (0)
; #define PG8_WAIT_V(n) asm volatile("s_waitcnt vmcnt(" #n ")" ::: "memory")
; #define PG8_WAIT_L(n) asm volatile("s_waitcnt lgkmcnt(" #n ")" ::: "memory")
; #define PG8_BAR __builtin_amdgcn_s_barrier()
; template <class Epi, bool ALIGN_EPI, bool ABLK = false>
; __device__ __forceinline__ void gemm_phase(PG8_LAS unsigned char* lds, const Gemm g, const StaticOrder& S, const Epi& E) {
;     ...
;         for (int t = 0; t < nt; t += 2) {
;             const bool last = (t == nt - 2);
;             const char* a1 = cA + (size_t)(t + 1) * kstepA;
;             const char* a2 = last ? nA : cA + (size_t)(t + 2) * kstepA; const char* b2 = last ? nB : cB + (size_t)(t + 2) * kstepB;
;             const char* a3 = a2 + kstepA; const char* b3 = b2 + kstepB;
;             PG8_LDB(B0, 0, 0); PG8_LDB(B1, 0, 1); PG8_SCHED; PG8_LDA(At, 0, 0); PG8_STAGE(PG8_SA(1, 1), a1 + hstepA, voffA);
;             PG8_WAIT_V(8); PG8_WAIT_L(0); PG8_BAR; PG8_MMA(0, 0, At, B0); PG8_MMA(0, 1, At, B1); PG8_BAR; PG8_SCHED;
;             PG8_LDA(At, 0, 1); PG8_STAGE(PG8_SB(0, 0), b2, voffB); PG8_STAGE(PG8_SB(0, 1), b2 + hstepB, voffB); PG8_STAGE(PG8_SA(0, 0), a2, voffA);
;             PG8_WAIT_V(8); PG8_WAIT_L(0); PG8_BAR; PG8_MMA(1, 0, At, B0); PG8_MMA(1, 1, At, B1); PG8_BAR; PG8_SCHED;
.LBB0_818:
	ds_read_b128 v[132:135], v153
	ds_read_b128 v[136:139], v153 offset:1024
	ds_read_b128 v[140:143], v153 offset:2048
	ds_read_b128 v[144:147], v153 offset:3072
	ds_read_b128 v[148:151], v153 offset:16384
	ds_read_b128 v[178:181], v153 offset:17408
	ds_read_b128 v[182:185], v153 offset:18432
	ds_read_b128 v[212:215], v153 offset:19456
	s_add_u32 s12, s38, s10
	s_addc_u32 s13, s39, s11
	s_sub_u32 s98, s12, 0x10000
	s_subb_u32 s99, s13, 0
	s_cmp_eq_u32 s65, 12
	s_cselect_b32 s101, s33, s13
	s_cselect_b32 s100, s57, s12
	s_cselect_b32 s13, s55, s64
	s_cselect_b32 s12, s62, s63
	s_mov_b64 s[68:69], 0xc000
	s_add_i32 m0, s35, 0xc000
	s_mov_b64 s[68:69], 0xe000
	ds_read_b128 v[216:219], v205
	ds_read_b128 v[220:223], v205 offset:1024
	ds_read_b128 v[224:227], v205 offset:2048
	ds_read_b128 v[228:231], v205 offset:3072
	ds_read_b128 v[232:235], v205 offset:4096
	ds_read_b128 v[236:239], v205 offset:5120
	ds_read_b128 v[240:243], v205 offset:6144
	ds_read_b128 v[244:247], v205 offset:7168
	global_load_lds_dwordx4 v253, s[98:99]
	s_add_i32 m0, s35, 0xe000
	s_nop 0
	global_load_lds_dwordx4 v152, s[98:99]
	s_waitcnt vmcnt(8)
	s_waitcnt lgkmcnt(0)
	s_barrier
	s_setprio 1
	s_waitcnt lgkmcnt(0)
	v_mfma_f32_16x16x32_bf16 v[126:129], v[132:135], v[216:219], v[126:129]
	v_mfma_f32_16x16x32_bf16 v[122:125], v[140:143], v[216:219], v[122:125]
	v_mfma_f32_16x16x32_bf16 v[118:121], v[132:135], v[224:227], v[118:121]
	v_mfma_f32_16x16x32_bf16 v[114:117], v[140:143], v[224:227], v[114:117]
	v_mfma_f32_16x16x32_bf16 v[110:113], v[132:135], v[232:235], v[110:113]
	v_mfma_f32_16x16x32_bf16 v[106:109], v[140:143], v[232:235], v[106:109]
	v_mfma_f32_16x16x32_bf16 v[102:105], v[132:135], v[240:243], v[102:105]
	v_mfma_f32_16x16x32_bf16 v[98:101], v[140:143], v[240:243], v[98:101]
	v_mfma_f32_16x16x32_bf16 v[126:129], v[136:139], v[220:223], v[126:129]
	v_mfma_f32_16x16x32_bf16 v[122:125], v[144:147], v[220:223], v[122:125]
	v_mfma_f32_16x16x32_bf16 v[118:121], v[136:139], v[228:231], v[118:121]
	v_mfma_f32_16x16x32_bf16 v[114:117], v[144:147], v[228:231], v[114:117]
	v_mfma_f32_16x16x32_bf16 v[110:113], v[136:139], v[236:239], v[110:113]
	v_mfma_f32_16x16x32_bf16 v[106:109], v[144:147], v[236:239], v[106:109]
	v_mfma_f32_16x16x32_bf16 v[102:105], v[136:139], v[244:247], v[102:105]
	v_mfma_f32_16x16x32_bf16 v[98:101], v[144:147], v[244:247], v[98:101]
	s_setprio 0
	s_setprio 1
	v_mfma_f32_16x16x32_bf16 v[94:97], v[148:151], v[216:219], v[94:97]
	s_add_i32 s68, s42, s31
	v_mfma_f32_16x16x32_bf16 v[90:93], v[182:185], v[216:219], v[90:93]
	s_mov_b32 m0, s68
	v_mfma_f32_16x16x32_bf16 v[86:89], v[148:151], v[224:227], v[86:89]
	v_mfma_f32_16x16x32_bf16 v[82:85], v[182:185], v[224:227], v[82:85]
	v_mfma_f32_16x16x32_bf16 v[78:81], v[148:151], v[232:235], v[78:81]
	v_mfma_f32_16x16x32_bf16 v[74:77], v[182:185], v[232:235], v[74:77]
	v_mfma_f32_16x16x32_bf16 v[70:73], v[148:151], v[240:243], v[70:73]
	v_mfma_f32_16x16x32_bf16 v[66:69], v[182:185], v[240:243], v[66:69]
	v_mfma_f32_16x16x32_bf16 v[94:97], v[178:181], v[220:223], v[94:97]
	v_mfma_f32_16x16x32_bf16 v[90:93], v[212:215], v[220:223], v[90:93]
	v_mfma_f32_16x16x32_bf16 v[86:89], v[178:181], v[228:231], v[86:89]
	v_mfma_f32_16x16x32_bf16 v[82:85], v[212:215], v[228:231], v[82:85]
	v_mfma_f32_16x16x32_bf16 v[78:81], v[178:181], v[236:239], v[78:81]
	v_mfma_f32_16x16x32_bf16 v[74:77], v[212:215], v[236:239], v[74:77]
	v_mfma_f32_16x16x32_bf16 v[70:73], v[178:181], v[244:247], v[70:73]
	v_mfma_f32_16x16x32_bf16 v[66:69], v[212:215], v[244:247], v[66:69]
	s_setprio 0
	s_barrier
	ds_read_b128 v[216:219], v205 offset:16384
	ds_read_b128 v[220:223], v205 offset:17408
	ds_read_b128 v[224:227], v205 offset:18432
	ds_read_b128 v[228:231], v205 offset:19456
	ds_read_b128 v[232:235], v205 offset:20480
	ds_read_b128 v[236:239], v205 offset:21504
	ds_read_b128 v[240:243], v205 offset:22528
	ds_read_b128 v[244:247], v205 offset:23552
	global_load_lds_dwordx4 v156, s[12:13]
	s_add_i32 m0, s68, 0x2000
	s_add_u32 s68, s12, 0x40000
	s_addc_u32 s69, s13, 0
	s_add_i32 s70, s43, s31
	global_load_lds_dwordx4 v158, s[12:13]
	s_mov_b32 m0, s70
	s_nop 0
	global_load_lds_dwordx4 v156, s[68:69]
	s_add_i32 m0, s70, 0x2000
	s_nop 0
	global_load_lds_dwordx4 v158, s[68:69]
	s_mov_b32 m0, s35
	s_mov_b64 s[66:67], 0x2000
	global_load_lds_dwordx4 v154, s[100:101]
	s_mov_b32 m0, s18
	s_nop 0
	global_load_lds_dwordx4 v248, s[100:101]
	s_waitcnt vmcnt(8)
	s_waitcnt lgkmcnt(0)
	s_barrier
	s_setprio 1
	s_waitcnt lgkmcnt(0)
	v_mfma_f32_16x16x32_bf16 v[62:65], v[132:135], v[216:219], v[62:65]
	v_mfma_f32_16x16x32_bf16 v[58:61], v[140:143], v[216:219], v[58:61]
	v_mfma_f32_16x16x32_bf16 v[54:57], v[132:135], v[224:227], v[54:57]
	v_mfma_f32_16x16x32_bf16 v[50:53], v[140:143], v[224:227], v[50:53]
	v_mfma_f32_16x16x32_bf16 v[46:49], v[132:135], v[232:235], v[46:49]
	v_mfma_f32_16x16x32_bf16 v[42:45], v[140:143], v[232:235], v[42:45]
	v_mfma_f32_16x16x32_bf16 v[38:41], v[132:135], v[240:243], v[38:41]
	v_mfma_f32_16x16x32_bf16 v[34:37], v[140:143], v[240:243], v[34:37]
	v_mfma_f32_16x16x32_bf16 v[62:65], v[136:139], v[220:223], v[62:65]
	v_mfma_f32_16x16x32_bf16 v[58:61], v[144:147], v[220:223], v[58:61]
	v_mfma_f32_16x16x32_bf16 v[54:57], v[136:139], v[228:231], v[54:57]
	v_mfma_f32_16x16x32_bf16 v[50:53], v[144:147], v[228:231], v[50:53]
	v_mfma_f32_16x16x32_bf16 v[46:49], v[136:139], v[236:239], v[46:49]
	v_mfma_f32_16x16x32_bf16 v[42:45], v[144:147], v[236:239], v[42:45]
	v_mfma_f32_16x16x32_bf16 v[38:41], v[136:139], v[244:247], v[38:41]
	v_mfma_f32_16x16x32_bf16 v[34:37], v[144:147], v[244:247], v[34:37]
	s_setprio 0
	s_setprio 1
	v_mfma_f32_16x16x32_bf16 v[30:33], v[148:151], v[216:219], v[30:33]
	s_add_i32 s68, 0, 0x18000
	v_mfma_f32_16x16x32_bf16 v[26:29], v[182:185], v[216:219], v[26:29]
	s_add_i32 s69, 0, 0x1c000
	v_mfma_f32_16x16x32_bf16 v[22:25], v[148:151], v[224:227], v[22:25]
	v_mfma_f32_16x16x32_bf16 v[18:21], v[182:185], v[224:227], v[18:21]
	v_mfma_f32_16x16x32_bf16 v[14:17], v[148:151], v[232:235], v[14:17]
	v_mfma_f32_16x16x32_bf16 v[10:13], v[182:185], v[232:235], v[10:13]
	v_mfma_f32_16x16x32_bf16 v[6:9], v[148:151], v[240:243], v[6:9]
	v_mfma_f32_16x16x32_bf16 v[2:5], v[182:185], v[240:243], v[2:5]
	v_mfma_f32_16x16x32_bf16 v[30:33], v[178:181], v[220:223], v[30:33]
	v_mfma_f32_16x16x32_bf16 v[26:29], v[212:215], v[220:223], v[26:29]
	v_mfma_f32_16x16x32_bf16 v[22:25], v[178:181], v[228:231], v[22:25]
	v_mfma_f32_16x16x32_bf16 v[18:21], v[212:215], v[228:231], v[18:21]
	v_mfma_f32_16x16x32_bf16 v[14:17], v[178:181], v[236:239], v[14:17]
	v_mfma_f32_16x16x32_bf16 v[10:13], v[212:215], v[236:239], v[10:13]
	v_mfma_f32_16x16x32_bf16 v[6:9], v[178:181], v[244:247], v[6:9]
	v_mfma_f32_16x16x32_bf16 v[2:5], v[212:215], v[244:247], v[2:5]
	s_setprio 0
	s_barrier
; #define PG8_STAGE(bufoff, gbase, voff) do { _Pragma("unroll") for (int _i = 0; _i < 2; ++_i) \
;         __builtin_amdgcn_global_load_lds((const unsigned*)((const char*)(gbase) + (voff)[_i]), (PG8_LAS unsigned*)(lds + (bufoff) + ldsw + _i * 8192), 16, 0, 0); } while (0)
; #define PG8_LDA(dst, b, h) do { _Pragma("unroll") for (int m = 0; m < 4; ++m) _Pragma("unroll") for (int k = 0; k < 2; ++k) dst[m][k] = *(const PG8_LAS bf16x8*)(lds + PG8_SA(b, h) + aoff + m * 2048 + k * 1024); } while (0)
; #define PG8_LDB(dst, b, h) do { _Pragma("unroll") for (int n = 0; n < 2; ++n) _Pragma("unroll") for (int k = 0; k < 2; ++k) dst[n][k] = *(const PG8_LAS bf16x8*)(lds + PG8_SB(b, h) + boff + n * 2048 + k * 1024); } while (0)
; #define PG8_MMA(ai, bj, At, Bt) do { __builtin_amdgcn_s_setprio(1); _Pragma("unroll") for (int m = 0; m < 4; ++m) _Pragma("unroll") for (int n = 0; n < 2; ++n) _Pragma("unroll") for (int k = 0; k < 2; ++k) \
;         acc[ai][bj][m][n] = __builtin_amdgcn_mfma_f32_16x16x32_bf16(Bt[n][k], At[m][k], acc[ai][bj][m][n], 0, 0, 0); __builtin_amdgcn_s_setprio(0); } while (0)
; #define PG8_WAIT_V(n) asm volatile("s_waitcnt vmcnt(" #n ")" ::: "memory")
; #define PG8_WAIT_L(n) asm volatile("s_waitcnt lgkmcnt(" #n ")" ::: "memory")
; #define PG8_BAR __builtin_amdgcn_s_barrier()
; #define PG8_SCHED __builtin_amdgcn_sched_barrier(0)
; template <class Epi, bool ALIGN_EPI, bool ABLK = false>
; __device__ __forceinline__ void gemm_phase(PG8_LAS unsigned char* lds, const Gemm g, const StaticOrder& S, const Epi& E) {
;     ...
;             PG8_LDB(B0, 1, 0); PG8_LDB(B1, 1, 1); PG8_SCHED; PG8_LDA(At, 1, 0); PG8_STAGE(PG8_SA(0, 1), a2 + hstepA, voffA);
;             PG8_WAIT_V(8); PG8_WAIT_L(0); PG8_BAR; PG8_MMA(0, 0, At, B0); PG8_MMA(0, 1, At, B1); PG8_BAR; PG8_SCHED;
;             PG8_LDA(At, 1, 1); PG8_STAGE(PG8_SB(1, 0), b3, voffB); PG8_STAGE(PG8_SB(1, 1), b3 + hstepB, voffB); PG8_STAGE(PG8_SA(1, 0), a3, voffA);
;             PG8_WAIT_V(8); PG8_WAIT_L(0); PG8_BAR; PG8_MMA(1, 0, At, B0); PG8_MMA(1, 1, At, B1); PG8_BAR; PG8_SCHED;
;         }
	ds_read_b128 v[132:135], v153 offset:32768
	ds_read_b128 v[136:139], v153 offset:33792
	ds_read_b128 v[140:143], v153 offset:34816
	ds_read_b128 v[144:147], v153 offset:35840
	ds_read_b128 v[148:151], v153 offset:49152
	ds_read_b128 v[178:181], v153 offset:50176
	ds_read_b128 v[182:185], v153 offset:51200
	ds_read_b128 v[212:215], v153 offset:52224
	s_mov_b64 s[66:67], 0x4000
	s_mov_b32 m0, s28
	s_mov_b64 s[66:67], 0x6000
	ds_read_b128 v[216:219], v205 offset:32768
	ds_read_b128 v[220:223], v205 offset:33792
	ds_read_b128 v[224:227], v205 offset:34816
	ds_read_b128 v[228:231], v205 offset:35840
	ds_read_b128 v[232:235], v205 offset:36864
	ds_read_b128 v[236:239], v205 offset:37888
	ds_read_b128 v[240:243], v205 offset:38912
	ds_read_b128 v[244:247], v205 offset:39936
	global_load_lds_dwordx4 v249, s[100:101]
	s_mov_b32 m0, s29
	s_nop 0
	global_load_lds_dwordx4 v250, s[100:101]
	s_waitcnt vmcnt(8)
	s_waitcnt lgkmcnt(0)
	s_barrier
	s_setprio 1
	s_waitcnt lgkmcnt(0)
	v_mfma_f32_16x16x32_bf16 v[126:129], v[132:135], v[216:219], v[126:129]
	v_mfma_f32_16x16x32_bf16 v[122:125], v[140:143], v[216:219], v[122:125]
	v_mfma_f32_16x16x32_bf16 v[118:121], v[132:135], v[224:227], v[118:121]
	v_mfma_f32_16x16x32_bf16 v[114:117], v[140:143], v[224:227], v[114:117]
	v_mfma_f32_16x16x32_bf16 v[110:113], v[132:135], v[232:235], v[110:113]
	v_mfma_f32_16x16x32_bf16 v[106:109], v[140:143], v[232:235], v[106:109]
	v_mfma_f32_16x16x32_bf16 v[102:105], v[132:135], v[240:243], v[102:105]
	v_mfma_f32_16x16x32_bf16 v[98:101], v[140:143], v[240:243], v[98:101]
	v_mfma_f32_16x16x32_bf16 v[126:129], v[136:139], v[220:223], v[126:129]
	v_mfma_f32_16x16x32_bf16 v[122:125], v[144:147], v[220:223], v[122:125]
	v_mfma_f32_16x16x32_bf16 v[118:121], v[136:139], v[228:231], v[118:121]
	v_mfma_f32_16x16x32_bf16 v[114:117], v[144:147], v[228:231], v[114:117]
	v_mfma_f32_16x16x32_bf16 v[110:113], v[136:139], v[236:239], v[110:113]
	v_mfma_f32_16x16x32_bf16 v[106:109], v[144:147], v[236:239], v[106:109]
	v_mfma_f32_16x16x32_bf16 v[102:105], v[136:139], v[244:247], v[102:105]
	v_mfma_f32_16x16x32_bf16 v[98:101], v[144:147], v[244:247], v[98:101]
	s_setprio 0
	s_setprio 1
	v_mfma_f32_16x16x32_bf16 v[94:97], v[148:151], v[216:219], v[94:97]
	s_add_i32 s66, s68, s31
	v_mfma_f32_16x16x32_bf16 v[90:93], v[182:185], v[216:219], v[90:93]
	s_add_u32 s12, s12, s46
	v_mfma_f32_16x16x32_bf16 v[86:89], v[148:151], v[224:227], v[86:89]
	s_addc_u32 s13, s13, s47
	v_mfma_f32_16x16x32_bf16 v[82:85], v[182:185], v[224:227], v[82:85]
	s_mov_b32 m0, s66
	v_mfma_f32_16x16x32_bf16 v[78:81], v[148:151], v[232:235], v[78:81]
	v_mfma_f32_16x16x32_bf16 v[74:77], v[182:185], v[232:235], v[74:77]
	v_mfma_f32_16x16x32_bf16 v[70:73], v[148:151], v[240:243], v[70:73]
	v_mfma_f32_16x16x32_bf16 v[66:69], v[182:185], v[240:243], v[66:69]
	v_mfma_f32_16x16x32_bf16 v[94:97], v[178:181], v[220:223], v[94:97]
	v_mfma_f32_16x16x32_bf16 v[90:93], v[212:215], v[220:223], v[90:93]
	v_mfma_f32_16x16x32_bf16 v[86:89], v[178:181], v[228:231], v[86:89]
	v_mfma_f32_16x16x32_bf16 v[82:85], v[212:215], v[228:231], v[82:85]
	v_mfma_f32_16x16x32_bf16 v[78:81], v[178:181], v[236:239], v[78:81]
	v_mfma_f32_16x16x32_bf16 v[74:77], v[212:215], v[236:239], v[74:77]
	v_mfma_f32_16x16x32_bf16 v[70:73], v[178:181], v[244:247], v[70:73]
	v_mfma_f32_16x16x32_bf16 v[66:69], v[212:215], v[244:247], v[66:69]
	s_setprio 0
	s_barrier
	ds_read_b128 v[216:219], v205 offset:49152
	ds_read_b128 v[220:223], v205 offset:50176
	ds_read_b128 v[224:227], v205 offset:51200
	ds_read_b128 v[228:231], v205 offset:52224
	ds_read_b128 v[232:235], v205 offset:53248
	ds_read_b128 v[236:239], v205 offset:54272
	ds_read_b128 v[240:243], v205 offset:55296
	ds_read_b128 v[244:247], v205 offset:56320
	global_load_lds_dwordx4 v156, s[12:13]
	s_add_i32 m0, s66, 0x2000
	s_add_i32 s66, s69, s31
	global_load_lds_dwordx4 v158, s[12:13]
	s_add_u32 s12, s12, 0x40000
	s_addc_u32 s13, s13, 0
	s_mov_b32 m0, s66
	s_nop 0
	global_load_lds_dwordx4 v156, s[12:13]
	s_add_i32 m0, s66, 0x2000
	s_nop 0
	global_load_lds_dwordx4 v158, s[12:13]
	s_mov_b32 m0, s0
	s_nop 0
	global_load_lds_dwordx4 v251, s[100:101]
	s_mov_b32 m0, s1
	s_nop 0
	global_load_lds_dwordx4 v252, s[100:101]
	s_waitcnt vmcnt(8)
	s_waitcnt lgkmcnt(0)
	s_barrier
	s_setprio 1
	s_waitcnt lgkmcnt(0)
	v_mfma_f32_16x16x32_bf16 v[62:65], v[132:135], v[216:219], v[62:65]
	v_mfma_f32_16x16x32_bf16 v[58:61], v[140:143], v[216:219], v[58:61]
	v_mfma_f32_16x16x32_bf16 v[54:57], v[132:135], v[224:227], v[54:57]
	v_mfma_f32_16x16x32_bf16 v[50:53], v[140:143], v[224:227], v[50:53]
	v_mfma_f32_16x16x32_bf16 v[46:49], v[132:135], v[232:235], v[46:49]
	v_mfma_f32_16x16x32_bf16 v[42:45], v[140:143], v[232:235], v[42:45]
	v_mfma_f32_16x16x32_bf16 v[38:41], v[132:135], v[240:243], v[38:41]
	v_mfma_f32_16x16x32_bf16 v[34:37], v[140:143], v[240:243], v[34:37]
	v_mfma_f32_16x16x32_bf16 v[62:65], v[136:139], v[220:223], v[62:65]
	v_mfma_f32_16x16x32_bf16 v[58:61], v[144:147], v[220:223], v[58:61]
	v_mfma_f32_16x16x32_bf16 v[54:57], v[136:139], v[228:231], v[54:57]
	v_mfma_f32_16x16x32_bf16 v[50:53], v[144:147], v[228:231], v[50:53]
	v_mfma_f32_16x16x32_bf16 v[46:49], v[136:139], v[236:239], v[46:49]
	v_mfma_f32_16x16x32_bf16 v[42:45], v[144:147], v[236:239], v[42:45]
	v_mfma_f32_16x16x32_bf16 v[38:41], v[136:139], v[244:247], v[38:41]
	v_mfma_f32_16x16x32_bf16 v[34:37], v[144:147], v[244:247], v[34:37]
	s_setprio 0
	s_setprio 1
	v_mfma_f32_16x16x32_bf16 v[30:33], v[148:151], v[216:219], v[30:33]
	s_add_i32 s65, s65, 2
	v_mfma_f32_16x16x32_bf16 v[26:29], v[182:185], v[216:219], v[26:29]
	s_add_u32 s63, s63, 0x100
	v_mfma_f32_16x16x32_bf16 v[22:25], v[148:151], v[224:227], v[22:25]
	s_addc_u32 s64, s64, 0
	v_mfma_f32_16x16x32_bf16 v[18:21], v[182:185], v[224:227], v[18:21]
	s_add_u32 s10, s10, 0x10000
	v_mfma_f32_16x16x32_bf16 v[14:17], v[148:151], v[232:235], v[14:17]
	s_addc_u32 s11, s11, 0
	v_mfma_f32_16x16x32_bf16 v[10:13], v[182:185], v[232:235], v[10:13]
	s_mov_b64 s[12:13], 0x10000
	v_mfma_f32_16x16x32_bf16 v[6:9], v[148:151], v[240:243], v[6:9]
	s_cmp_gt_u32 s65, 13
	v_mfma_f32_16x16x32_bf16 v[2:5], v[182:185], v[240:243], v[2:5]
	v_mfma_f32_16x16x32_bf16 v[30:33], v[178:181], v[220:223], v[30:33]
	v_mfma_f32_16x16x32_bf16 v[26:29], v[212:215], v[220:223], v[26:29]
	v_mfma_f32_16x16x32_bf16 v[22:25], v[178:181], v[228:231], v[22:25]
	v_mfma_f32_16x16x32_bf16 v[18:21], v[212:215], v[228:231], v[18:21]
	v_mfma_f32_16x16x32_bf16 v[14:17], v[178:181], v[236:239], v[14:17]
	v_mfma_f32_16x16x32_bf16 v[10:13], v[212:215], v[236:239], v[10:13]
	v_mfma_f32_16x16x32_bf16 v[6:9], v[178:181], v[244:247], v[6:9]
	v_mfma_f32_16x16x32_bf16 v[2:5], v[212:215], v[244:247], v[2:5]
	s_setprio 0
	s_barrier
	s_cbranch_scc0 .LBB0_818
	s_and_b64 vcc, exec, s[52:53]
	s_cbranch_vccz .LBB0_821
	s_barrier

; #define PG8_STAGE(bufoff, gbase, voff) do { _Pragma("unroll") for (int _i = 0; _i < 2; ++_i) \
;         __builtin_amdgcn_global_load_lds((const unsigned*)((const char*)(gbase) + (voff)[_i]), (PG8_LAS unsigned*)(lds + (bufoff) + ldsw + _i * 8192), 16, 0, 0); } while (0)
; #define PG8_LDA(dst, b, h) do { _Pragma("unroll") for (int m = 0; m < 4; ++m) _Pragma("unroll") for (int k = 0; k < 2; ++k) dst[m][k] = *(const PG8_LAS bf16x8*)(lds + PG8_SA(b, h) + aoff + m * 2048 + k * 1024); } while (0)
; #define PG8_LDB(dst, b, h) do { _Pragma("unroll") for (int n = 0; n < 2; ++n) _Pragma("unroll") for (int k = 0; k < 2; ++k) dst[n][k] = *(const PG8_LAS bf16x8*)(lds + PG8_SB(b, h) + boff + n * 2048 + k * 1024); } while (0)
; #define PG8_MMA(ai, bj, At, Bt) do { __builtin_amdgcn_s_setprio(1); _Pragma("unroll") for (int m = 0; m < 4; ++m) _Pragma("unroll") for (int n = 0; n < 2; ++n) _Pragma("unroll") for (int k = 0; k < 2; ++k) \
;         acc[ai][bj][m][n] = __builtin_amdgcn_mfma_f32_16x16x32_bf16(Bt[n][k], At[m][k], acc[ai][bj][m][n], 0, 0, 0); __builtin_amdgcn_s_setprio(0); } while (0)
; #define PG8_WAIT_V(n) asm volatile("s_waitcnt vmcnt(" #n ")" ::: "memory")
; #define PG8_WAIT_L(n) asm volatile("s_waitcnt lgkmcnt(" #n ")" ::: "memory")
; #define PG8_BAR __builtin_amdgcn_s_barrier()
; template <class Epi, bool ALIGN_EPI, bool ABLK = false>
; __device__ __forceinline__ void gemm_phase(PG8_LAS unsigned char* lds, const Gemm g, const StaticOrder& S, const Epi& E) {
;     ...
;         for (int t = 0; t < nt; t += 2) {
;             const bool last = (t == nt - 2);
;             const char* a1 = cA + (size_t)(t + 1) * kstepA;
;             const char* a2 = last ? nA : cA + (size_t)(t + 2) * kstepA; const char* b2 = last ? nB : cB + (size_t)(t + 2) * kstepB;
;             const char* a3 = a2 + kstepA; const char* b3 = b2 + kstepB;
;             PG8_LDB(B0, 0, 0); PG8_LDB(B1, 0, 1); PG8_SCHED; PG8_LDA(At, 0, 0); PG8_STAGE(PG8_SA(1, 1), a1 + hstepA, voffA);
;             PG8_WAIT_V(8); PG8_WAIT_L(0); PG8_BAR; PG8_MMA(0, 0, At, B0); PG8_MMA(0, 1, At, B1); PG8_BAR; PG8_SCHED;
;             PG8_LDA(At, 0, 1); PG8_STAGE(PG8_SB(0, 0), b2, voffB); PG8_STAGE(PG8_SB(0, 1), b2 + hstepB, voffB); PG8_STAGE(PG8_SA(0, 0), a2, voffA);
;             PG8_WAIT_V(8); PG8_WAIT_L(0); PG8_BAR; PG8_MMA(1, 0, At, B0); PG8_MMA(1, 1, At, B1); PG8_BAR; PG8_SCHED;
.LBB0_1983:
	v_add_u32_e32 v136, s71, v179
	ds_read_b128 v[132:135], v136
	ds_read_b128 v[184:187], v136 offset:1024
	ds_read_b128 v[188:191], v136 offset:2048
	ds_read_b128 v[192:195], v136 offset:3072
	v_add_u32_e32 v136, s72, v179
	ds_read_b128 v[196:199], v136
	ds_read_b128 v[200:203], v136 offset:1024
	ds_read_b128 v[204:207], v136 offset:2048
	ds_read_b128 v[208:211], v136 offset:3072
	s_add_u32 s62, s26, s60
	s_addc_u32 s63, s27, s61
	s_cmp_eq_u32 s79, 12
	s_cselect_b32 s81, s55, s63
	s_cselect_b32 s80, s75, s62
	s_cselect_b32 s63, s53, s78
	s_cselect_b32 s62, s76, s77
	v_lshl_add_u64 v[136:137], s[26:27], 0, v[130:131]
	v_lshl_add_u64 v[244:245], v[136:137], 0, s[40:41]
	s_add_i32 m0, s23, 0xc000
	ds_read_b128 v[212:215], v182
	ds_read_b128 v[216:219], v182 offset:1024
	ds_read_b128 v[220:223], v182 offset:2048
	ds_read_b128 v[224:227], v182 offset:3072
	ds_read_b128 v[228:231], v182 offset:4096
	ds_read_b128 v[232:235], v182 offset:5120
	ds_read_b128 v[236:239], v182 offset:6144
	ds_read_b128 v[240:243], v182 offset:7168
	global_load_lds_dwordx4 v[244:245], off
	v_lshl_add_u64 v[136:137], v[136:137], 0, s[42:43]
	s_add_i32 m0, s23, 0xe000
	s_nop 0
	global_load_lds_dwordx4 v[136:137], off
	s_waitcnt vmcnt(8)
	s_waitcnt lgkmcnt(0)
	s_barrier
	s_setprio 1
	s_waitcnt lgkmcnt(0)
	v_mfma_f32_16x16x32_bf16 v[126:129], v[132:135], v[212:215], v[126:129]
	v_mfma_f32_16x16x32_bf16 v[122:125], v[188:191], v[212:215], v[122:125]
	v_mfma_f32_16x16x32_bf16 v[118:121], v[132:135], v[220:223], v[118:121]
	v_mfma_f32_16x16x32_bf16 v[114:117], v[188:191], v[220:223], v[114:117]
	v_mfma_f32_16x16x32_bf16 v[110:113], v[132:135], v[228:231], v[110:113]
	v_mfma_f32_16x16x32_bf16 v[106:109], v[188:191], v[228:231], v[106:109]
	v_mfma_f32_16x16x32_bf16 v[102:105], v[132:135], v[236:239], v[102:105]
	v_mfma_f32_16x16x32_bf16 v[98:101], v[188:191], v[236:239], v[98:101]
	v_mfma_f32_16x16x32_bf16 v[126:129], v[184:187], v[216:219], v[126:129]
	v_mfma_f32_16x16x32_bf16 v[122:125], v[192:195], v[216:219], v[122:125]
	v_mfma_f32_16x16x32_bf16 v[118:121], v[184:187], v[224:227], v[118:121]
	v_mfma_f32_16x16x32_bf16 v[114:117], v[192:195], v[224:227], v[114:117]
	v_mfma_f32_16x16x32_bf16 v[110:113], v[184:187], v[232:235], v[110:113]
	v_mfma_f32_16x16x32_bf16 v[106:109], v[192:195], v[232:235], v[106:109]
	v_mfma_f32_16x16x32_bf16 v[102:105], v[184:187], v[240:243], v[102:105]
	v_mfma_f32_16x16x32_bf16 v[98:101], v[192:195], v[240:243], v[98:101]
	s_setprio 0
	s_setprio 1
	v_mfma_f32_16x16x32_bf16 v[94:97], v[196:199], v[212:215], v[94:97]
	s_add_i32 s82, s71, s21
	v_mfma_f32_16x16x32_bf16 v[90:93], v[204:207], v[212:215], v[90:93]
	s_mov_b32 m0, s82
	v_mfma_f32_16x16x32_bf16 v[86:89], v[196:199], v[220:223], v[86:89]
	v_mfma_f32_16x16x32_bf16 v[82:85], v[204:207], v[220:223], v[82:85]
	v_mfma_f32_16x16x32_bf16 v[78:81], v[196:199], v[228:231], v[78:81]
	v_mfma_f32_16x16x32_bf16 v[74:77], v[204:207], v[228:231], v[74:77]
	v_mfma_f32_16x16x32_bf16 v[70:73], v[196:199], v[236:239], v[70:73]
	v_mfma_f32_16x16x32_bf16 v[66:69], v[204:207], v[236:239], v[66:69]
	v_mfma_f32_16x16x32_bf16 v[94:97], v[200:203], v[216:219], v[94:97]
	v_mfma_f32_16x16x32_bf16 v[90:93], v[208:211], v[216:219], v[90:93]
	v_mfma_f32_16x16x32_bf16 v[86:89], v[200:203], v[224:227], v[86:89]
	v_mfma_f32_16x16x32_bf16 v[82:85], v[208:211], v[224:227], v[82:85]
	v_mfma_f32_16x16x32_bf16 v[78:81], v[200:203], v[232:235], v[78:81]
	v_mfma_f32_16x16x32_bf16 v[74:77], v[208:211], v[232:235], v[74:77]
	v_mfma_f32_16x16x32_bf16 v[70:73], v[200:203], v[240:243], v[70:73]
	v_mfma_f32_16x16x32_bf16 v[66:69], v[208:211], v[240:243], v[66:69]
	s_setprio 0
	s_barrier
	v_lshl_add_u64 v[136:137], s[62:63], 0, v[140:141]
	ds_read_b128 v[212:215], v182 offset:16384
	ds_read_b128 v[216:219], v182 offset:17408
	ds_read_b128 v[220:223], v182 offset:18432
	ds_read_b128 v[224:227], v182 offset:19456
	ds_read_b128 v[228:231], v182 offset:20480
	ds_read_b128 v[232:235], v182 offset:21504
	ds_read_b128 v[236:239], v182 offset:22528
	ds_read_b128 v[240:243], v182 offset:23552
	global_load_lds_dwordx4 v[136:137], off
	s_add_i32 m0, s82, 0x2000
	s_add_u32 s82, s62, 0x40000
	v_lshl_add_u64 v[244:245], s[62:63], 0, v[142:143]
	s_addc_u32 s83, s63, 0
	s_add_i32 s84, s72, s21
	global_load_lds_dwordx4 v[244:245], off
	v_lshl_add_u64 v[246:247], s[82:83], 0, v[140:141]
	s_mov_b32 m0, s84
	s_nop 0
	global_load_lds_dwordx4 v[246:247], off
	v_lshl_add_u64 v[246:247], s[82:83], 0, v[142:143]
	s_add_i32 m0, s84, 0x2000
	s_nop 0
	global_load_lds_dwordx4 v[246:247], off
	v_lshl_add_u64 v[246:247], s[80:81], 0, v[138:139]
	s_mov_b32 m0, s23
	v_lshl_add_u64 v[248:249], v[246:247], 0, s[44:45]
	global_load_lds_dwordx4 v[246:247], off
	s_mov_b32 m0, s33
	s_nop 0
	global_load_lds_dwordx4 v[248:249], off
	s_waitcnt vmcnt(8)
	s_waitcnt lgkmcnt(0)
	s_barrier
; #define PG8_STAGE(bufoff, gbase, voff) do { _Pragma("unroll") for (int _i = 0; _i < 2; ++_i) \
;         __builtin_amdgcn_global_load_lds((const unsigned*)((const char*)(gbase) + (voff)[_i]), (PG8_LAS unsigned*)(lds + (bufoff) + ldsw + _i * 8192), 16, 0, 0); } while (0)
; #define PG8_LDA(dst, b, h) do { _Pragma("unroll") for (int m = 0; m < 4; ++m) _Pragma("unroll") for (int k = 0; k < 2; ++k) dst[m][k] = *(const PG8_LAS bf16x8*)(lds + PG8_SA(b, h) + aoff + m * 2048 + k * 1024); } while (0)
; #define PG8_LDB(dst, b, h) do { _Pragma("unroll") for (int n = 0; n < 2; ++n) _Pragma("unroll") for (int k = 0; k < 2; ++k) dst[n][k] = *(const PG8_LAS bf16x8*)(lds + PG8_SB(b, h) + boff + n * 2048 + k * 1024); } while (0)
; #define PG8_MMA(ai, bj, At, Bt) do { __builtin_amdgcn_s_setprio(1); _Pragma("unroll") for (int m = 0; m < 4; ++m) _Pragma("unroll") for (int n = 0; n < 2; ++n) _Pragma("unroll") for (int k = 0; k < 2; ++k) \
;         acc[ai][bj][m][n] = __builtin_amdgcn_mfma_f32_16x16x32_bf16(Bt[n][k], At[m][k], acc[ai][bj][m][n], 0, 0, 0); __builtin_amdgcn_s_setprio(0); } while (0)
; #define PG8_WAIT_V(n) asm volatile("s_waitcnt vmcnt(" #n ")" ::: "memory")
; #define PG8_WAIT_L(n) asm volatile("s_waitcnt lgkmcnt(" #n ")" ::: "memory")
; #define PG8_BAR __builtin_amdgcn_s_barrier()
; #define PG8_SCHED __builtin_amdgcn_sched_barrier(0)
; template <class Epi, bool ALIGN_EPI, bool ABLK = false>
; __device__ __forceinline__ void gemm_phase(PG8_LAS unsigned char* lds, const Gemm g, const StaticOrder& S, const Epi& E) {
;     ...
;             PG8_WAIT_V(8); PG8_WAIT_L(0); PG8_BAR; PG8_MMA(1, 0, At, B0); PG8_MMA(1, 1, At, B1); PG8_BAR; PG8_SCHED;
;             PG8_LDB(B0, 1, 0); PG8_LDB(B1, 1, 1); PG8_SCHED; PG8_LDA(At, 1, 0); PG8_STAGE(PG8_SA(0, 1), a2 + hstepA, voffA);
;             PG8_WAIT_V(8); PG8_WAIT_L(0); PG8_BAR; PG8_MMA(0, 0, At, B0); PG8_MMA(0, 1, At, B1); PG8_BAR; PG8_SCHED;
	s_setprio 1
	s_waitcnt lgkmcnt(0)
	v_mfma_f32_16x16x32_bf16 v[62:65], v[132:135], v[212:215], v[62:65]
	v_mfma_f32_16x16x32_bf16 v[58:61], v[188:191], v[212:215], v[58:61]
	v_mfma_f32_16x16x32_bf16 v[54:57], v[132:135], v[220:223], v[54:57]
	v_mfma_f32_16x16x32_bf16 v[50:53], v[188:191], v[220:223], v[50:53]
	v_mfma_f32_16x16x32_bf16 v[46:49], v[132:135], v[228:231], v[46:49]
	v_mfma_f32_16x16x32_bf16 v[42:45], v[188:191], v[228:231], v[42:45]
	v_mfma_f32_16x16x32_bf16 v[38:41], v[132:135], v[236:239], v[38:41]
	v_mfma_f32_16x16x32_bf16 v[34:37], v[188:191], v[236:239], v[34:37]
	v_mfma_f32_16x16x32_bf16 v[62:65], v[184:187], v[216:219], v[62:65]
	v_mfma_f32_16x16x32_bf16 v[58:61], v[192:195], v[216:219], v[58:61]
	v_mfma_f32_16x16x32_bf16 v[54:57], v[184:187], v[224:227], v[54:57]
	v_mfma_f32_16x16x32_bf16 v[50:53], v[192:195], v[224:227], v[50:53]
	v_mfma_f32_16x16x32_bf16 v[46:49], v[184:187], v[232:235], v[46:49]
	v_mfma_f32_16x16x32_bf16 v[42:45], v[192:195], v[232:235], v[42:45]
	v_mfma_f32_16x16x32_bf16 v[38:41], v[184:187], v[240:243], v[38:41]
	v_mfma_f32_16x16x32_bf16 v[34:37], v[192:195], v[240:243], v[34:37]
	s_setprio 0
	s_setprio 1
	v_mfma_f32_16x16x32_bf16 v[30:33], v[196:199], v[212:215], v[30:33]
	s_add_i32 s80, 0, 0x18000
	v_mfma_f32_16x16x32_bf16 v[26:29], v[204:207], v[212:215], v[26:29]
	s_add_i32 s81, 0, 0x1c000
	v_mfma_f32_16x16x32_bf16 v[22:25], v[196:199], v[220:223], v[22:25]
	v_mfma_f32_16x16x32_bf16 v[18:21], v[204:207], v[220:223], v[18:21]
	v_mfma_f32_16x16x32_bf16 v[14:17], v[196:199], v[228:231], v[14:17]
	v_mfma_f32_16x16x32_bf16 v[10:13], v[204:207], v[228:231], v[10:13]
	v_mfma_f32_16x16x32_bf16 v[6:9], v[196:199], v[236:239], v[6:9]
	v_mfma_f32_16x16x32_bf16 v[2:5], v[204:207], v[236:239], v[2:5]
	v_mfma_f32_16x16x32_bf16 v[30:33], v[200:203], v[216:219], v[30:33]
	v_mfma_f32_16x16x32_bf16 v[26:29], v[208:211], v[216:219], v[26:29]
	v_mfma_f32_16x16x32_bf16 v[22:25], v[200:203], v[224:227], v[22:25]
	v_mfma_f32_16x16x32_bf16 v[18:21], v[208:211], v[224:227], v[18:21]
	v_mfma_f32_16x16x32_bf16 v[14:17], v[200:203], v[232:235], v[14:17]
	v_mfma_f32_16x16x32_bf16 v[10:13], v[208:211], v[232:235], v[10:13]
	v_mfma_f32_16x16x32_bf16 v[6:9], v[200:203], v[240:243], v[6:9]
	v_mfma_f32_16x16x32_bf16 v[2:5], v[208:211], v[240:243], v[2:5]
	s_setprio 0
	s_barrier
	v_add_u32_e32 v192, s80, v179
	v_add_u32_e32 v208, s81, v179
	ds_read_b128 v[132:135], v192
	ds_read_b128 v[184:187], v192 offset:1024
	ds_read_b128 v[188:191], v192 offset:2048
	ds_read_b128 v[192:195], v192 offset:3072
	ds_read_b128 v[196:199], v208
	ds_read_b128 v[200:203], v208 offset:1024
	ds_read_b128 v[204:207], v208 offset:2048
	ds_read_b128 v[208:211], v208 offset:3072
	s_mov_b32 m0, s67
	v_lshl_add_u64 v[248:249], v[246:247], 0, s[46:47]
	ds_read_b128 v[212:215], v182 offset:32768
	ds_read_b128 v[216:219], v182 offset:33792
	ds_read_b128 v[220:223], v182 offset:34816
	ds_read_b128 v[224:227], v182 offset:35840
	ds_read_b128 v[228:231], v182 offset:36864
	ds_read_b128 v[232:235], v182 offset:37888
	ds_read_b128 v[236:239], v182 offset:38912
	ds_read_b128 v[240:243], v182 offset:39936
	global_load_lds_dwordx4 v[248:249], off
	v_lshl_add_u64 v[248:249], v[246:247], 0, s[48:49]
	s_mov_b32 m0, s68
	s_nop 0
	global_load_lds_dwordx4 v[248:249], off
	s_waitcnt vmcnt(8)
	s_waitcnt lgkmcnt(0)
	s_barrier
	s_setprio 1
	s_waitcnt lgkmcnt(0)
	v_mfma_f32_16x16x32_bf16 v[126:129], v[132:135], v[212:215], v[126:129]
	v_mfma_f32_16x16x32_bf16 v[122:125], v[188:191], v[212:215], v[122:125]
	v_mfma_f32_16x16x32_bf16 v[118:121], v[132:135], v[220:223], v[118:121]
	v_mfma_f32_16x16x32_bf16 v[114:117], v[188:191], v[220:223], v[114:117]
	v_mfma_f32_16x16x32_bf16 v[110:113], v[132:135], v[228:231], v[110:113]
	v_mfma_f32_16x16x32_bf16 v[106:109], v[188:191], v[228:231], v[106:109]
	v_mfma_f32_16x16x32_bf16 v[102:105], v[132:135], v[236:239], v[102:105]
	v_mfma_f32_16x16x32_bf16 v[98:101], v[188:191], v[236:239], v[98:101]
	v_mfma_f32_16x16x32_bf16 v[126:129], v[184:187], v[216:219], v[126:129]
	v_mfma_f32_16x16x32_bf16 v[122:125], v[192:195], v[216:219], v[122:125]
	v_mfma_f32_16x16x32_bf16 v[118:121], v[184:187], v[224:227], v[118:121]
	v_mfma_f32_16x16x32_bf16 v[114:117], v[192:195], v[224:227], v[114:117]
	v_mfma_f32_16x16x32_bf16 v[110:113], v[184:187], v[232:235], v[110:113]
	v_mfma_f32_16x16x32_bf16 v[106:109], v[192:195], v[232:235], v[106:109]
	v_mfma_f32_16x16x32_bf16 v[102:105], v[184:187], v[240:243], v[102:105]
	v_mfma_f32_16x16x32_bf16 v[98:101], v[192:195], v[240:243], v[98:101]
	s_setprio 0
	s_setprio 1
	v_mfma_f32_16x16x32_bf16 v[94:97], v[196:199], v[212:215], v[94:97]
	s_add_i32 s80, s80, s21
	v_mfma_f32_16x16x32_bf16 v[90:93], v[204:207], v[212:215], v[90:93]
	s_mov_b32 m0, s80
	v_mfma_f32_16x16x32_bf16 v[86:89], v[196:199], v[220:223], v[86:89]
	v_mfma_f32_16x16x32_bf16 v[82:85], v[204:207], v[220:223], v[82:85]
	v_mfma_f32_16x16x32_bf16 v[78:81], v[196:199], v[228:231], v[78:81]
	v_mfma_f32_16x16x32_bf16 v[74:77], v[204:207], v[228:231], v[74:77]
	v_mfma_f32_16x16x32_bf16 v[70:73], v[196:199], v[236:239], v[70:73]
	v_mfma_f32_16x16x32_bf16 v[66:69], v[204:207], v[236:239], v[66:69]
	v_mfma_f32_16x16x32_bf16 v[94:97], v[200:203], v[216:219], v[94:97]
	v_mfma_f32_16x16x32_bf16 v[90:93], v[208:211], v[216:219], v[90:93]
	v_mfma_f32_16x16x32_bf16 v[86:89], v[200:203], v[224:227], v[86:89]
	v_mfma_f32_16x16x32_bf16 v[82:85], v[208:211], v[224:227], v[82:85]
	v_mfma_f32_16x16x32_bf16 v[78:81], v[200:203], v[232:235], v[78:81]
	v_mfma_f32_16x16x32_bf16 v[74:77], v[208:211], v[232:235], v[74:77]
	v_mfma_f32_16x16x32_bf16 v[70:73], v[200:203], v[240:243], v[70:73]
	v_mfma_f32_16x16x32_bf16 v[66:69], v[208:211], v[240:243], v[66:69]
	s_setprio 0
	s_barrier
; #define PG8_STAGE(bufoff, gbase, voff) do { _Pragma("unroll") for (int _i = 0; _i < 2; ++_i) \
;         __builtin_amdgcn_global_load_lds((const unsigned*)((const char*)(gbase) + (voff)[_i]), (PG8_LAS unsigned*)(lds + (bufoff) + ldsw + _i * 8192), 16, 0, 0); } while (0)
; #define PG8_LDA(dst, b, h) do { _Pragma("unroll") for (int m = 0; m < 4; ++m) _Pragma("unroll") for (int k = 0; k < 2; ++k) dst[m][k] = *(const PG8_LAS bf16x8*)(lds + PG8_SA(b, h) + aoff + m * 2048 + k * 1024); } while (0)
; #define PG8_MMA(ai, bj, At, Bt) do { __builtin_amdgcn_s_setprio(1); _Pragma("unroll") for (int m = 0; m < 4; ++m) _Pragma("unroll") for (int n = 0; n < 2; ++n) _Pragma("unroll") for (int k = 0; k < 2; ++k) \
;         acc[ai][bj][m][n] = __builtin_amdgcn_mfma_f32_16x16x32_bf16(Bt[n][k], At[m][k], acc[ai][bj][m][n], 0, 0, 0); __builtin_amdgcn_s_setprio(0); } while (0)
; #define PG8_WAIT_V(n) asm volatile("s_waitcnt vmcnt(" #n ")" ::: "memory")
; #define PG8_WAIT_L(n) asm volatile("s_waitcnt lgkmcnt(" #n ")" ::: "memory")
; #define PG8_BAR __builtin_amdgcn_s_barrier()
; #define PG8_SCHED __builtin_amdgcn_sched_barrier(0)
; template <class Epi, bool ALIGN_EPI, bool ABLK = false>
; __device__ __forceinline__ void gemm_phase(PG8_LAS unsigned char* lds, const Gemm g, const StaticOrder& S, const Epi& E) {
;     ...
;             PG8_LDA(At, 1, 1); PG8_STAGE(PG8_SB(1, 0), b3, voffB); PG8_STAGE(PG8_SB(1, 1), b3 + hstepB, voffB); PG8_STAGE(PG8_SA(1, 0), a3, voffA);
;             PG8_WAIT_V(8); PG8_WAIT_L(0); PG8_BAR; PG8_MMA(1, 0, At, B0); PG8_MMA(1, 1, At, B1); PG8_BAR; PG8_SCHED;
;         }
	v_lshl_add_u64 v[136:137], v[136:137], 0, s[30:31]
	ds_read_b128 v[212:215], v182 offset:49152
	ds_read_b128 v[216:219], v182 offset:50176
	ds_read_b128 v[220:223], v182 offset:51200
	ds_read_b128 v[224:227], v182 offset:52224
	ds_read_b128 v[228:231], v182 offset:53248
	ds_read_b128 v[232:235], v182 offset:54272
	ds_read_b128 v[236:239], v182 offset:55296
	ds_read_b128 v[240:243], v182 offset:56320
	global_load_lds_dwordx4 v[136:137], off
	s_add_i32 m0, s80, 0x2000
	s_add_u32 s62, s62, 0x40080
	v_lshl_add_u64 v[136:137], v[244:245], 0, s[30:31]
	s_addc_u32 s63, s63, 0
	s_add_i32 s80, s81, s21
	global_load_lds_dwordx4 v[136:137], off
	v_lshl_add_u64 v[136:137], s[62:63], 0, v[140:141]
	s_mov_b32 m0, s80
	s_nop 0
	global_load_lds_dwordx4 v[136:137], off
	v_lshl_add_u64 v[136:137], s[62:63], 0, v[142:143]
	s_add_i32 m0, s80, 0x2000
	s_nop 0
	global_load_lds_dwordx4 v[136:137], off
	v_lshl_add_u64 v[136:137], v[246:247], 0, s[34:35]
	s_mov_b32 m0, s9
	s_nop 0
	global_load_lds_dwordx4 v[136:137], off
	v_lshl_add_u64 v[136:137], v[246:247], 0, s[36:37]
	s_mov_b32 m0, s70
	s_nop 0
	global_load_lds_dwordx4 v[136:137], off
	s_waitcnt vmcnt(8)
	s_waitcnt lgkmcnt(0)
	s_barrier
	s_setprio 1
	s_waitcnt lgkmcnt(0)
	v_mfma_f32_16x16x32_bf16 v[62:65], v[132:135], v[212:215], v[62:65]
	v_mfma_f32_16x16x32_bf16 v[58:61], v[188:191], v[212:215], v[58:61]
	v_mfma_f32_16x16x32_bf16 v[54:57], v[132:135], v[220:223], v[54:57]
	v_mfma_f32_16x16x32_bf16 v[50:53], v[188:191], v[220:223], v[50:53]
	v_mfma_f32_16x16x32_bf16 v[46:49], v[132:135], v[228:231], v[46:49]
	v_mfma_f32_16x16x32_bf16 v[42:45], v[188:191], v[228:231], v[42:45]
	v_mfma_f32_16x16x32_bf16 v[38:41], v[132:135], v[236:239], v[38:41]
	v_mfma_f32_16x16x32_bf16 v[34:37], v[188:191], v[236:239], v[34:37]
	v_mfma_f32_16x16x32_bf16 v[62:65], v[184:187], v[216:219], v[62:65]
	v_mfma_f32_16x16x32_bf16 v[58:61], v[192:195], v[216:219], v[58:61]
	v_mfma_f32_16x16x32_bf16 v[54:57], v[184:187], v[224:227], v[54:57]
	v_mfma_f32_16x16x32_bf16 v[50:53], v[192:195], v[224:227], v[50:53]
	v_mfma_f32_16x16x32_bf16 v[46:49], v[184:187], v[232:235], v[46:49]
	v_mfma_f32_16x16x32_bf16 v[42:45], v[192:195], v[232:235], v[42:45]
	v_mfma_f32_16x16x32_bf16 v[38:41], v[184:187], v[240:243], v[38:41]
	v_mfma_f32_16x16x32_bf16 v[34:37], v[192:195], v[240:243], v[34:37]
	s_setprio 0
	s_setprio 1
	v_mfma_f32_16x16x32_bf16 v[30:33], v[196:199], v[212:215], v[30:33]
	s_add_i32 s79, s79, 2
	v_mfma_f32_16x16x32_bf16 v[26:29], v[204:207], v[212:215], v[26:29]
	s_add_u32 s77, s77, 0x100
	v_mfma_f32_16x16x32_bf16 v[22:25], v[196:199], v[220:223], v[22:25]
	s_addc_u32 s78, s78, 0
	v_mfma_f32_16x16x32_bf16 v[18:21], v[204:207], v[220:223], v[18:21]
	s_add_u32 s60, s60, 0x10000
	v_mfma_f32_16x16x32_bf16 v[14:17], v[196:199], v[228:231], v[14:17]
	s_addc_u32 s61, s61, 0
	v_mfma_f32_16x16x32_bf16 v[10:13], v[204:207], v[228:231], v[10:13]
	s_cmp_gt_u32 s79, 13
	v_mfma_f32_16x16x32_bf16 v[6:9], v[196:199], v[236:239], v[6:9]
	v_mfma_f32_16x16x32_bf16 v[2:5], v[204:207], v[236:239], v[2:5]
	v_mfma_f32_16x16x32_bf16 v[30:33], v[200:203], v[216:219], v[30:33]
	v_mfma_f32_16x16x32_bf16 v[26:29], v[208:211], v[216:219], v[26:29]
	v_mfma_f32_16x16x32_bf16 v[22:25], v[200:203], v[224:227], v[22:25]
	v_mfma_f32_16x16x32_bf16 v[18:21], v[208:211], v[224:227], v[18:21]
	v_mfma_f32_16x16x32_bf16 v[14:17], v[200:203], v[232:235], v[14:17]
	v_mfma_f32_16x16x32_bf16 v[10:13], v[208:211], v[232:235], v[10:13]
	v_mfma_f32_16x16x32_bf16 v[6:9], v[200:203], v[240:243], v[6:9]
	v_mfma_f32_16x16x32_bf16 v[2:5], v[208:211], v[240:243], v[2:5]
	s_setprio 0
	s_barrier
	v_lshl_add_u64 v[130:131], v[130:131], 0, s[50:51]
	s_cbranch_scc0 .LBB0_1983
	s_and_b64 vcc, exec, s[38:39]
	s_cbranch_vccz .LBB0_1986
	s_barrier

; #define PG8_STAGE(bufoff, gbase, voff) do { _Pragma("unroll") for (int _i = 0; _i < 2; ++_i) \
;         __builtin_amdgcn_global_load_lds((const unsigned*)((const char*)(gbase) + (voff)[_i]), (PG8_LAS unsigned*)(lds + (bufoff) + ldsw + _i * 8192), 16, 0, 0); } while (0)
; #define PG8_LDA(dst, b, h) do { _Pragma("unroll") for (int m = 0; m < 4; ++m) _Pragma("unroll") for (int k = 0; k < 2; ++k) dst[m][k] = *(const PG8_LAS bf16x8*)(lds + PG8_SA(b, h) + aoff + m * 2048 + k * 1024); } while (0)
; #define PG8_LDB(dst, b, h) do { _Pragma("unroll") for (int n = 0; n < 2; ++n) _Pragma("unroll") for (int k = 0; k < 2; ++k) dst[n][k] = *(const PG8_LAS bf16x8*)(lds + PG8_SB(b, h) + boff + n * 2048 + k * 1024); } while (0)
; #define PG8_MMA(ai, bj, At, Bt) do { __builtin_amdgcn_s_setprio(1); _Pragma("unroll") for (int m = 0; m < 4; ++m) _Pragma("unroll") for (int n = 0; n < 2; ++n) _Pragma("unroll") for (int k = 0; k < 2; ++k) \
;         acc[ai][bj][m][n] = __builtin_amdgcn_mfma_f32_16x16x32_bf16(Bt[n][k], At[m][k], acc[ai][bj][m][n], 0, 0, 0); __builtin_amdgcn_s_setprio(0); } while (0)
; #define PG8_WAIT_V(n) asm volatile("s_waitcnt vmcnt(" #n ")" ::: "memory")
; #define PG8_WAIT_L(n) asm volatile("s_waitcnt lgkmcnt(" #n ")" ::: "memory")
; #define PG8_BAR __builtin_amdgcn_s_barrier()
; template <class Epi, bool ALIGN_EPI, bool ABLK = false>
; __device__ __forceinline__ void gemm_phase(PG8_LAS unsigned char* lds, const Gemm g, const StaticOrder& S, const Epi& E) {
;     ...
;         for (int t = 0; t < nt; t += 2) {
;             const bool last = (t == nt - 2);
;             const char* a1 = cA + (size_t)(t + 1) * kstepA;
;             const char* a2 = last ? nA : cA + (size_t)(t + 2) * kstepA; const char* b2 = last ? nB : cB + (size_t)(t + 2) * kstepB;
;             const char* a3 = a2 + kstepA; const char* b3 = b2 + kstepB;
;             PG8_LDB(B0, 0, 0); PG8_LDB(B1, 0, 1); PG8_SCHED; PG8_LDA(At, 0, 0); PG8_STAGE(PG8_SA(1, 1), a1 + hstepA, voffA);
;             PG8_WAIT_V(8); PG8_WAIT_L(0); PG8_BAR; PG8_MMA(0, 0, At, B0); PG8_MMA(0, 1, At, B1); PG8_BAR; PG8_SCHED;
;             PG8_LDA(At, 0, 1); PG8_STAGE(PG8_SB(0, 0), b2, voffB); PG8_STAGE(PG8_SB(0, 1), b2 + hstepB, voffB); PG8_STAGE(PG8_SA(0, 0), a2, voffA);
;             PG8_WAIT_V(8); PG8_WAIT_L(0); PG8_BAR; PG8_MMA(1, 0, At, B0); PG8_MMA(1, 1, At, B1); PG8_BAR; PG8_SCHED;
.LBB0_2105:
	v_add_u32_e32 v3, s64, v239
	ds_read_b128 v[134:137], v3
	ds_read_b128 v[138:141], v3 offset:1024
	ds_read_b128 v[142:145], v3 offset:2048
	ds_read_b128 v[146:149], v3 offset:3072
	v_add_u32_e32 v3, s65, v239
	ds_read_b128 v[150:153], v3
	ds_read_b128 v[154:157], v3 offset:1024
	ds_read_b128 v[158:161], v3 offset:2048
	ds_read_b128 v[162:165], v3 offset:3072
	s_add_u32 s48, s6, 0xfffc0080
	s_addc_u32 s49, s7, -1
	s_cmp_eq_u32 s73, 12
	s_cselect_b32 s51, s43, s49
	s_cselect_b32 s50, s69, s48
	s_cselect_b32 s49, s41, s72
	s_cselect_b32 s48, s70, s71
	v_lshl_add_u64 v[4:5], s[6:7], 0, v[218:219]
	s_add_i32 m0, s37, 0xc000
	ds_read_b128 v[166:169], v240
	ds_read_b128 v[170:173], v240 offset:1024
	ds_read_b128 v[174:177], v240 offset:2048
	ds_read_b128 v[178:181], v240 offset:3072
	ds_read_b128 v[182:185], v240 offset:4096
	ds_read_b128 v[186:189], v240 offset:5120
	ds_read_b128 v[190:193], v240 offset:6144
	ds_read_b128 v[226:229], v240 offset:7168
	global_load_lds_dwordx4 v[4:5], off
	v_lshl_add_u64 v[4:5], s[6:7], 0, v[220:221]
	s_add_i32 m0, s37, 0xe000
	s_nop 0
	global_load_lds_dwordx4 v[4:5], off
	s_waitcnt vmcnt(8)
	s_waitcnt lgkmcnt(0)
	s_barrier
	s_setprio 1
	s_waitcnt lgkmcnt(0)
	v_mfma_f32_16x16x32_bf16 v[130:133], v[134:137], v[166:169], v[130:133]
	v_mfma_f32_16x16x32_bf16 v[126:129], v[142:145], v[166:169], v[126:129]
	v_mfma_f32_16x16x32_bf16 v[122:125], v[134:137], v[174:177], v[122:125]
	v_mfma_f32_16x16x32_bf16 v[118:121], v[142:145], v[174:177], v[118:121]
	v_mfma_f32_16x16x32_bf16 v[114:117], v[134:137], v[182:185], v[114:117]
	v_mfma_f32_16x16x32_bf16 v[110:113], v[142:145], v[182:185], v[110:113]
	v_mfma_f32_16x16x32_bf16 v[106:109], v[134:137], v[190:193], v[106:109]
	v_mfma_f32_16x16x32_bf16 v[102:105], v[142:145], v[190:193], v[102:105]
	v_mfma_f32_16x16x32_bf16 v[130:133], v[138:141], v[170:173], v[130:133]
	v_mfma_f32_16x16x32_bf16 v[126:129], v[146:149], v[170:173], v[126:129]
	v_mfma_f32_16x16x32_bf16 v[122:125], v[138:141], v[178:181], v[122:125]
	v_mfma_f32_16x16x32_bf16 v[118:121], v[146:149], v[178:181], v[118:121]
	v_mfma_f32_16x16x32_bf16 v[114:117], v[138:141], v[186:189], v[114:117]
	v_mfma_f32_16x16x32_bf16 v[110:113], v[146:149], v[186:189], v[110:113]
	v_mfma_f32_16x16x32_bf16 v[106:109], v[138:141], v[226:229], v[106:109]
	v_mfma_f32_16x16x32_bf16 v[102:105], v[146:149], v[226:229], v[102:105]
	s_setprio 0
	s_setprio 1
	v_mfma_f32_16x16x32_bf16 v[98:101], v[150:153], v[166:169], v[98:101]
	s_add_i32 s74, s64, s54
	v_mfma_f32_16x16x32_bf16 v[94:97], v[158:161], v[166:169], v[94:97]
	s_mov_b32 m0, s74
	v_mfma_f32_16x16x32_bf16 v[90:93], v[150:153], v[174:177], v[90:93]
	v_mfma_f32_16x16x32_bf16 v[86:89], v[158:161], v[174:177], v[86:89]
	v_mfma_f32_16x16x32_bf16 v[82:85], v[150:153], v[182:185], v[82:85]
	v_mfma_f32_16x16x32_bf16 v[78:81], v[158:161], v[182:185], v[78:81]
	v_mfma_f32_16x16x32_bf16 v[74:77], v[150:153], v[190:193], v[74:77]
	v_mfma_f32_16x16x32_bf16 v[70:73], v[158:161], v[190:193], v[70:73]
	v_mfma_f32_16x16x32_bf16 v[98:101], v[154:157], v[170:173], v[98:101]
	v_mfma_f32_16x16x32_bf16 v[94:97], v[162:165], v[170:173], v[94:97]
	v_mfma_f32_16x16x32_bf16 v[90:93], v[154:157], v[178:181], v[90:93]
	v_mfma_f32_16x16x32_bf16 v[86:89], v[162:165], v[178:181], v[86:89]
	v_mfma_f32_16x16x32_bf16 v[82:85], v[154:157], v[186:189], v[82:85]
	v_mfma_f32_16x16x32_bf16 v[78:81], v[162:165], v[186:189], v[78:81]
	v_mfma_f32_16x16x32_bf16 v[74:77], v[154:157], v[226:229], v[74:77]
	v_mfma_f32_16x16x32_bf16 v[70:73], v[162:165], v[226:229], v[70:73]
	s_setprio 0
	s_barrier
	v_lshl_add_u64 v[230:231], s[48:49], 0, v[196:197]
	ds_read_b128 v[166:169], v240 offset:16384
	ds_read_b128 v[170:173], v240 offset:17408
	ds_read_b128 v[174:177], v240 offset:18432
	ds_read_b128 v[178:181], v240 offset:19456
	ds_read_b128 v[182:185], v240 offset:20480
	ds_read_b128 v[186:189], v240 offset:21504
	ds_read_b128 v[190:193], v240 offset:22528
	ds_read_b128 v[226:229], v240 offset:23552
	global_load_lds_dwordx4 v[230:231], off
	s_add_i32 m0, s74, 0x2000
	s_add_u32 s74, s48, 0x80000
	v_lshl_add_u64 v[242:243], s[48:49], 0, v[200:201]
	s_addc_u32 s75, s49, 0
	s_add_i32 s76, s65, s54
	global_load_lds_dwordx4 v[242:243], off
	v_lshl_add_u64 v[4:5], s[74:75], 0, v[196:197]
	s_mov_b32 m0, s76
	v_lshl_add_u64 v[244:245], s[50:51], 0, v[194:195]
	global_load_lds_dwordx4 v[4:5], off
	v_lshl_add_u64 v[4:5], s[74:75], 0, v[200:201]
	s_add_i32 m0, s76, 0x2000
	v_lshl_add_u64 v[246:247], s[50:51], 0, v[198:199]
	global_load_lds_dwordx4 v[4:5], off
	s_mov_b32 m0, s37
	s_nop 0
	global_load_lds_dwordx4 v[244:245], off
	s_mov_b32 m0, s39
	s_nop 0
	global_load_lds_dwordx4 v[246:247], off
	s_waitcnt vmcnt(8)
	s_waitcnt lgkmcnt(0)
	s_barrier
; #define PG8_STAGE(bufoff, gbase, voff) do { _Pragma("unroll") for (int _i = 0; _i < 2; ++_i) \
;         __builtin_amdgcn_global_load_lds((const unsigned*)((const char*)(gbase) + (voff)[_i]), (PG8_LAS unsigned*)(lds + (bufoff) + ldsw + _i * 8192), 16, 0, 0); } while (0)
; #define PG8_LDA(dst, b, h) do { _Pragma("unroll") for (int m = 0; m < 4; ++m) _Pragma("unroll") for (int k = 0; k < 2; ++k) dst[m][k] = *(const PG8_LAS bf16x8*)(lds + PG8_SA(b, h) + aoff + m * 2048 + k * 1024); } while (0)
; #define PG8_LDB(dst, b, h) do { _Pragma("unroll") for (int n = 0; n < 2; ++n) _Pragma("unroll") for (int k = 0; k < 2; ++k) dst[n][k] = *(const PG8_LAS bf16x8*)(lds + PG8_SB(b, h) + boff + n * 2048 + k * 1024); } while (0)
; #define PG8_MMA(ai, bj, At, Bt) do { __builtin_amdgcn_s_setprio(1); _Pragma("unroll") for (int m = 0; m < 4; ++m) _Pragma("unroll") for (int n = 0; n < 2; ++n) _Pragma("unroll") for (int k = 0; k < 2; ++k) \
;         acc[ai][bj][m][n] = __builtin_amdgcn_mfma_f32_16x16x32_bf16(Bt[n][k], At[m][k], acc[ai][bj][m][n], 0, 0, 0); __builtin_amdgcn_s_setprio(0); } while (0)
; #define PG8_WAIT_V(n) asm volatile("s_waitcnt vmcnt(" #n ")" ::: "memory")
; #define PG8_WAIT_L(n) asm volatile("s_waitcnt lgkmcnt(" #n ")" ::: "memory")
; #define PG8_BAR __builtin_amdgcn_s_barrier()
; #define PG8_SCHED __builtin_amdgcn_sched_barrier(0)
; template <class Epi, bool ALIGN_EPI, bool ABLK = false>
; __device__ __forceinline__ void gemm_phase(PG8_LAS unsigned char* lds, const Gemm g, const StaticOrder& S, const Epi& E) {
;     ...
;             PG8_WAIT_V(8); PG8_WAIT_L(0); PG8_BAR; PG8_MMA(1, 0, At, B0); PG8_MMA(1, 1, At, B1); PG8_BAR; PG8_SCHED;
;             PG8_LDB(B0, 1, 0); PG8_LDB(B1, 1, 1); PG8_SCHED; PG8_LDA(At, 1, 0); PG8_STAGE(PG8_SA(0, 1), a2 + hstepA, voffA);
;             PG8_WAIT_V(8); PG8_WAIT_L(0); PG8_BAR; PG8_MMA(0, 0, At, B0); PG8_MMA(0, 1, At, B1); PG8_BAR; PG8_SCHED;
	s_setprio 1
	s_waitcnt lgkmcnt(0)
	v_mfma_f32_16x16x32_bf16 v[66:69], v[134:137], v[166:169], v[66:69]
	v_mfma_f32_16x16x32_bf16 v[62:65], v[142:145], v[166:169], v[62:65]
	v_mfma_f32_16x16x32_bf16 v[58:61], v[134:137], v[174:177], v[58:61]
	v_mfma_f32_16x16x32_bf16 v[54:57], v[142:145], v[174:177], v[54:57]
	v_mfma_f32_16x16x32_bf16 v[50:53], v[134:137], v[182:185], v[50:53]
	v_mfma_f32_16x16x32_bf16 v[46:49], v[142:145], v[182:185], v[46:49]
	v_mfma_f32_16x16x32_bf16 v[42:45], v[134:137], v[190:193], v[42:45]
	v_mfma_f32_16x16x32_bf16 v[38:41], v[142:145], v[190:193], v[38:41]
	v_mfma_f32_16x16x32_bf16 v[66:69], v[138:141], v[170:173], v[66:69]
	v_mfma_f32_16x16x32_bf16 v[62:65], v[146:149], v[170:173], v[62:65]
	v_mfma_f32_16x16x32_bf16 v[58:61], v[138:141], v[178:181], v[58:61]
	v_mfma_f32_16x16x32_bf16 v[54:57], v[146:149], v[178:181], v[54:57]
	v_mfma_f32_16x16x32_bf16 v[50:53], v[138:141], v[186:189], v[50:53]
	v_mfma_f32_16x16x32_bf16 v[46:49], v[146:149], v[186:189], v[46:49]
	v_mfma_f32_16x16x32_bf16 v[42:45], v[138:141], v[226:229], v[42:45]
	v_mfma_f32_16x16x32_bf16 v[38:41], v[146:149], v[226:229], v[38:41]
	s_setprio 0
	s_setprio 1
	v_mfma_f32_16x16x32_bf16 v[34:37], v[150:153], v[166:169], v[34:37]
	s_add_i32 s74, 0, 0x18000
	v_mfma_f32_16x16x32_bf16 v[30:33], v[158:161], v[166:169], v[30:33]
	s_add_i32 s75, 0, 0x1c000
	v_mfma_f32_16x16x32_bf16 v[26:29], v[150:153], v[174:177], v[26:29]
	v_mfma_f32_16x16x32_bf16 v[22:25], v[158:161], v[174:177], v[22:25]
	v_mfma_f32_16x16x32_bf16 v[18:21], v[150:153], v[182:185], v[18:21]
	v_mfma_f32_16x16x32_bf16 v[14:17], v[158:161], v[182:185], v[14:17]
	v_mfma_f32_16x16x32_bf16 v[10:13], v[150:153], v[190:193], v[10:13]
	v_mfma_f32_16x16x32_bf16 v[4:7], v[158:161], v[190:193], v[6:9]
	v_mfma_f32_16x16x32_bf16 v[34:37], v[154:157], v[170:173], v[34:37]
	v_mfma_f32_16x16x32_bf16 v[30:33], v[162:165], v[170:173], v[30:33]
	v_mfma_f32_16x16x32_bf16 v[26:29], v[154:157], v[178:181], v[26:29]
	v_mfma_f32_16x16x32_bf16 v[22:25], v[162:165], v[178:181], v[22:25]
	v_mfma_f32_16x16x32_bf16 v[18:21], v[154:157], v[186:189], v[18:21]
	v_mfma_f32_16x16x32_bf16 v[14:17], v[162:165], v[186:189], v[14:17]
	v_mfma_f32_16x16x32_bf16 v[10:13], v[154:157], v[226:229], v[10:13]
	v_mfma_f32_16x16x32_bf16 v[4:7], v[162:165], v[226:229], v[4:7]
	s_setprio 0
	s_barrier
	v_add_u32_e32 v3, s74, v239
	ds_read_b128 v[134:137], v3
	ds_read_b128 v[138:141], v3 offset:1024
	ds_read_b128 v[142:145], v3 offset:2048
	ds_read_b128 v[146:149], v3 offset:3072
	v_add_u32_e32 v3, s75, v239
	ds_read_b128 v[150:153], v3
	ds_read_b128 v[154:157], v3 offset:1024
	ds_read_b128 v[158:161], v3 offset:2048
	ds_read_b128 v[162:165], v3 offset:3072
	s_add_u32 s50, s50, 0x40000
	s_addc_u32 s51, s51, 0
	s_mov_b32 m0, s55
	v_lshl_add_u64 v[8:9], s[50:51], 0, v[194:195]
	ds_read_b128 v[166:169], v240 offset:32768
	ds_read_b128 v[170:173], v240 offset:33792
	ds_read_b128 v[174:177], v240 offset:34816
	ds_read_b128 v[178:181], v240 offset:35840
	ds_read_b128 v[182:185], v240 offset:36864
	ds_read_b128 v[186:189], v240 offset:37888
	ds_read_b128 v[190:193], v240 offset:38912
	ds_read_b128 v[226:229], v240 offset:39936
	global_load_lds_dwordx4 v[8:9], off
	v_lshl_add_u64 v[8:9], s[50:51], 0, v[198:199]
	s_mov_b32 m0, s56
	s_nop 0
	global_load_lds_dwordx4 v[8:9], off
	s_waitcnt vmcnt(8)
	s_waitcnt lgkmcnt(0)
	s_barrier
	s_setprio 1
	s_waitcnt lgkmcnt(0)
	v_mfma_f32_16x16x32_bf16 v[130:133], v[134:137], v[166:169], v[130:133]
	v_mfma_f32_16x16x32_bf16 v[126:129], v[142:145], v[166:169], v[126:129]
	v_mfma_f32_16x16x32_bf16 v[122:125], v[134:137], v[174:177], v[122:125]
	v_mfma_f32_16x16x32_bf16 v[118:121], v[142:145], v[174:177], v[118:121]
	v_mfma_f32_16x16x32_bf16 v[114:117], v[134:137], v[182:185], v[114:117]
	v_mfma_f32_16x16x32_bf16 v[110:113], v[142:145], v[182:185], v[110:113]
	v_mfma_f32_16x16x32_bf16 v[106:109], v[134:137], v[190:193], v[106:109]
	v_mfma_f32_16x16x32_bf16 v[102:105], v[142:145], v[190:193], v[102:105]
	v_mfma_f32_16x16x32_bf16 v[130:133], v[138:141], v[170:173], v[130:133]
	v_mfma_f32_16x16x32_bf16 v[126:129], v[146:149], v[170:173], v[126:129]
	v_mfma_f32_16x16x32_bf16 v[122:125], v[138:141], v[178:181], v[122:125]
	v_mfma_f32_16x16x32_bf16 v[118:121], v[146:149], v[178:181], v[118:121]
	v_mfma_f32_16x16x32_bf16 v[114:117], v[138:141], v[186:189], v[114:117]
	v_mfma_f32_16x16x32_bf16 v[110:113], v[146:149], v[186:189], v[110:113]
	v_mfma_f32_16x16x32_bf16 v[106:109], v[138:141], v[226:229], v[106:109]
	v_mfma_f32_16x16x32_bf16 v[102:105], v[146:149], v[226:229], v[102:105]
	s_setprio 0
	s_setprio 1
	v_mfma_f32_16x16x32_bf16 v[98:101], v[150:153], v[166:169], v[98:101]
	s_add_i32 s50, s74, s54
	v_mfma_f32_16x16x32_bf16 v[94:97], v[158:161], v[166:169], v[94:97]
	s_mov_b32 m0, s50
	v_mfma_f32_16x16x32_bf16 v[90:93], v[150:153], v[174:177], v[90:93]
	v_mfma_f32_16x16x32_bf16 v[86:89], v[158:161], v[174:177], v[86:89]
	v_mfma_f32_16x16x32_bf16 v[82:85], v[150:153], v[182:185], v[82:85]
	v_mfma_f32_16x16x32_bf16 v[78:81], v[158:161], v[182:185], v[78:81]
	v_mfma_f32_16x16x32_bf16 v[74:77], v[150:153], v[190:193], v[74:77]
	v_mfma_f32_16x16x32_bf16 v[70:73], v[158:161], v[190:193], v[70:73]
	v_mfma_f32_16x16x32_bf16 v[98:101], v[154:157], v[170:173], v[98:101]
	v_mfma_f32_16x16x32_bf16 v[94:97], v[162:165], v[170:173], v[94:97]
	v_mfma_f32_16x16x32_bf16 v[90:93], v[154:157], v[178:181], v[90:93]
	v_mfma_f32_16x16x32_bf16 v[86:89], v[162:165], v[178:181], v[86:89]
	v_mfma_f32_16x16x32_bf16 v[82:85], v[154:157], v[186:189], v[82:85]
	v_mfma_f32_16x16x32_bf16 v[78:81], v[162:165], v[186:189], v[78:81]
	v_mfma_f32_16x16x32_bf16 v[74:77], v[154:157], v[226:229], v[74:77]
	v_mfma_f32_16x16x32_bf16 v[70:73], v[162:165], v[226:229], v[70:73]
	s_setprio 0
	s_barrier
; #define PG8_STAGE(bufoff, gbase, voff) do { _Pragma("unroll") for (int _i = 0; _i < 2; ++_i) \
;         __builtin_amdgcn_global_load_lds((const unsigned*)((const char*)(gbase) + (voff)[_i]), (PG8_LAS unsigned*)(lds + (bufoff) + ldsw + _i * 8192), 16, 0, 0); } while (0)
; #define PG8_LDA(dst, b, h) do { _Pragma("unroll") for (int m = 0; m < 4; ++m) _Pragma("unroll") for (int k = 0; k < 2; ++k) dst[m][k] = *(const PG8_LAS bf16x8*)(lds + PG8_SA(b, h) + aoff + m * 2048 + k * 1024); } while (0)
; #define PG8_MMA(ai, bj, At, Bt) do { __builtin_amdgcn_s_setprio(1); _Pragma("unroll") for (int m = 0; m < 4; ++m) _Pragma("unroll") for (int n = 0; n < 2; ++n) _Pragma("unroll") for (int k = 0; k < 2; ++k) \
;         acc[ai][bj][m][n] = __builtin_amdgcn_mfma_f32_16x16x32_bf16(Bt[n][k], At[m][k], acc[ai][bj][m][n], 0, 0, 0); __builtin_amdgcn_s_setprio(0); } while (0)
; #define PG8_WAIT_V(n) asm volatile("s_waitcnt vmcnt(" #n ")" ::: "memory")
; #define PG8_WAIT_L(n) asm volatile("s_waitcnt lgkmcnt(" #n ")" ::: "memory")
; #define PG8_BAR __builtin_amdgcn_s_barrier()
; #define PG8_SCHED __builtin_amdgcn_sched_barrier(0)
; template <class Epi, bool ALIGN_EPI, bool ABLK = false>
; __device__ __forceinline__ void gemm_phase(PG8_LAS unsigned char* lds, const Gemm g, const StaticOrder& S, const Epi& E) {
;     ...
;             PG8_LDA(At, 1, 1); PG8_STAGE(PG8_SB(1, 0), b3, voffB); PG8_STAGE(PG8_SB(1, 1), b3 + hstepB, voffB); PG8_STAGE(PG8_SA(1, 0), a3, voffA);
;             PG8_WAIT_V(8); PG8_WAIT_L(0); PG8_BAR; PG8_MMA(1, 0, At, B0); PG8_MMA(1, 1, At, B1); PG8_BAR; PG8_SCHED;
;         }
	v_lshl_add_u64 v[8:9], v[230:231], 0, s[22:23]
	ds_read_b128 v[166:169], v240 offset:49152
	ds_read_b128 v[170:173], v240 offset:50176
	ds_read_b128 v[174:177], v240 offset:51200
	ds_read_b128 v[178:181], v240 offset:52224
	ds_read_b128 v[182:185], v240 offset:53248
	ds_read_b128 v[186:189], v240 offset:54272
	ds_read_b128 v[190:193], v240 offset:55296
	ds_read_b128 v[226:229], v240 offset:56320
	global_load_lds_dwordx4 v[8:9], off
	s_add_i32 m0, s50, 0x2000
	s_add_u32 s48, s48, 0x80080
	v_lshl_add_u64 v[8:9], v[242:243], 0, s[22:23]
	s_addc_u32 s49, s49, 0
	s_add_i32 s50, s75, s54
	global_load_lds_dwordx4 v[8:9], off
	v_lshl_add_u64 v[8:9], s[48:49], 0, v[196:197]
	s_mov_b32 m0, s50
	s_nop 0
	global_load_lds_dwordx4 v[8:9], off
	v_lshl_add_u64 v[8:9], s[48:49], 0, v[200:201]
	s_add_i32 m0, s50, 0x2000
	s_nop 0
	global_load_lds_dwordx4 v[8:9], off
	v_lshl_add_u64 v[8:9], v[244:245], 0, s[22:23]
	s_mov_b32 m0, s59
	s_nop 0
	global_load_lds_dwordx4 v[8:9], off
	v_lshl_add_u64 v[8:9], v[246:247], 0, s[22:23]
	s_mov_b32 m0, s60
	s_nop 0
	global_load_lds_dwordx4 v[8:9], off
	s_waitcnt vmcnt(8)
	s_waitcnt lgkmcnt(0)
	s_barrier
	s_setprio 1
	s_waitcnt lgkmcnt(0)
	v_mfma_f32_16x16x32_bf16 v[66:69], v[134:137], v[166:169], v[66:69]
	v_mfma_f32_16x16x32_bf16 v[62:65], v[142:145], v[166:169], v[62:65]
	v_mfma_f32_16x16x32_bf16 v[58:61], v[134:137], v[174:177], v[58:61]
	v_mfma_f32_16x16x32_bf16 v[54:57], v[142:145], v[174:177], v[54:57]
	v_mfma_f32_16x16x32_bf16 v[50:53], v[134:137], v[182:185], v[50:53]
	v_mfma_f32_16x16x32_bf16 v[46:49], v[142:145], v[182:185], v[46:49]
	v_mfma_f32_16x16x32_bf16 v[42:45], v[134:137], v[190:193], v[42:45]
	v_mfma_f32_16x16x32_bf16 v[38:41], v[142:145], v[190:193], v[38:41]
	v_mfma_f32_16x16x32_bf16 v[66:69], v[138:141], v[170:173], v[66:69]
	v_mfma_f32_16x16x32_bf16 v[62:65], v[146:149], v[170:173], v[62:65]
	v_mfma_f32_16x16x32_bf16 v[58:61], v[138:141], v[178:181], v[58:61]
	v_mfma_f32_16x16x32_bf16 v[54:57], v[146:149], v[178:181], v[54:57]
	v_mfma_f32_16x16x32_bf16 v[50:53], v[138:141], v[186:189], v[50:53]
	v_mfma_f32_16x16x32_bf16 v[46:49], v[146:149], v[186:189], v[46:49]
	v_mfma_f32_16x16x32_bf16 v[42:45], v[138:141], v[226:229], v[42:45]
	v_mfma_f32_16x16x32_bf16 v[38:41], v[146:149], v[226:229], v[38:41]
	s_setprio 0
	s_setprio 1
	v_mfma_f32_16x16x32_bf16 v[34:37], v[150:153], v[166:169], v[34:37]
	s_add_i32 s73, s73, 2
	v_mfma_f32_16x16x32_bf16 v[30:33], v[158:161], v[166:169], v[30:33]
	s_add_u32 s6, s6, 0x100
	v_mfma_f32_16x16x32_bf16 v[26:29], v[150:153], v[174:177], v[26:29]
	s_addc_u32 s7, s7, 0
	v_mfma_f32_16x16x32_bf16 v[22:25], v[158:161], v[174:177], v[22:25]
	s_add_u32 s71, s71, 0x100
	v_mfma_f32_16x16x32_bf16 v[18:21], v[150:153], v[182:185], v[18:21]
	s_addc_u32 s72, s72, 0
	v_mfma_f32_16x16x32_bf16 v[14:17], v[158:161], v[182:185], v[14:17]
	s_cmp_gt_u32 s73, 13
	v_mfma_f32_16x16x32_bf16 v[8:11], v[150:153], v[190:193], v[10:13]
	v_mfma_f32_16x16x32_bf16 v[4:7], v[158:161], v[190:193], v[4:7]
	v_mfma_f32_16x16x32_bf16 v[34:37], v[154:157], v[170:173], v[34:37]
	v_mfma_f32_16x16x32_bf16 v[30:33], v[162:165], v[170:173], v[30:33]
	v_mfma_f32_16x16x32_bf16 v[26:29], v[154:157], v[178:181], v[26:29]
	v_mfma_f32_16x16x32_bf16 v[22:25], v[162:165], v[178:181], v[22:25]
	v_mfma_f32_16x16x32_bf16 v[18:21], v[154:157], v[186:189], v[18:21]
	v_mfma_f32_16x16x32_bf16 v[14:17], v[162:165], v[186:189], v[14:17]
	v_mfma_f32_16x16x32_bf16 v[10:13], v[154:157], v[226:229], v[8:11]
	v_mfma_f32_16x16x32_bf16 v[6:9], v[162:165], v[226:229], v[4:7]
	s_setprio 0
	s_barrier
	s_cbranch_scc0 .LBB0_2105
	s_and_b64 vcc, exec, s[24:25]
	s_cbranch_vccz .LBB0_2108
	s_barrier

; #define PG8_STAGE(bufoff, gbase, voff) do { _Pragma("unroll") for (int _i = 0; _i < 2; ++_i) \
;         __builtin_amdgcn_global_load_lds((const unsigned*)((const char*)(gbase) + (voff)[_i]), (PG8_LAS unsigned*)(lds + (bufoff) + ldsw + _i * 8192), 16, 0, 0); } while (0)
; #define PG8_LDA(dst, b, h) do { _Pragma("unroll") for (int m = 0; m < 4; ++m) _Pragma("unroll") for (int k = 0; k < 2; ++k) dst[m][k] = *(const PG8_LAS bf16x8*)(lds + PG8_SA(b, h) + aoff + m * 2048 + k * 1024); } while (0)
; #define PG8_LDB(dst, b, h) do { _Pragma("unroll") for (int n = 0; n < 2; ++n) _Pragma("unroll") for (int k = 0; k < 2; ++k) dst[n][k] = *(const PG8_LAS bf16x8*)(lds + PG8_SB(b, h) + boff + n * 2048 + k * 1024); } while (0)
; #define PG8_MMA(ai, bj, At, Bt) do { __builtin_amdgcn_s_setprio(1); _Pragma("unroll") for (int m = 0; m < 4; ++m) _Pragma("unroll") for (int n = 0; n < 2; ++n) _Pragma("unroll") for (int k = 0; k < 2; ++k) \
;         acc[ai][bj][m][n] = __builtin_amdgcn_mfma_f32_16x16x32_bf16(Bt[n][k], At[m][k], acc[ai][bj][m][n], 0, 0, 0); __builtin_amdgcn_s_setprio(0); } while (0)
; #define PG8_WAIT_V(n) asm volatile("s_waitcnt vmcnt(" #n ")" ::: "memory")
; #define PG8_WAIT_L(n) asm volatile("s_waitcnt lgkmcnt(" #n ")" ::: "memory")
; #define PG8_BAR __builtin_amdgcn_s_barrier()
; template <class Epi, bool ALIGN_EPI, bool ABLK = false>
; __device__ __forceinline__ void gemm_phase(PG8_LAS unsigned char* lds, const Gemm g, const StaticOrder& S, const Epi& E) {
;     ...
;         for (int t = 0; t < nt; t += 2) {
;             const bool last = (t == nt - 2);
;             const char* a1 = cA + (size_t)(t + 1) * kstepA;
;             const char* a2 = last ? nA : cA + (size_t)(t + 2) * kstepA; const char* b2 = last ? nB : cB + (size_t)(t + 2) * kstepB;
;             const char* a3 = a2 + kstepA; const char* b3 = b2 + kstepB;
;             PG8_LDB(B0, 0, 0); PG8_LDB(B1, 0, 1); PG8_SCHED; PG8_LDA(At, 0, 0); PG8_STAGE(PG8_SA(1, 1), a1 + hstepA, voffA);
;             PG8_WAIT_V(8); PG8_WAIT_L(0); PG8_BAR; PG8_MMA(0, 0, At, B0); PG8_MMA(0, 1, At, B1); PG8_BAR; PG8_SCHED;
;             PG8_LDA(At, 0, 1); PG8_STAGE(PG8_SB(0, 0), b2, voffB); PG8_STAGE(PG8_SB(0, 1), b2 + hstepB, voffB); PG8_STAGE(PG8_SA(0, 0), a2, voffA);
;             PG8_WAIT_V(8); PG8_WAIT_L(0); PG8_BAR; PG8_MMA(1, 0, At, B0); PG8_MMA(1, 1, At, B1); PG8_BAR; PG8_SCHED;
.LBB0_2289:
	ds_read_b128 v[102:105], v232
	ds_read_b128 v[110:113], v232 offset:1024
	ds_read_b128 v[122:125], v232 offset:2048
	ds_read_b128 v[134:137], v232 offset:3072
	ds_read_b128 v[146:149], v233
	ds_read_b128 v[150:153], v233 offset:1024
	ds_read_b128 v[154:157], v233 offset:2048
	ds_read_b128 v[158:161], v233 offset:3072
	s_cmp_eq_u32 s82, 12
	s_cselect_b32 s85, s51, s57
	s_cselect_b32 s84, s60, s56
	s_cselect_b32 s59, s49, s81
	s_cselect_b32 s58, s61, s80
	s_movk_i32 s86, 0xc000
	v_lshl_add_u64 v[212:213], s[56:57], 0, v[186:187]
	s_mov_b32 s87, -1
	v_lshl_add_u64 v[244:245], v[212:213], 0, s[86:87]
	s_movk_i32 s86, 0xe000
	s_add_i32 m0, s9, 0xc000
	s_mov_b32 s87, -1
	ds_read_b128 v[162:165], v234
	ds_read_b128 v[166:169], v234 offset:1024
	ds_read_b128 v[170:173], v234 offset:2048
	ds_read_b128 v[174:177], v234 offset:3072
	ds_read_b128 v[178:181], v234 offset:4096
	ds_read_b128 v[182:185], v234 offset:5120
	ds_read_b128 v[236:239], v234 offset:6144
	ds_read_b128 v[240:243], v234 offset:7168
	global_load_lds_dwordx4 v[244:245], off
	v_lshl_add_u64 v[212:213], v[212:213], 0, s[86:87]
	s_add_i32 m0, s9, 0xe000
	s_nop 0
	global_load_lds_dwordx4 v[212:213], off
	s_waitcnt vmcnt(8)
	s_waitcnt lgkmcnt(0)
	s_barrier
	s_setprio 1
	s_waitcnt lgkmcnt(0)
	v_mfma_f32_16x16x32_bf16 v[142:145], v[102:105], v[162:165], v[142:145]
	v_mfma_f32_16x16x32_bf16 v[138:141], v[122:125], v[162:165], v[138:141]
	v_mfma_f32_16x16x32_bf16 v[118:121], v[102:105], v[170:173], v[118:121]
	v_mfma_f32_16x16x32_bf16 v[114:117], v[122:125], v[170:173], v[114:117]
	v_mfma_f32_16x16x32_bf16 v[94:97], v[102:105], v[178:181], v[94:97]
	v_mfma_f32_16x16x32_bf16 v[90:93], v[122:125], v[178:181], v[90:93]
	v_mfma_f32_16x16x32_bf16 v[78:81], v[102:105], v[236:239], v[78:81]
	v_mfma_f32_16x16x32_bf16 v[74:77], v[122:125], v[236:239], v[74:77]
	v_mfma_f32_16x16x32_bf16 v[142:145], v[110:113], v[166:169], v[142:145]
	v_mfma_f32_16x16x32_bf16 v[138:141], v[134:137], v[166:169], v[138:141]
	v_mfma_f32_16x16x32_bf16 v[118:121], v[110:113], v[174:177], v[118:121]
	v_mfma_f32_16x16x32_bf16 v[114:117], v[134:137], v[174:177], v[114:117]
	v_mfma_f32_16x16x32_bf16 v[94:97], v[110:113], v[182:185], v[94:97]
	v_mfma_f32_16x16x32_bf16 v[90:93], v[134:137], v[182:185], v[90:93]
	v_mfma_f32_16x16x32_bf16 v[78:81], v[110:113], v[240:243], v[78:81]
	v_mfma_f32_16x16x32_bf16 v[74:77], v[134:137], v[240:243], v[74:77]
	s_setprio 0
	s_setprio 1
	v_mfma_f32_16x16x32_bf16 v[130:133], v[146:149], v[162:165], v[130:133]
	s_add_i32 s83, s77, s65
	v_mfma_f32_16x16x32_bf16 v[126:129], v[154:157], v[162:165], v[126:129]
	s_mov_b32 m0, s83
	v_mfma_f32_16x16x32_bf16 v[106:109], v[146:149], v[170:173], v[106:109]
	v_mfma_f32_16x16x32_bf16 v[98:101], v[154:157], v[170:173], v[98:101]
	v_mfma_f32_16x16x32_bf16 v[86:89], v[146:149], v[178:181], v[86:89]
	v_mfma_f32_16x16x32_bf16 v[82:85], v[154:157], v[178:181], v[82:85]
	v_mfma_f32_16x16x32_bf16 v[70:73], v[146:149], v[236:239], v[70:73]
	v_mfma_f32_16x16x32_bf16 v[66:69], v[154:157], v[236:239], v[66:69]
	v_mfma_f32_16x16x32_bf16 v[130:133], v[150:153], v[166:169], v[130:133]
	v_mfma_f32_16x16x32_bf16 v[126:129], v[158:161], v[166:169], v[126:129]
	v_mfma_f32_16x16x32_bf16 v[106:109], v[150:153], v[174:177], v[106:109]
	v_mfma_f32_16x16x32_bf16 v[98:101], v[158:161], v[174:177], v[98:101]
	v_mfma_f32_16x16x32_bf16 v[86:89], v[150:153], v[182:185], v[86:89]
	v_mfma_f32_16x16x32_bf16 v[82:85], v[158:161], v[182:185], v[82:85]
	v_mfma_f32_16x16x32_bf16 v[70:73], v[150:153], v[240:243], v[70:73]
	v_mfma_f32_16x16x32_bf16 v[66:69], v[158:161], v[240:243], v[66:69]
	s_setprio 0
	s_barrier
	v_lshl_add_u64 v[212:213], s[58:59], 0, v[188:189]
	ds_read_b128 v[162:165], v234 offset:16384
	ds_read_b128 v[166:169], v234 offset:17408
	ds_read_b128 v[170:173], v234 offset:18432
	ds_read_b128 v[174:177], v234 offset:19456
	ds_read_b128 v[178:181], v234 offset:20480
	ds_read_b128 v[182:185], v234 offset:21504
	ds_read_b128 v[236:239], v234 offset:22528
	ds_read_b128 v[240:243], v234 offset:23552
	global_load_lds_dwordx4 v[212:213], off
	s_add_i32 m0, s83, 0x2000
	s_add_u32 s86, s58, 0x40000
	v_lshl_add_u64 v[244:245], s[58:59], 0, v[190:191]
	s_addc_u32 s87, s59, 0
	s_add_i32 s83, s78, s65
	global_load_lds_dwordx4 v[244:245], off
	v_lshl_add_u64 v[246:247], s[86:87], 0, v[188:189]
	s_mov_b32 m0, s83
	s_nop 0
	global_load_lds_dwordx4 v[246:247], off
	v_lshl_add_u64 v[246:247], s[86:87], 0, v[190:191]
	s_add_i32 m0, s83, 0x2000
	s_nop 0
	global_load_lds_dwordx4 v[246:247], off
	v_lshl_add_u64 v[246:247], s[84:85], 0, v[186:187]
	s_mov_b32 m0, s9
	v_lshl_add_u64 v[248:249], v[246:247], 0, s[10:11]
	global_load_lds_dwordx4 v[246:247], off
	s_mov_b32 m0, s66
	s_nop 0
	global_load_lds_dwordx4 v[248:249], off
	s_waitcnt vmcnt(8)
	s_waitcnt lgkmcnt(0)
	s_barrier
; #define PG8_STAGE(bufoff, gbase, voff) do { _Pragma("unroll") for (int _i = 0; _i < 2; ++_i) \
;         __builtin_amdgcn_global_load_lds((const unsigned*)((const char*)(gbase) + (voff)[_i]), (PG8_LAS unsigned*)(lds + (bufoff) + ldsw + _i * 8192), 16, 0, 0); } while (0)
; #define PG8_LDA(dst, b, h) do { _Pragma("unroll") for (int m = 0; m < 4; ++m) _Pragma("unroll") for (int k = 0; k < 2; ++k) dst[m][k] = *(const PG8_LAS bf16x8*)(lds + PG8_SA(b, h) + aoff + m * 2048 + k * 1024); } while (0)
; #define PG8_LDB(dst, b, h) do { _Pragma("unroll") for (int n = 0; n < 2; ++n) _Pragma("unroll") for (int k = 0; k < 2; ++k) dst[n][k] = *(const PG8_LAS bf16x8*)(lds + PG8_SB(b, h) + boff + n * 2048 + k * 1024); } while (0)
; #define PG8_MMA(ai, bj, At, Bt) do { __builtin_amdgcn_s_setprio(1); _Pragma("unroll") for (int m = 0; m < 4; ++m) _Pragma("unroll") for (int n = 0; n < 2; ++n) _Pragma("unroll") for (int k = 0; k < 2; ++k) \
;         acc[ai][bj][m][n] = __builtin_amdgcn_mfma_f32_16x16x32_bf16(Bt[n][k], At[m][k], acc[ai][bj][m][n], 0, 0, 0); __builtin_amdgcn_s_setprio(0); } while (0)
; #define PG8_WAIT_V(n) asm volatile("s_waitcnt vmcnt(" #n ")" ::: "memory")
; #define PG8_WAIT_L(n) asm volatile("s_waitcnt lgkmcnt(" #n ")" ::: "memory")
; #define PG8_BAR __builtin_amdgcn_s_barrier()
; #define PG8_SCHED __builtin_amdgcn_sched_barrier(0)
; template <class Epi, bool ALIGN_EPI, bool ABLK = false>
; __device__ __forceinline__ void gemm_phase(PG8_LAS unsigned char* lds, const Gemm g, const StaticOrder& S, const Epi& E) {
;     ...
;             PG8_WAIT_V(8); PG8_WAIT_L(0); PG8_BAR; PG8_MMA(1, 0, At, B0); PG8_MMA(1, 1, At, B1); PG8_BAR; PG8_SCHED;
;             PG8_LDB(B0, 1, 0); PG8_LDB(B1, 1, 1); PG8_SCHED; PG8_LDA(At, 1, 0); PG8_STAGE(PG8_SA(0, 1), a2 + hstepA, voffA);
;             PG8_WAIT_V(8); PG8_WAIT_L(0); PG8_BAR; PG8_MMA(0, 0, At, B0); PG8_MMA(0, 1, At, B1); PG8_BAR; PG8_SCHED;
	s_setprio 1
	s_waitcnt lgkmcnt(0)
	v_mfma_f32_16x16x32_bf16 v[62:65], v[102:105], v[162:165], v[62:65]
	v_mfma_f32_16x16x32_bf16 v[58:61], v[122:125], v[162:165], v[58:61]
	v_mfma_f32_16x16x32_bf16 v[46:49], v[102:105], v[170:173], v[46:49]
	v_mfma_f32_16x16x32_bf16 v[42:45], v[122:125], v[170:173], v[42:45]
	v_mfma_f32_16x16x32_bf16 v[30:33], v[102:105], v[178:181], v[30:33]
	v_mfma_f32_16x16x32_bf16 v[26:29], v[122:125], v[178:181], v[26:29]
	v_mfma_f32_16x16x32_bf16 v[14:17], v[102:105], v[236:239], v[14:17]
	v_mfma_f32_16x16x32_bf16 v[10:13], v[122:125], v[236:239], v[10:13]
	v_mfma_f32_16x16x32_bf16 v[62:65], v[110:113], v[166:169], v[62:65]
	v_mfma_f32_16x16x32_bf16 v[58:61], v[134:137], v[166:169], v[58:61]
	v_mfma_f32_16x16x32_bf16 v[46:49], v[110:113], v[174:177], v[46:49]
	v_mfma_f32_16x16x32_bf16 v[42:45], v[134:137], v[174:177], v[42:45]
	v_mfma_f32_16x16x32_bf16 v[30:33], v[110:113], v[182:185], v[30:33]
	v_mfma_f32_16x16x32_bf16 v[26:29], v[134:137], v[182:185], v[26:29]
	v_mfma_f32_16x16x32_bf16 v[14:17], v[110:113], v[240:243], v[14:17]
	v_mfma_f32_16x16x32_bf16 v[10:13], v[134:137], v[240:243], v[10:13]
	s_setprio 0
	s_setprio 1
	v_mfma_f32_16x16x32_bf16 v[54:57], v[146:149], v[162:165], v[54:57]
	s_add_i32 s83, 0, 0x18000
	v_mfma_f32_16x16x32_bf16 v[50:53], v[154:157], v[162:165], v[50:53]
	s_add_i32 s84, 0, 0x1c000
	v_mfma_f32_16x16x32_bf16 v[38:41], v[146:149], v[170:173], v[38:41]
	v_mfma_f32_16x16x32_bf16 v[34:37], v[154:157], v[170:173], v[34:37]
	v_mfma_f32_16x16x32_bf16 v[22:25], v[146:149], v[178:181], v[22:25]
	v_mfma_f32_16x16x32_bf16 v[18:21], v[154:157], v[178:181], v[18:21]
	v_mfma_f32_16x16x32_bf16 v[6:9], v[146:149], v[236:239], v[6:9]
	v_mfma_f32_16x16x32_bf16 v[2:5], v[154:157], v[236:239], v[2:5]
	v_mfma_f32_16x16x32_bf16 v[54:57], v[150:153], v[166:169], v[54:57]
	v_mfma_f32_16x16x32_bf16 v[50:53], v[158:161], v[166:169], v[50:53]
	v_mfma_f32_16x16x32_bf16 v[38:41], v[150:153], v[174:177], v[38:41]
	v_mfma_f32_16x16x32_bf16 v[34:37], v[158:161], v[174:177], v[34:37]
	v_mfma_f32_16x16x32_bf16 v[22:25], v[150:153], v[182:185], v[22:25]
	v_mfma_f32_16x16x32_bf16 v[18:21], v[158:161], v[182:185], v[18:21]
	v_mfma_f32_16x16x32_bf16 v[6:9], v[150:153], v[240:243], v[6:9]
	v_mfma_f32_16x16x32_bf16 v[2:5], v[158:161], v[240:243], v[2:5]
	s_setprio 0
	s_barrier
	v_add_u32_e32 v134, s83, v224
	v_add_u32_e32 v158, s84, v224
	ds_read_b128 v[102:105], v134
	ds_read_b128 v[110:113], v134 offset:1024
	ds_read_b128 v[122:125], v134 offset:2048
	ds_read_b128 v[134:137], v134 offset:3072
	ds_read_b128 v[146:149], v158
	ds_read_b128 v[150:153], v158 offset:1024
	ds_read_b128 v[154:157], v158 offset:2048
	ds_read_b128 v[158:161], v158 offset:3072
	s_mov_b32 m0, s67
	v_lshl_add_u64 v[248:249], v[246:247], 0, s[12:13]
	ds_read_b128 v[162:165], v234 offset:32768
	ds_read_b128 v[166:169], v234 offset:33792
	ds_read_b128 v[170:173], v234 offset:34816
	ds_read_b128 v[174:177], v234 offset:35840
	ds_read_b128 v[178:181], v234 offset:36864
	ds_read_b128 v[182:185], v234 offset:37888
	ds_read_b128 v[236:239], v234 offset:38912
	ds_read_b128 v[240:243], v234 offset:39936
	global_load_lds_dwordx4 v[248:249], off
	v_lshl_add_u64 v[248:249], v[246:247], 0, s[24:25]
	s_mov_b32 m0, s68
	s_nop 0
	global_load_lds_dwordx4 v[248:249], off
	s_waitcnt vmcnt(8)
	s_waitcnt lgkmcnt(0)
	s_barrier
	s_setprio 1
	s_waitcnt lgkmcnt(0)
	v_mfma_f32_16x16x32_bf16 v[142:145], v[102:105], v[162:165], v[142:145]
	v_mfma_f32_16x16x32_bf16 v[138:141], v[122:125], v[162:165], v[138:141]
	v_mfma_f32_16x16x32_bf16 v[118:121], v[102:105], v[170:173], v[118:121]
	v_mfma_f32_16x16x32_bf16 v[114:117], v[122:125], v[170:173], v[114:117]
	v_mfma_f32_16x16x32_bf16 v[94:97], v[102:105], v[178:181], v[94:97]
	v_mfma_f32_16x16x32_bf16 v[90:93], v[122:125], v[178:181], v[90:93]
	v_mfma_f32_16x16x32_bf16 v[78:81], v[102:105], v[236:239], v[78:81]
	v_mfma_f32_16x16x32_bf16 v[74:77], v[122:125], v[236:239], v[74:77]
	v_mfma_f32_16x16x32_bf16 v[142:145], v[110:113], v[166:169], v[142:145]
	v_mfma_f32_16x16x32_bf16 v[138:141], v[134:137], v[166:169], v[138:141]
	v_mfma_f32_16x16x32_bf16 v[118:121], v[110:113], v[174:177], v[118:121]
	v_mfma_f32_16x16x32_bf16 v[114:117], v[134:137], v[174:177], v[114:117]
	v_mfma_f32_16x16x32_bf16 v[94:97], v[110:113], v[182:185], v[94:97]
	v_mfma_f32_16x16x32_bf16 v[90:93], v[134:137], v[182:185], v[90:93]
	v_mfma_f32_16x16x32_bf16 v[78:81], v[110:113], v[240:243], v[78:81]
	v_mfma_f32_16x16x32_bf16 v[74:77], v[134:137], v[240:243], v[74:77]
	s_setprio 0
	s_setprio 1
	v_mfma_f32_16x16x32_bf16 v[130:133], v[146:149], v[162:165], v[130:133]
	s_add_i32 s83, s83, s65
	v_mfma_f32_16x16x32_bf16 v[126:129], v[154:157], v[162:165], v[126:129]
	s_mov_b32 m0, s83
	v_mfma_f32_16x16x32_bf16 v[106:109], v[146:149], v[170:173], v[106:109]
	v_mfma_f32_16x16x32_bf16 v[98:101], v[154:157], v[170:173], v[98:101]
	v_mfma_f32_16x16x32_bf16 v[86:89], v[146:149], v[178:181], v[86:89]
	v_mfma_f32_16x16x32_bf16 v[82:85], v[154:157], v[178:181], v[82:85]
	v_mfma_f32_16x16x32_bf16 v[70:73], v[146:149], v[236:239], v[70:73]
	v_mfma_f32_16x16x32_bf16 v[66:69], v[154:157], v[236:239], v[66:69]
	v_mfma_f32_16x16x32_bf16 v[130:133], v[150:153], v[166:169], v[130:133]
	v_mfma_f32_16x16x32_bf16 v[126:129], v[158:161], v[166:169], v[126:129]
	v_mfma_f32_16x16x32_bf16 v[106:109], v[150:153], v[174:177], v[106:109]
	v_mfma_f32_16x16x32_bf16 v[98:101], v[158:161], v[174:177], v[98:101]
	v_mfma_f32_16x16x32_bf16 v[86:89], v[150:153], v[182:185], v[86:89]
	v_mfma_f32_16x16x32_bf16 v[82:85], v[158:161], v[182:185], v[82:85]
	v_mfma_f32_16x16x32_bf16 v[70:73], v[150:153], v[240:243], v[70:73]
	v_mfma_f32_16x16x32_bf16 v[66:69], v[158:161], v[240:243], v[66:69]
	s_setprio 0
	s_barrier
; #define PG8_STAGE(bufoff, gbase, voff) do { _Pragma("unroll") for (int _i = 0; _i < 2; ++_i) \
;         __builtin_amdgcn_global_load_lds((const unsigned*)((const char*)(gbase) + (voff)[_i]), (PG8_LAS unsigned*)(lds + (bufoff) + ldsw + _i * 8192), 16, 0, 0); } while (0)
; #define PG8_LDA(dst, b, h) do { _Pragma("unroll") for (int m = 0; m < 4; ++m) _Pragma("unroll") for (int k = 0; k < 2; ++k) dst[m][k] = *(const PG8_LAS bf16x8*)(lds + PG8_SA(b, h) + aoff + m * 2048 + k * 1024); } while (0)
; #define PG8_MMA(ai, bj, At, Bt) do { __builtin_amdgcn_s_setprio(1); _Pragma("unroll") for (int m = 0; m < 4; ++m) _Pragma("unroll") for (int n = 0; n < 2; ++n) _Pragma("unroll") for (int k = 0; k < 2; ++k) \
;         acc[ai][bj][m][n] = __builtin_amdgcn_mfma_f32_16x16x32_bf16(Bt[n][k], At[m][k], acc[ai][bj][m][n], 0, 0, 0); __builtin_amdgcn_s_setprio(0); } while (0)
; #define PG8_WAIT_V(n) asm volatile("s_waitcnt vmcnt(" #n ")" ::: "memory")
; #define PG8_WAIT_L(n) asm volatile("s_waitcnt lgkmcnt(" #n ")" ::: "memory")
; #define PG8_BAR __builtin_amdgcn_s_barrier()
; #define PG8_SCHED __builtin_amdgcn_sched_barrier(0)
; template <class Epi, bool ALIGN_EPI, bool ABLK = false>
; __device__ __forceinline__ void gemm_phase(PG8_LAS unsigned char* lds, const Gemm g, const StaticOrder& S, const Epi& E) {
;     ...
;             PG8_LDA(At, 1, 1); PG8_STAGE(PG8_SB(1, 0), b3, voffB); PG8_STAGE(PG8_SB(1, 1), b3 + hstepB, voffB); PG8_STAGE(PG8_SA(1, 0), a3, voffA);
;             PG8_WAIT_V(8); PG8_WAIT_L(0); PG8_BAR; PG8_MMA(1, 0, At, B0); PG8_MMA(1, 1, At, B1); PG8_BAR; PG8_SCHED;
;         }
	v_lshl_add_u64 v[212:213], v[212:213], 0, s[34:35]
	ds_read_b128 v[162:165], v234 offset:49152
	ds_read_b128 v[166:169], v234 offset:50176
	ds_read_b128 v[170:173], v234 offset:51200
	ds_read_b128 v[174:177], v234 offset:52224
	ds_read_b128 v[178:181], v234 offset:53248
	ds_read_b128 v[182:185], v234 offset:54272
	ds_read_b128 v[236:239], v234 offset:55296
	ds_read_b128 v[240:243], v234 offset:56320
	global_load_lds_dwordx4 v[212:213], off
	s_add_i32 m0, s83, 0x2000
	s_add_u32 s58, s58, 0x40080
	v_lshl_add_u64 v[212:213], v[244:245], 0, s[34:35]
	s_addc_u32 s59, s59, 0
	s_add_i32 s83, s84, s65
	global_load_lds_dwordx4 v[212:213], off
	v_lshl_add_u64 v[212:213], s[58:59], 0, v[188:189]
	s_mov_b32 m0, s83
	s_nop 0
	global_load_lds_dwordx4 v[212:213], off
	v_lshl_add_u64 v[212:213], s[58:59], 0, v[190:191]
	s_add_i32 m0, s83, 0x2000
	s_nop 0
	global_load_lds_dwordx4 v[212:213], off
	v_lshl_add_u64 v[212:213], v[246:247], 0, s[36:37]
	s_mov_b32 m0, s71
	s_nop 0
	global_load_lds_dwordx4 v[212:213], off
	v_lshl_add_u64 v[212:213], v[246:247], 0, s[38:39]
	s_mov_b32 m0, s72
	s_nop 0
	global_load_lds_dwordx4 v[212:213], off
	s_waitcnt vmcnt(8)
	s_waitcnt lgkmcnt(0)
	s_barrier
	s_setprio 1
	s_waitcnt lgkmcnt(0)
	v_mfma_f32_16x16x32_bf16 v[62:65], v[102:105], v[162:165], v[62:65]
	v_mfma_f32_16x16x32_bf16 v[58:61], v[122:125], v[162:165], v[58:61]
	v_mfma_f32_16x16x32_bf16 v[46:49], v[102:105], v[170:173], v[46:49]
	v_mfma_f32_16x16x32_bf16 v[42:45], v[122:125], v[170:173], v[42:45]
	v_mfma_f32_16x16x32_bf16 v[30:33], v[102:105], v[178:181], v[30:33]
	v_mfma_f32_16x16x32_bf16 v[26:29], v[122:125], v[178:181], v[26:29]
	v_mfma_f32_16x16x32_bf16 v[14:17], v[102:105], v[236:239], v[14:17]
	v_mfma_f32_16x16x32_bf16 v[10:13], v[122:125], v[236:239], v[10:13]
	v_mfma_f32_16x16x32_bf16 v[62:65], v[110:113], v[166:169], v[62:65]
	v_mfma_f32_16x16x32_bf16 v[58:61], v[134:137], v[166:169], v[58:61]
	v_mfma_f32_16x16x32_bf16 v[46:49], v[110:113], v[174:177], v[46:49]
	v_mfma_f32_16x16x32_bf16 v[42:45], v[134:137], v[174:177], v[42:45]
	v_mfma_f32_16x16x32_bf16 v[30:33], v[110:113], v[182:185], v[30:33]
	v_mfma_f32_16x16x32_bf16 v[26:29], v[134:137], v[182:185], v[26:29]
	v_mfma_f32_16x16x32_bf16 v[14:17], v[110:113], v[240:243], v[14:17]
	v_mfma_f32_16x16x32_bf16 v[10:13], v[134:137], v[240:243], v[10:13]
	s_setprio 0
	s_setprio 1
	v_mfma_f32_16x16x32_bf16 v[54:57], v[146:149], v[162:165], v[54:57]
	s_add_i32 s82, s82, 2
	v_mfma_f32_16x16x32_bf16 v[50:53], v[154:157], v[162:165], v[50:53]
	s_add_u32 s80, s80, 0x100
	v_mfma_f32_16x16x32_bf16 v[38:41], v[146:149], v[170:173], v[38:41]
	s_addc_u32 s81, s81, 0
	v_mfma_f32_16x16x32_bf16 v[34:37], v[154:157], v[170:173], v[34:37]
	s_add_u32 s56, s56, 0x10000
	v_mfma_f32_16x16x32_bf16 v[22:25], v[146:149], v[178:181], v[22:25]
	s_addc_u32 s57, s57, 0
	v_mfma_f32_16x16x32_bf16 v[18:21], v[154:157], v[178:181], v[18:21]
	s_cmp_gt_u32 s82, 13
	v_mfma_f32_16x16x32_bf16 v[6:9], v[146:149], v[236:239], v[6:9]
	v_mfma_f32_16x16x32_bf16 v[2:5], v[154:157], v[236:239], v[2:5]
	v_mfma_f32_16x16x32_bf16 v[54:57], v[150:153], v[166:169], v[54:57]
	v_mfma_f32_16x16x32_bf16 v[50:53], v[158:161], v[166:169], v[50:53]
	v_mfma_f32_16x16x32_bf16 v[38:41], v[150:153], v[174:177], v[38:41]
	v_mfma_f32_16x16x32_bf16 v[34:37], v[158:161], v[174:177], v[34:37]
	v_mfma_f32_16x16x32_bf16 v[22:25], v[150:153], v[182:185], v[22:25]
	v_mfma_f32_16x16x32_bf16 v[18:21], v[158:161], v[182:185], v[18:21]
	v_mfma_f32_16x16x32_bf16 v[6:9], v[150:153], v[240:243], v[6:9]
	v_mfma_f32_16x16x32_bf16 v[2:5], v[158:161], v[240:243], v[2:5]
	s_setprio 0
	s_barrier
	s_cbranch_scc0 .LBB0_2289
	s_and_b64 vcc, exec, s[40:41]
	s_cbranch_vccz .LBB0_2292
	s_barrier

; #define PG8_STAGE(bufoff, gbase, voff) do { _Pragma("unroll") for (int _i = 0; _i < 2; ++_i) \
;         __builtin_amdgcn_global_load_lds((const unsigned*)((const char*)(gbase) + (voff)[_i]), (PG8_LAS unsigned*)(lds + (bufoff) + ldsw + _i * 8192), 16, 0, 0); } while (0)
; #define PG8_LDA(dst, b, h) do { _Pragma("unroll") for (int m = 0; m < 4; ++m) _Pragma("unroll") for (int k = 0; k < 2; ++k) dst[m][k] = *(const PG8_LAS bf16x8*)(lds + PG8_SA(b, h) + aoff + m * 2048 + k * 1024); } while (0)
; #define PG8_LDB(dst, b, h) do { _Pragma("unroll") for (int n = 0; n < 2; ++n) _Pragma("unroll") for (int k = 0; k < 2; ++k) dst[n][k] = *(const PG8_LAS bf16x8*)(lds + PG8_SB(b, h) + boff + n * 2048 + k * 1024); } while (0)
; #define PG8_MMA(ai, bj, At, Bt) do { __builtin_amdgcn_s_setprio(1); _Pragma("unroll") for (int m = 0; m < 4; ++m) _Pragma("unroll") for (int n = 0; n < 2; ++n) _Pragma("unroll") for (int k = 0; k < 2; ++k) \
;         acc[ai][bj][m][n] = __builtin_amdgcn_mfma_f32_16x16x32_bf16(Bt[n][k], At[m][k], acc[ai][bj][m][n], 0, 0, 0); __builtin_amdgcn_s_setprio(0); } while (0)
; #define PG8_WAIT_V(n) asm volatile("s_waitcnt vmcnt(" #n ")" ::: "memory")
; #define PG8_WAIT_L(n) asm volatile("s_waitcnt lgkmcnt(" #n ")" ::: "memory")
; #define PG8_BAR __builtin_amdgcn_s_barrier()
; template <class Epi, bool ALIGN_EPI, bool ABLK = false>
; __device__ __forceinline__ void gemm_phase(PG8_LAS unsigned char* lds, const Gemm g, const StaticOrder& S, const Epi& E) {
;     ...
;         for (int t = 0; t < nt; t += 2) {
;             const bool last = (t == nt - 2);
;             const char* a1 = cA + (size_t)(t + 1) * kstepA;
;             const char* a2 = last ? nA : cA + (size_t)(t + 2) * kstepA; const char* b2 = last ? nB : cB + (size_t)(t + 2) * kstepB;
;             const char* a3 = a2 + kstepA; const char* b3 = b2 + kstepB;
;             PG8_LDB(B0, 0, 0); PG8_LDB(B1, 0, 1); PG8_SCHED; PG8_LDA(At, 0, 0); PG8_STAGE(PG8_SA(1, 1), a1 + hstepA, voffA);
;             PG8_WAIT_V(8); PG8_WAIT_L(0); PG8_BAR; PG8_MMA(0, 0, At, B0); PG8_MMA(0, 1, At, B1); PG8_BAR; PG8_SCHED;
;             PG8_LDA(At, 0, 1); PG8_STAGE(PG8_SB(0, 0), b2, voffB); PG8_STAGE(PG8_SB(0, 1), b2 + hstepB, voffB); PG8_STAGE(PG8_SA(0, 0), a2, voffA);
;             PG8_WAIT_V(8); PG8_WAIT_L(0); PG8_BAR; PG8_MMA(1, 0, At, B0); PG8_MMA(1, 1, At, B1); PG8_BAR; PG8_SCHED;
.LBB0_2495:
	ds_read_b128 v[132:135], v251
	ds_read_b128 v[178:181], v251 offset:1024
	ds_read_b128 v[182:185], v251 offset:2048
	ds_read_b128 v[186:189], v251 offset:3072
	ds_read_b128 v[190:193], v251 offset:16384
	ds_read_b128 v[194:197], v251 offset:17408
	ds_read_b128 v[198:201], v251 offset:18432
	ds_read_b128 v[202:205], v251 offset:19456
	s_add_u32 s60, s24, s58
	s_addc_u32 s61, s25, s59
	s_sub_u32 s98, s60, 0x10000
	s_subb_u32 s99, s61, 0
	s_cmp_eq_u32 s83, 12
	s_cselect_b32 s101, s53, s61
	s_cselect_b32 s100, s79, s60
	s_cselect_b32 s61, s51, s82
	s_cselect_b32 s60, s80, s81
	s_add_i32 m0, s66, 0xc000
	ds_read_b128 v[206:209], v176
	ds_read_b128 v[210:213], v176 offset:1024
	ds_read_b128 v[214:217], v176 offset:2048
	ds_read_b128 v[218:221], v176 offset:3072
	ds_read_b128 v[222:225], v176 offset:4096
	ds_read_b128 v[226:229], v176 offset:5120
	ds_read_b128 v[230:233], v176 offset:6144
	ds_read_b128 v[234:237], v176 offset:7168
	global_load_lds_dwordx4 v249, s[98:99]
	s_add_i32 m0, s66, 0xe000
	s_nop 0
	global_load_lds_dwordx4 v250, s[98:99]
	s_waitcnt vmcnt(8)
	s_waitcnt lgkmcnt(0)
	s_barrier
	s_setprio 1
	s_waitcnt lgkmcnt(0)
	v_mfma_f32_16x16x32_bf16 v[126:129], v[132:135], v[206:209], v[126:129]
	v_mfma_f32_16x16x32_bf16 v[122:125], v[182:185], v[206:209], v[122:125]
	v_mfma_f32_16x16x32_bf16 v[118:121], v[132:135], v[214:217], v[118:121]
	v_mfma_f32_16x16x32_bf16 v[114:117], v[182:185], v[214:217], v[114:117]
	v_mfma_f32_16x16x32_bf16 v[110:113], v[132:135], v[222:225], v[110:113]
	v_mfma_f32_16x16x32_bf16 v[106:109], v[182:185], v[222:225], v[106:109]
	v_mfma_f32_16x16x32_bf16 v[102:105], v[132:135], v[230:233], v[102:105]
	v_mfma_f32_16x16x32_bf16 v[98:101], v[182:185], v[230:233], v[98:101]
	v_mfma_f32_16x16x32_bf16 v[126:129], v[178:181], v[210:213], v[126:129]
	v_mfma_f32_16x16x32_bf16 v[122:125], v[186:189], v[210:213], v[122:125]
	v_mfma_f32_16x16x32_bf16 v[118:121], v[178:181], v[218:221], v[118:121]
	v_mfma_f32_16x16x32_bf16 v[114:117], v[186:189], v[218:221], v[114:117]
	v_mfma_f32_16x16x32_bf16 v[110:113], v[178:181], v[226:229], v[110:113]
	v_mfma_f32_16x16x32_bf16 v[106:109], v[186:189], v[226:229], v[106:109]
	v_mfma_f32_16x16x32_bf16 v[102:105], v[178:181], v[234:237], v[102:105]
	v_mfma_f32_16x16x32_bf16 v[98:101], v[186:189], v[234:237], v[98:101]
	s_setprio 0
	s_setprio 1
	v_mfma_f32_16x16x32_bf16 v[94:97], v[190:193], v[206:209], v[94:97]
	s_add_i32 s86, s75, s9
	v_mfma_f32_16x16x32_bf16 v[90:93], v[198:201], v[206:209], v[90:93]
	s_mov_b32 m0, s86
	v_mfma_f32_16x16x32_bf16 v[86:89], v[190:193], v[214:217], v[86:89]
	v_mfma_f32_16x16x32_bf16 v[82:85], v[198:201], v[214:217], v[82:85]
	v_mfma_f32_16x16x32_bf16 v[78:81], v[190:193], v[222:225], v[78:81]
	v_mfma_f32_16x16x32_bf16 v[74:77], v[198:201], v[222:225], v[74:77]
	v_mfma_f32_16x16x32_bf16 v[70:73], v[190:193], v[230:233], v[70:73]
	v_mfma_f32_16x16x32_bf16 v[66:69], v[198:201], v[230:233], v[66:69]
	v_mfma_f32_16x16x32_bf16 v[94:97], v[194:197], v[210:213], v[94:97]
	v_mfma_f32_16x16x32_bf16 v[90:93], v[202:205], v[210:213], v[90:93]
	v_mfma_f32_16x16x32_bf16 v[86:89], v[194:197], v[218:221], v[86:89]
	v_mfma_f32_16x16x32_bf16 v[82:85], v[202:205], v[218:221], v[82:85]
	v_mfma_f32_16x16x32_bf16 v[78:81], v[194:197], v[226:229], v[78:81]
	v_mfma_f32_16x16x32_bf16 v[74:77], v[202:205], v[226:229], v[74:77]
	v_mfma_f32_16x16x32_bf16 v[70:73], v[194:197], v[234:237], v[70:73]
	v_mfma_f32_16x16x32_bf16 v[66:69], v[202:205], v[234:237], v[66:69]
	s_setprio 0
	s_barrier
	ds_read_b128 v[206:209], v176 offset:16384
	ds_read_b128 v[210:213], v176 offset:17408
	ds_read_b128 v[214:217], v176 offset:18432
	ds_read_b128 v[218:221], v176 offset:19456
	ds_read_b128 v[222:225], v176 offset:20480
	ds_read_b128 v[226:229], v176 offset:21504
	ds_read_b128 v[230:233], v176 offset:22528
	ds_read_b128 v[234:237], v176 offset:23552
	global_load_lds_dwordx4 v140, s[60:61]
	s_add_i32 m0, s86, 0x2000
	s_add_u32 s86, s60, 0x40000
	s_addc_u32 s87, s61, 0
	s_add_i32 s88, s76, s9
	global_load_lds_dwordx4 v142, s[60:61]
	s_mov_b32 m0, s88
	s_nop 0
	global_load_lds_dwordx4 v140, s[86:87]
	s_add_i32 m0, s88, 0x2000
	s_nop 0
	global_load_lds_dwordx4 v142, s[86:87]
	s_mov_b32 m0, s66
	s_nop 0
	global_load_lds_dwordx4 v138, s[100:101]
	s_mov_b32 m0, s67
	s_nop 0
	global_load_lds_dwordx4 v244, s[100:101]
	s_waitcnt vmcnt(8)
	s_waitcnt lgkmcnt(0)
	s_barrier
	s_setprio 1
	s_waitcnt lgkmcnt(0)
	v_mfma_f32_16x16x32_bf16 v[62:65], v[132:135], v[206:209], v[62:65]
	v_mfma_f32_16x16x32_bf16 v[58:61], v[182:185], v[206:209], v[58:61]
	v_mfma_f32_16x16x32_bf16 v[54:57], v[132:135], v[214:217], v[54:57]
	v_mfma_f32_16x16x32_bf16 v[50:53], v[182:185], v[214:217], v[50:53]
	v_mfma_f32_16x16x32_bf16 v[46:49], v[132:135], v[222:225], v[46:49]
	v_mfma_f32_16x16x32_bf16 v[42:45], v[182:185], v[222:225], v[42:45]
	v_mfma_f32_16x16x32_bf16 v[38:41], v[132:135], v[230:233], v[38:41]
	v_mfma_f32_16x16x32_bf16 v[34:37], v[182:185], v[230:233], v[34:37]
	v_mfma_f32_16x16x32_bf16 v[62:65], v[178:181], v[210:213], v[62:65]
	v_mfma_f32_16x16x32_bf16 v[58:61], v[186:189], v[210:213], v[58:61]
	v_mfma_f32_16x16x32_bf16 v[54:57], v[178:181], v[218:221], v[54:57]
	v_mfma_f32_16x16x32_bf16 v[50:53], v[186:189], v[218:221], v[50:53]
	v_mfma_f32_16x16x32_bf16 v[46:49], v[178:181], v[226:229], v[46:49]
	v_mfma_f32_16x16x32_bf16 v[42:45], v[186:189], v[226:229], v[42:45]
	v_mfma_f32_16x16x32_bf16 v[38:41], v[178:181], v[234:237], v[38:41]
	v_mfma_f32_16x16x32_bf16 v[34:37], v[186:189], v[234:237], v[34:37]
	s_setprio 0
	s_setprio 1
	v_mfma_f32_16x16x32_bf16 v[30:33], v[190:193], v[206:209], v[30:33]
	s_add_i32 s84, 0, 0x18000
	v_mfma_f32_16x16x32_bf16 v[26:29], v[198:201], v[206:209], v[26:29]
	s_add_i32 s85, 0, 0x1c000
	v_mfma_f32_16x16x32_bf16 v[22:25], v[190:193], v[214:217], v[22:25]
	v_mfma_f32_16x16x32_bf16 v[18:21], v[198:201], v[214:217], v[18:21]
	v_mfma_f32_16x16x32_bf16 v[14:17], v[190:193], v[222:225], v[14:17]
	v_mfma_f32_16x16x32_bf16 v[10:13], v[198:201], v[222:225], v[10:13]
	v_mfma_f32_16x16x32_bf16 v[6:9], v[190:193], v[230:233], v[6:9]
	v_mfma_f32_16x16x32_bf16 v[2:5], v[198:201], v[230:233], v[2:5]
	v_mfma_f32_16x16x32_bf16 v[30:33], v[194:197], v[210:213], v[30:33]
	v_mfma_f32_16x16x32_bf16 v[26:29], v[202:205], v[210:213], v[26:29]
	v_mfma_f32_16x16x32_bf16 v[22:25], v[194:197], v[218:221], v[22:25]
	v_mfma_f32_16x16x32_bf16 v[18:21], v[202:205], v[218:221], v[18:21]
	v_mfma_f32_16x16x32_bf16 v[14:17], v[194:197], v[226:229], v[14:17]
	v_mfma_f32_16x16x32_bf16 v[10:13], v[202:205], v[226:229], v[10:13]
	v_mfma_f32_16x16x32_bf16 v[6:9], v[194:197], v[234:237], v[6:9]
	v_mfma_f32_16x16x32_bf16 v[2:5], v[202:205], v[234:237], v[2:5]
	s_setprio 0
	s_barrier
; #define PG8_STAGE(bufoff, gbase, voff) do { _Pragma("unroll") for (int _i = 0; _i < 2; ++_i) \
;         __builtin_amdgcn_global_load_lds((const unsigned*)((const char*)(gbase) + (voff)[_i]), (PG8_LAS unsigned*)(lds + (bufoff) + ldsw + _i * 8192), 16, 0, 0); } while (0)
; #define PG8_LDA(dst, b, h) do { _Pragma("unroll") for (int m = 0; m < 4; ++m) _Pragma("unroll") for (int k = 0; k < 2; ++k) dst[m][k] = *(const PG8_LAS bf16x8*)(lds + PG8_SA(b, h) + aoff + m * 2048 + k * 1024); } while (0)
; #define PG8_LDB(dst, b, h) do { _Pragma("unroll") for (int n = 0; n < 2; ++n) _Pragma("unroll") for (int k = 0; k < 2; ++k) dst[n][k] = *(const PG8_LAS bf16x8*)(lds + PG8_SB(b, h) + boff + n * 2048 + k * 1024); } while (0)
; #define PG8_MMA(ai, bj, At, Bt) do { __builtin_amdgcn_s_setprio(1); _Pragma("unroll") for (int m = 0; m < 4; ++m) _Pragma("unroll") for (int n = 0; n < 2; ++n) _Pragma("unroll") for (int k = 0; k < 2; ++k) \
;         acc[ai][bj][m][n] = __builtin_amdgcn_mfma_f32_16x16x32_bf16(Bt[n][k], At[m][k], acc[ai][bj][m][n], 0, 0, 0); __builtin_amdgcn_s_setprio(0); } while (0)
; #define PG8_WAIT_V(n) asm volatile("s_waitcnt vmcnt(" #n ")" ::: "memory")
; #define PG8_WAIT_L(n) asm volatile("s_waitcnt lgkmcnt(" #n ")" ::: "memory")
; #define PG8_BAR __builtin_amdgcn_s_barrier()
; #define PG8_SCHED __builtin_amdgcn_sched_barrier(0)
; template <class Epi, bool ALIGN_EPI, bool ABLK = false>
; __device__ __forceinline__ void gemm_phase(PG8_LAS unsigned char* lds, const Gemm g, const StaticOrder& S, const Epi& E) {
;     ...
;             PG8_LDB(B0, 1, 0); PG8_LDB(B1, 1, 1); PG8_SCHED; PG8_LDA(At, 1, 0); PG8_STAGE(PG8_SA(0, 1), a2 + hstepA, voffA);
;             PG8_WAIT_V(8); PG8_WAIT_L(0); PG8_BAR; PG8_MMA(0, 0, At, B0); PG8_MMA(0, 1, At, B1); PG8_BAR; PG8_SCHED;
;             PG8_LDA(At, 1, 1); PG8_STAGE(PG8_SB(1, 0), b3, voffB); PG8_STAGE(PG8_SB(1, 1), b3 + hstepB, voffB); PG8_STAGE(PG8_SA(1, 0), a3, voffA);
;             PG8_WAIT_V(8); PG8_WAIT_L(0); PG8_BAR; PG8_MMA(1, 0, At, B0); PG8_MMA(1, 1, At, B1); PG8_BAR; PG8_SCHED;
;         }
	ds_read_b128 v[132:135], v251 offset:32768
	ds_read_b128 v[178:181], v251 offset:33792
	ds_read_b128 v[182:185], v251 offset:34816
	ds_read_b128 v[186:189], v251 offset:35840
	ds_read_b128 v[190:193], v251 offset:49152
	ds_read_b128 v[194:197], v251 offset:50176
	ds_read_b128 v[198:201], v251 offset:51200
	ds_read_b128 v[202:205], v251 offset:52224
	s_mov_b32 m0, s68
	ds_read_b128 v[206:209], v176 offset:32768
	ds_read_b128 v[210:213], v176 offset:33792
	ds_read_b128 v[214:217], v176 offset:34816
	ds_read_b128 v[218:221], v176 offset:35840
	ds_read_b128 v[222:225], v176 offset:36864
	ds_read_b128 v[226:229], v176 offset:37888
	ds_read_b128 v[230:233], v176 offset:38912
	ds_read_b128 v[234:237], v176 offset:39936
	global_load_lds_dwordx4 v245, s[100:101]
	s_mov_b32 m0, s69
	s_nop 0
	global_load_lds_dwordx4 v246, s[100:101]
	s_waitcnt vmcnt(8)
	s_waitcnt lgkmcnt(0)
	s_barrier
	s_setprio 1
	s_waitcnt lgkmcnt(0)
	v_mfma_f32_16x16x32_bf16 v[126:129], v[132:135], v[206:209], v[126:129]
	v_mfma_f32_16x16x32_bf16 v[122:125], v[182:185], v[206:209], v[122:125]
	v_mfma_f32_16x16x32_bf16 v[118:121], v[132:135], v[214:217], v[118:121]
	v_mfma_f32_16x16x32_bf16 v[114:117], v[182:185], v[214:217], v[114:117]
	v_mfma_f32_16x16x32_bf16 v[110:113], v[132:135], v[222:225], v[110:113]
	v_mfma_f32_16x16x32_bf16 v[106:109], v[182:185], v[222:225], v[106:109]
	v_mfma_f32_16x16x32_bf16 v[102:105], v[132:135], v[230:233], v[102:105]
	v_mfma_f32_16x16x32_bf16 v[98:101], v[182:185], v[230:233], v[98:101]
	v_mfma_f32_16x16x32_bf16 v[126:129], v[178:181], v[210:213], v[126:129]
	v_mfma_f32_16x16x32_bf16 v[122:125], v[186:189], v[210:213], v[122:125]
	v_mfma_f32_16x16x32_bf16 v[118:121], v[178:181], v[218:221], v[118:121]
	v_mfma_f32_16x16x32_bf16 v[114:117], v[186:189], v[218:221], v[114:117]
	v_mfma_f32_16x16x32_bf16 v[110:113], v[178:181], v[226:229], v[110:113]
	v_mfma_f32_16x16x32_bf16 v[106:109], v[186:189], v[226:229], v[106:109]
	v_mfma_f32_16x16x32_bf16 v[102:105], v[178:181], v[234:237], v[102:105]
	v_mfma_f32_16x16x32_bf16 v[98:101], v[186:189], v[234:237], v[98:101]
	s_setprio 0
	s_setprio 1
	v_mfma_f32_16x16x32_bf16 v[94:97], v[190:193], v[206:209], v[94:97]
	s_add_i32 s84, s84, s9
	v_mfma_f32_16x16x32_bf16 v[90:93], v[198:201], v[206:209], v[90:93]
	s_add_u32 s60, s60, s28
	v_mfma_f32_16x16x32_bf16 v[86:89], v[190:193], v[214:217], v[86:89]
	s_addc_u32 s61, s61, s29
	v_mfma_f32_16x16x32_bf16 v[82:85], v[198:201], v[214:217], v[82:85]
	s_mov_b32 m0, s84
	v_mfma_f32_16x16x32_bf16 v[78:81], v[190:193], v[222:225], v[78:81]
	v_mfma_f32_16x16x32_bf16 v[74:77], v[198:201], v[222:225], v[74:77]
	v_mfma_f32_16x16x32_bf16 v[70:73], v[190:193], v[230:233], v[70:73]
	v_mfma_f32_16x16x32_bf16 v[66:69], v[198:201], v[230:233], v[66:69]
	v_mfma_f32_16x16x32_bf16 v[94:97], v[194:197], v[210:213], v[94:97]
	v_mfma_f32_16x16x32_bf16 v[90:93], v[202:205], v[210:213], v[90:93]
	v_mfma_f32_16x16x32_bf16 v[86:89], v[194:197], v[218:221], v[86:89]
	v_mfma_f32_16x16x32_bf16 v[82:85], v[202:205], v[218:221], v[82:85]
	v_mfma_f32_16x16x32_bf16 v[78:81], v[194:197], v[226:229], v[78:81]
	v_mfma_f32_16x16x32_bf16 v[74:77], v[202:205], v[226:229], v[74:77]
	v_mfma_f32_16x16x32_bf16 v[70:73], v[194:197], v[234:237], v[70:73]
	v_mfma_f32_16x16x32_bf16 v[66:69], v[202:205], v[234:237], v[66:69]
	s_setprio 0
	s_barrier
	ds_read_b128 v[206:209], v176 offset:49152
	ds_read_b128 v[210:213], v176 offset:50176
	ds_read_b128 v[214:217], v176 offset:51200
	ds_read_b128 v[218:221], v176 offset:52224
	ds_read_b128 v[222:225], v176 offset:53248
	ds_read_b128 v[226:229], v176 offset:54272
	ds_read_b128 v[230:233], v176 offset:55296
	ds_read_b128 v[234:237], v176 offset:56320
	global_load_lds_dwordx4 v140, s[60:61]
	s_add_i32 m0, s84, 0x2000
	s_add_i32 s84, s85, s9
	global_load_lds_dwordx4 v142, s[60:61]
	s_add_u32 s60, s60, 0x40000
	s_addc_u32 s61, s61, 0
	s_mov_b32 m0, s84
	s_nop 0
	global_load_lds_dwordx4 v140, s[60:61]
	s_add_i32 m0, s84, 0x2000
	s_nop 0
	global_load_lds_dwordx4 v142, s[60:61]
	s_mov_b32 m0, s70
	s_nop 0
	global_load_lds_dwordx4 v247, s[100:101]
	s_mov_b32 m0, s72
	s_nop 0
	global_load_lds_dwordx4 v248, s[100:101]
	s_waitcnt vmcnt(8)
	s_waitcnt lgkmcnt(0)
	s_barrier
	s_setprio 1
	s_waitcnt lgkmcnt(0)
	v_mfma_f32_16x16x32_bf16 v[62:65], v[132:135], v[206:209], v[62:65]
	v_mfma_f32_16x16x32_bf16 v[58:61], v[182:185], v[206:209], v[58:61]
	v_mfma_f32_16x16x32_bf16 v[54:57], v[132:135], v[214:217], v[54:57]
	v_mfma_f32_16x16x32_bf16 v[50:53], v[182:185], v[214:217], v[50:53]
	v_mfma_f32_16x16x32_bf16 v[46:49], v[132:135], v[222:225], v[46:49]
	v_mfma_f32_16x16x32_bf16 v[42:45], v[182:185], v[222:225], v[42:45]
	v_mfma_f32_16x16x32_bf16 v[38:41], v[132:135], v[230:233], v[38:41]
	v_mfma_f32_16x16x32_bf16 v[34:37], v[182:185], v[230:233], v[34:37]
	v_mfma_f32_16x16x32_bf16 v[62:65], v[178:181], v[210:213], v[62:65]
	v_mfma_f32_16x16x32_bf16 v[58:61], v[186:189], v[210:213], v[58:61]
	v_mfma_f32_16x16x32_bf16 v[54:57], v[178:181], v[218:221], v[54:57]
	v_mfma_f32_16x16x32_bf16 v[50:53], v[186:189], v[218:221], v[50:53]
	v_mfma_f32_16x16x32_bf16 v[46:49], v[178:181], v[226:229], v[46:49]
	v_mfma_f32_16x16x32_bf16 v[42:45], v[186:189], v[226:229], v[42:45]
	v_mfma_f32_16x16x32_bf16 v[38:41], v[178:181], v[234:237], v[38:41]
	v_mfma_f32_16x16x32_bf16 v[34:37], v[186:189], v[234:237], v[34:37]
	s_setprio 0
	s_setprio 1
	v_mfma_f32_16x16x32_bf16 v[30:33], v[190:193], v[206:209], v[30:33]
	s_add_i32 s83, s83, 2
	v_mfma_f32_16x16x32_bf16 v[26:29], v[198:201], v[206:209], v[26:29]
	s_add_u32 s81, s81, 0x100
	v_mfma_f32_16x16x32_bf16 v[22:25], v[190:193], v[214:217], v[22:25]
	s_addc_u32 s82, s82, 0
	v_mfma_f32_16x16x32_bf16 v[18:21], v[198:201], v[214:217], v[18:21]
	s_add_u32 s58, s58, 0x10000
	v_mfma_f32_16x16x32_bf16 v[14:17], v[190:193], v[222:225], v[14:17]
	s_addc_u32 s59, s59, 0
	v_mfma_f32_16x16x32_bf16 v[10:13], v[198:201], v[222:225], v[10:13]
	s_cmp_gt_u32 s83, 13
	v_mfma_f32_16x16x32_bf16 v[6:9], v[190:193], v[230:233], v[6:9]
	v_mfma_f32_16x16x32_bf16 v[2:5], v[198:201], v[230:233], v[2:5]
	v_mfma_f32_16x16x32_bf16 v[30:33], v[194:197], v[210:213], v[30:33]
	v_mfma_f32_16x16x32_bf16 v[26:29], v[202:205], v[210:213], v[26:29]
	v_mfma_f32_16x16x32_bf16 v[22:25], v[194:197], v[218:221], v[22:25]
	v_mfma_f32_16x16x32_bf16 v[18:21], v[202:205], v[218:221], v[18:21]
	v_mfma_f32_16x16x32_bf16 v[14:17], v[194:197], v[226:229], v[14:17]
	v_mfma_f32_16x16x32_bf16 v[10:13], v[202:205], v[226:229], v[10:13]
	v_mfma_f32_16x16x32_bf16 v[6:9], v[194:197], v[234:237], v[6:9]
	v_mfma_f32_16x16x32_bf16 v[2:5], v[202:205], v[234:237], v[2:5]
	s_setprio 0
	s_barrier
	s_cbranch_scc0 .LBB0_2495
	s_and_b64 vcc, exec, s[36:37]
	s_cbranch_vccz .LBB0_2498
	s_barrier

; #define PG8_STAGE(bufoff, gbase, voff) do { _Pragma("unroll") for (int _i = 0; _i < 2; ++_i) \
;         __builtin_amdgcn_global_load_lds((const unsigned*)((const char*)(gbase) + (voff)[_i]), (PG8_LAS unsigned*)(lds + (bufoff) + ldsw + _i * 8192), 16, 0, 0); } while (0)
; #define PG8_LDA(dst, b, h) do { _Pragma("unroll") for (int m = 0; m < 4; ++m) _Pragma("unroll") for (int k = 0; k < 2; ++k) dst[m][k] = *(const PG8_LAS bf16x8*)(lds + PG8_SA(b, h) + aoff + m * 2048 + k * 1024); } while (0)
; #define PG8_LDB(dst, b, h) do { _Pragma("unroll") for (int n = 0; n < 2; ++n) _Pragma("unroll") for (int k = 0; k < 2; ++k) dst[n][k] = *(const PG8_LAS bf16x8*)(lds + PG8_SB(b, h) + boff + n * 2048 + k * 1024); } while (0)
; #define PG8_MMA(ai, bj, At, Bt) do { __builtin_amdgcn_s_setprio(1); _Pragma("unroll") for (int m = 0; m < 4; ++m) _Pragma("unroll") for (int n = 0; n < 2; ++n) _Pragma("unroll") for (int k = 0; k < 2; ++k) \
;         acc[ai][bj][m][n] = __builtin_amdgcn_mfma_f32_16x16x32_bf16(Bt[n][k], At[m][k], acc[ai][bj][m][n], 0, 0, 0); __builtin_amdgcn_s_setprio(0); } while (0)
; #define PG8_WAIT_V(n) asm volatile("s_waitcnt vmcnt(" #n ")" ::: "memory")
; #define PG8_WAIT_L(n) asm volatile("s_waitcnt lgkmcnt(" #n ")" ::: "memory")
; #define PG8_BAR __builtin_amdgcn_s_barrier()
; #define PG8_SCHED __builtin_amdgcn_sched_barrier(0)
; template <class Epi, bool ALIGN_EPI, bool ABLK = false>
; __device__ __forceinline__ void gemm_phase(PG8_LAS unsigned char* lds, const Gemm g, const StaticOrder& S, const Epi& E) {
;     ...
;             const char* a1 = cA + (size_t)(t + 1) * kstepA;
;             const char* a2 = last ? nA : cA + (size_t)(t + 2) * kstepA; const char* b2 = last ? nB : cB + (size_t)(t + 2) * kstepB;
;             const char* a3 = a2 + kstepA; const char* b3 = b2 + kstepB;
;             PG8_LDB(B0, 0, 0); PG8_LDB(B1, 0, 1); PG8_SCHED; PG8_LDA(At, 0, 0); PG8_STAGE(PG8_SA(1, 1), a1 + hstepA, voffA);
;             PG8_WAIT_V(8); PG8_WAIT_L(0); PG8_BAR; PG8_MMA(0, 0, At, B0); PG8_MMA(0, 1, At, B1); PG8_BAR; PG8_SCHED;
;             PG8_LDA(At, 0, 1); PG8_STAGE(PG8_SB(0, 0), b2, voffB); PG8_STAGE(PG8_SB(0, 1), b2 + hstepB, voffB); PG8_STAGE(PG8_SA(0, 0), a2, voffA);
.LBB0_2631:
	ds_read_b128 v[130:133], v234
	ds_read_b128 v[134:137], v234 offset:1024
	ds_read_b128 v[138:141], v234 offset:2048
	ds_read_b128 v[142:145], v234 offset:3072
	ds_read_b128 v[146:149], v235
	ds_read_b128 v[150:153], v235 offset:1024
	ds_read_b128 v[154:157], v235 offset:2048
	ds_read_b128 v[158:161], v235 offset:3072
	s_cmp_eq_u32 s57, 40
	s_cselect_b32 s81, s13, s53
	s_cselect_b32 s80, s12, s52
	s_cselect_b32 s55, s49, s56
	s_cselect_b32 s54, s48, s51
	v_lshl_add_u64 v[248:249], s[52:53], 0, v[186:187]
	v_lshl_add_u64 v[250:251], v[248:249], 0, s[44:45]
	s_add_i32 m0, s62, 0xc000
	ds_read_b128 v[162:165], v236
	ds_read_b128 v[166:169], v236 offset:1024
	ds_read_b128 v[170:173], v236 offset:2048
	ds_read_b128 v[174:177], v236 offset:3072
	ds_read_b128 v[178:181], v236 offset:4096
	ds_read_b128 v[182:185], v236 offset:5120
	ds_read_b128 v[240:243], v236 offset:6144
	ds_read_b128 v[244:247], v236 offset:7168
	global_load_lds_dwordx4 v[250:251], off
	v_lshl_add_u64 v[248:249], v[248:249], 0, s[46:47]
	s_add_i32 m0, s62, 0xe000
	s_nop 0
	global_load_lds_dwordx4 v[248:249], off
	s_waitcnt vmcnt(8)
	s_waitcnt lgkmcnt(0)
	s_barrier
	s_setprio 1
	s_waitcnt lgkmcnt(0)
	v_mfma_f32_16x16x32_bf16 v[126:129], v[130:133], v[162:165], v[126:129]
	v_mfma_f32_16x16x32_bf16 v[122:125], v[138:141], v[162:165], v[122:125]
	v_mfma_f32_16x16x32_bf16 v[110:113], v[130:133], v[170:173], v[110:113]
	v_mfma_f32_16x16x32_bf16 v[106:109], v[138:141], v[170:173], v[106:109]
	v_mfma_f32_16x16x32_bf16 v[94:97], v[130:133], v[178:181], v[94:97]
	v_mfma_f32_16x16x32_bf16 v[90:93], v[138:141], v[178:181], v[90:93]
	v_mfma_f32_16x16x32_bf16 v[78:81], v[130:133], v[240:243], v[78:81]
	v_mfma_f32_16x16x32_bf16 v[74:77], v[138:141], v[240:243], v[74:77]
	v_mfma_f32_16x16x32_bf16 v[126:129], v[134:137], v[166:169], v[126:129]
	v_mfma_f32_16x16x32_bf16 v[122:125], v[142:145], v[166:169], v[122:125]
	v_mfma_f32_16x16x32_bf16 v[110:113], v[134:137], v[174:177], v[110:113]
	v_mfma_f32_16x16x32_bf16 v[106:109], v[142:145], v[174:177], v[106:109]
	v_mfma_f32_16x16x32_bf16 v[94:97], v[134:137], v[182:185], v[94:97]
	v_mfma_f32_16x16x32_bf16 v[90:93], v[142:145], v[182:185], v[90:93]
	v_mfma_f32_16x16x32_bf16 v[78:81], v[134:137], v[244:247], v[78:81]
	v_mfma_f32_16x16x32_bf16 v[74:77], v[142:145], v[244:247], v[74:77]
	s_setprio 0
	s_setprio 1
	v_mfma_f32_16x16x32_bf16 v[118:121], v[146:149], v[162:165], v[118:121]
	s_add_i32 s79, s74, s61
	v_mfma_f32_16x16x32_bf16 v[114:117], v[154:157], v[162:165], v[114:117]
	s_mov_b32 m0, s79
	v_mfma_f32_16x16x32_bf16 v[102:105], v[146:149], v[170:173], v[102:105]
	v_mfma_f32_16x16x32_bf16 v[98:101], v[154:157], v[170:173], v[98:101]
	v_mfma_f32_16x16x32_bf16 v[86:89], v[146:149], v[178:181], v[86:89]
	v_mfma_f32_16x16x32_bf16 v[82:85], v[154:157], v[178:181], v[82:85]
	v_mfma_f32_16x16x32_bf16 v[70:73], v[146:149], v[240:243], v[70:73]
	v_mfma_f32_16x16x32_bf16 v[66:69], v[154:157], v[240:243], v[66:69]
	v_mfma_f32_16x16x32_bf16 v[118:121], v[150:153], v[166:169], v[118:121]
	v_mfma_f32_16x16x32_bf16 v[114:117], v[158:161], v[166:169], v[114:117]
	v_mfma_f32_16x16x32_bf16 v[102:105], v[150:153], v[174:177], v[102:105]
	v_mfma_f32_16x16x32_bf16 v[98:101], v[158:161], v[174:177], v[98:101]
	v_mfma_f32_16x16x32_bf16 v[86:89], v[150:153], v[182:185], v[86:89]
	v_mfma_f32_16x16x32_bf16 v[82:85], v[158:161], v[182:185], v[82:85]
	v_mfma_f32_16x16x32_bf16 v[70:73], v[150:153], v[244:247], v[70:73]
	v_mfma_f32_16x16x32_bf16 v[66:69], v[158:161], v[244:247], v[66:69]
	s_setprio 0
	s_barrier
	v_lshl_add_u64 v[248:249], s[54:55], 0, v[188:189]
	ds_read_b128 v[162:165], v236 offset:16384
	ds_read_b128 v[166:169], v236 offset:17408
	ds_read_b128 v[170:173], v236 offset:18432
	ds_read_b128 v[174:177], v236 offset:19456
	ds_read_b128 v[178:181], v236 offset:20480
	ds_read_b128 v[182:185], v236 offset:21504
	ds_read_b128 v[240:243], v236 offset:22528
	ds_read_b128 v[244:247], v236 offset:23552
	global_load_lds_dwordx4 v[248:249], off
	s_add_i32 m0, s79, 0x2000
	s_add_u32 s82, s54, 0xb0000
	v_lshl_add_u64 v[250:251], s[54:55], 0, v[190:191]
	s_addc_u32 s83, s55, 0
	s_add_i32 s79, s75, s61
	global_load_lds_dwordx4 v[250:251], off
	v_lshl_add_u64 v[252:253], s[82:83], 0, v[188:189]
	s_mov_b32 m0, s79
	s_nop 0
	global_load_lds_dwordx4 v[252:253], off
	v_lshl_add_u64 v[252:253], s[82:83], 0, v[190:191]
	s_add_i32 m0, s79, 0x2000
	s_nop 0
	global_load_lds_dwordx4 v[252:253], off
	v_lshl_add_u64 v[252:253], s[80:81], 0, v[186:187]
	s_mov_b32 m0, s62
	v_lshl_add_u64 v[208:209], v[252:253], 0, s[22:23]
	global_load_lds_dwordx4 v[252:253], off
	s_mov_b32 m0, s63
	s_nop 0
	global_load_lds_dwordx4 v[208:209], off
	s_waitcnt vmcnt(8)
	s_waitcnt lgkmcnt(0)
	s_barrier
; #define PG8_STAGE(bufoff, gbase, voff) do { _Pragma("unroll") for (int _i = 0; _i < 2; ++_i) \
;         __builtin_amdgcn_global_load_lds((const unsigned*)((const char*)(gbase) + (voff)[_i]), (PG8_LAS unsigned*)(lds + (bufoff) + ldsw + _i * 8192), 16, 0, 0); } while (0)
; #define PG8_LDA(dst, b, h) do { _Pragma("unroll") for (int m = 0; m < 4; ++m) _Pragma("unroll") for (int k = 0; k < 2; ++k) dst[m][k] = *(const PG8_LAS bf16x8*)(lds + PG8_SA(b, h) + aoff + m * 2048 + k * 1024); } while (0)
; #define PG8_LDB(dst, b, h) do { _Pragma("unroll") for (int n = 0; n < 2; ++n) _Pragma("unroll") for (int k = 0; k < 2; ++k) dst[n][k] = *(const PG8_LAS bf16x8*)(lds + PG8_SB(b, h) + boff + n * 2048 + k * 1024); } while (0)
; #define PG8_MMA(ai, bj, At, Bt) do { __builtin_amdgcn_s_setprio(1); _Pragma("unroll") for (int m = 0; m < 4; ++m) _Pragma("unroll") for (int n = 0; n < 2; ++n) _Pragma("unroll") for (int k = 0; k < 2; ++k) \
;         acc[ai][bj][m][n] = __builtin_amdgcn_mfma_f32_16x16x32_bf16(Bt[n][k], At[m][k], acc[ai][bj][m][n], 0, 0, 0); __builtin_amdgcn_s_setprio(0); } while (0)
; #define PG8_WAIT_V(n) asm volatile("s_waitcnt vmcnt(" #n ")" ::: "memory")
; #define PG8_WAIT_L(n) asm volatile("s_waitcnt lgkmcnt(" #n ")" ::: "memory")
; #define PG8_BAR __builtin_amdgcn_s_barrier()
; #define PG8_SCHED __builtin_amdgcn_sched_barrier(0)
; template <class Epi, bool ALIGN_EPI, bool ABLK = false>
; __device__ __forceinline__ void gemm_phase(PG8_LAS unsigned char* lds, const Gemm g, const StaticOrder& S, const Epi& E) {
;     ...
;             PG8_WAIT_V(8); PG8_WAIT_L(0); PG8_BAR; PG8_MMA(1, 0, At, B0); PG8_MMA(1, 1, At, B1); PG8_BAR; PG8_SCHED;
;             PG8_LDB(B0, 1, 0); PG8_LDB(B1, 1, 1); PG8_SCHED; PG8_LDA(At, 1, 0); PG8_STAGE(PG8_SA(0, 1), a2 + hstepA, voffA);
;             PG8_WAIT_V(8); PG8_WAIT_L(0); PG8_BAR; PG8_MMA(0, 0, At, B0); PG8_MMA(0, 1, At, B1); PG8_BAR; PG8_SCHED;
	s_setprio 1
	s_waitcnt lgkmcnt(0)
	v_mfma_f32_16x16x32_bf16 v[62:65], v[130:133], v[162:165], v[62:65]
	v_mfma_f32_16x16x32_bf16 v[58:61], v[138:141], v[162:165], v[58:61]
	v_mfma_f32_16x16x32_bf16 v[46:49], v[130:133], v[170:173], v[46:49]
	v_mfma_f32_16x16x32_bf16 v[42:45], v[138:141], v[170:173], v[42:45]
	v_mfma_f32_16x16x32_bf16 v[30:33], v[130:133], v[178:181], v[30:33]
	v_mfma_f32_16x16x32_bf16 v[26:29], v[138:141], v[178:181], v[26:29]
	v_mfma_f32_16x16x32_bf16 v[14:17], v[130:133], v[240:243], v[14:17]
	v_mfma_f32_16x16x32_bf16 v[10:13], v[138:141], v[240:243], v[10:13]
	v_mfma_f32_16x16x32_bf16 v[62:65], v[134:137], v[166:169], v[62:65]
	v_mfma_f32_16x16x32_bf16 v[58:61], v[142:145], v[166:169], v[58:61]
	v_mfma_f32_16x16x32_bf16 v[46:49], v[134:137], v[174:177], v[46:49]
	v_mfma_f32_16x16x32_bf16 v[42:45], v[142:145], v[174:177], v[42:45]
	v_mfma_f32_16x16x32_bf16 v[30:33], v[134:137], v[182:185], v[30:33]
	v_mfma_f32_16x16x32_bf16 v[26:29], v[142:145], v[182:185], v[26:29]
	v_mfma_f32_16x16x32_bf16 v[14:17], v[134:137], v[244:247], v[14:17]
	v_mfma_f32_16x16x32_bf16 v[10:13], v[142:145], v[244:247], v[10:13]
	s_setprio 0
	s_setprio 1
	v_mfma_f32_16x16x32_bf16 v[54:57], v[146:149], v[162:165], v[54:57]
	s_add_i32 s79, 0, 0x18000
	v_mfma_f32_16x16x32_bf16 v[50:53], v[154:157], v[162:165], v[50:53]
	s_add_i32 s80, 0, 0x1c000
	v_mfma_f32_16x16x32_bf16 v[38:41], v[146:149], v[170:173], v[38:41]
	v_mfma_f32_16x16x32_bf16 v[34:37], v[154:157], v[170:173], v[34:37]
	v_mfma_f32_16x16x32_bf16 v[22:25], v[146:149], v[178:181], v[22:25]
	v_mfma_f32_16x16x32_bf16 v[18:21], v[154:157], v[178:181], v[18:21]
	v_mfma_f32_16x16x32_bf16 v[6:9], v[146:149], v[240:243], v[6:9]
	v_mfma_f32_16x16x32_bf16 v[2:5], v[154:157], v[240:243], v[2:5]
	v_mfma_f32_16x16x32_bf16 v[54:57], v[150:153], v[166:169], v[54:57]
	v_mfma_f32_16x16x32_bf16 v[50:53], v[158:161], v[166:169], v[50:53]
	v_mfma_f32_16x16x32_bf16 v[38:41], v[150:153], v[174:177], v[38:41]
	v_mfma_f32_16x16x32_bf16 v[34:37], v[158:161], v[174:177], v[34:37]
	v_mfma_f32_16x16x32_bf16 v[22:25], v[150:153], v[182:185], v[22:25]
	v_mfma_f32_16x16x32_bf16 v[18:21], v[158:161], v[182:185], v[18:21]
	v_mfma_f32_16x16x32_bf16 v[6:9], v[150:153], v[244:247], v[6:9]
	v_mfma_f32_16x16x32_bf16 v[2:5], v[158:161], v[244:247], v[2:5]
	s_setprio 0
	s_barrier
	v_add_u32_e32 v142, s79, v215
	v_add_u32_e32 v158, s80, v215
	ds_read_b128 v[130:133], v142
	ds_read_b128 v[134:137], v142 offset:1024
	ds_read_b128 v[138:141], v142 offset:2048
	ds_read_b128 v[142:145], v142 offset:3072
	ds_read_b128 v[146:149], v158
	ds_read_b128 v[150:153], v158 offset:1024
	ds_read_b128 v[154:157], v158 offset:2048
	ds_read_b128 v[158:161], v158 offset:3072
	s_mov_b32 m0, s64
	v_lshl_add_u64 v[208:209], v[252:253], 0, s[24:25]
	ds_read_b128 v[162:165], v236 offset:32768
	ds_read_b128 v[166:169], v236 offset:33792
	ds_read_b128 v[170:173], v236 offset:34816
	ds_read_b128 v[174:177], v236 offset:35840
	ds_read_b128 v[178:181], v236 offset:36864
	ds_read_b128 v[182:185], v236 offset:37888
	ds_read_b128 v[240:243], v236 offset:38912
	ds_read_b128 v[244:247], v236 offset:39936
	global_load_lds_dwordx4 v[208:209], off
	v_lshl_add_u64 v[208:209], v[252:253], 0, s[26:27]
	s_mov_b32 m0, s65
	s_nop 0
	global_load_lds_dwordx4 v[208:209], off
	s_waitcnt vmcnt(8)
	s_waitcnt lgkmcnt(0)
	s_barrier
	s_setprio 1
	s_waitcnt lgkmcnt(0)
	v_mfma_f32_16x16x32_bf16 v[126:129], v[130:133], v[162:165], v[126:129]
	v_mfma_f32_16x16x32_bf16 v[122:125], v[138:141], v[162:165], v[122:125]
	v_mfma_f32_16x16x32_bf16 v[110:113], v[130:133], v[170:173], v[110:113]
	v_mfma_f32_16x16x32_bf16 v[106:109], v[138:141], v[170:173], v[106:109]
	v_mfma_f32_16x16x32_bf16 v[94:97], v[130:133], v[178:181], v[94:97]
	v_mfma_f32_16x16x32_bf16 v[90:93], v[138:141], v[178:181], v[90:93]
	v_mfma_f32_16x16x32_bf16 v[78:81], v[130:133], v[240:243], v[78:81]
	v_mfma_f32_16x16x32_bf16 v[74:77], v[138:141], v[240:243], v[74:77]
	v_mfma_f32_16x16x32_bf16 v[126:129], v[134:137], v[166:169], v[126:129]
	v_mfma_f32_16x16x32_bf16 v[122:125], v[142:145], v[166:169], v[122:125]
	v_mfma_f32_16x16x32_bf16 v[110:113], v[134:137], v[174:177], v[110:113]
	v_mfma_f32_16x16x32_bf16 v[106:109], v[142:145], v[174:177], v[106:109]
	v_mfma_f32_16x16x32_bf16 v[94:97], v[134:137], v[182:185], v[94:97]
	v_mfma_f32_16x16x32_bf16 v[90:93], v[142:145], v[182:185], v[90:93]
	v_mfma_f32_16x16x32_bf16 v[78:81], v[134:137], v[244:247], v[78:81]
	v_mfma_f32_16x16x32_bf16 v[74:77], v[142:145], v[244:247], v[74:77]
	s_setprio 0
	s_setprio 1
	v_mfma_f32_16x16x32_bf16 v[118:121], v[146:149], v[162:165], v[118:121]
	s_add_i32 s79, s79, s61
	v_mfma_f32_16x16x32_bf16 v[114:117], v[154:157], v[162:165], v[114:117]
	s_mov_b32 m0, s79
	v_mfma_f32_16x16x32_bf16 v[102:105], v[146:149], v[170:173], v[102:105]
	v_mfma_f32_16x16x32_bf16 v[98:101], v[154:157], v[170:173], v[98:101]
	v_mfma_f32_16x16x32_bf16 v[86:89], v[146:149], v[178:181], v[86:89]
	v_mfma_f32_16x16x32_bf16 v[82:85], v[154:157], v[178:181], v[82:85]
	v_mfma_f32_16x16x32_bf16 v[70:73], v[146:149], v[240:243], v[70:73]
	v_mfma_f32_16x16x32_bf16 v[66:69], v[154:157], v[240:243], v[66:69]
	v_mfma_f32_16x16x32_bf16 v[118:121], v[150:153], v[166:169], v[118:121]
	v_mfma_f32_16x16x32_bf16 v[114:117], v[158:161], v[166:169], v[114:117]
	v_mfma_f32_16x16x32_bf16 v[102:105], v[150:153], v[174:177], v[102:105]
	v_mfma_f32_16x16x32_bf16 v[98:101], v[158:161], v[174:177], v[98:101]
	v_mfma_f32_16x16x32_bf16 v[86:89], v[150:153], v[182:185], v[86:89]
	v_mfma_f32_16x16x32_bf16 v[82:85], v[158:161], v[182:185], v[82:85]
	v_mfma_f32_16x16x32_bf16 v[70:73], v[150:153], v[244:247], v[70:73]
	v_mfma_f32_16x16x32_bf16 v[66:69], v[158:161], v[244:247], v[66:69]
	s_setprio 0
	s_barrier
; #define PG8_STAGE(bufoff, gbase, voff) do { _Pragma("unroll") for (int _i = 0; _i < 2; ++_i) \
;         __builtin_amdgcn_global_load_lds((const unsigned*)((const char*)(gbase) + (voff)[_i]), (PG8_LAS unsigned*)(lds + (bufoff) + ldsw + _i * 8192), 16, 0, 0); } while (0)
; #define PG8_LDA(dst, b, h) do { _Pragma("unroll") for (int m = 0; m < 4; ++m) _Pragma("unroll") for (int k = 0; k < 2; ++k) dst[m][k] = *(const PG8_LAS bf16x8*)(lds + PG8_SA(b, h) + aoff + m * 2048 + k * 1024); } while (0)
; #define PG8_MMA(ai, bj, At, Bt) do { __builtin_amdgcn_s_setprio(1); _Pragma("unroll") for (int m = 0; m < 4; ++m) _Pragma("unroll") for (int n = 0; n < 2; ++n) _Pragma("unroll") for (int k = 0; k < 2; ++k) \
;         acc[ai][bj][m][n] = __builtin_amdgcn_mfma_f32_16x16x32_bf16(Bt[n][k], At[m][k], acc[ai][bj][m][n], 0, 0, 0); __builtin_amdgcn_s_setprio(0); } while (0)
; #define PG8_WAIT_V(n) asm volatile("s_waitcnt vmcnt(" #n ")" ::: "memory")
; #define PG8_WAIT_L(n) asm volatile("s_waitcnt lgkmcnt(" #n ")" ::: "memory")
; #define PG8_BAR __builtin_amdgcn_s_barrier()
; #define PG8_SCHED __builtin_amdgcn_sched_barrier(0)
; template <class Epi, bool ALIGN_EPI, bool ABLK = false>
; __device__ __forceinline__ void gemm_phase(PG8_LAS unsigned char* lds, const Gemm g, const StaticOrder& S, const Epi& E) {
;     ...
;             PG8_LDA(At, 1, 1); PG8_STAGE(PG8_SB(1, 0), b3, voffB); PG8_STAGE(PG8_SB(1, 1), b3 + hstepB, voffB); PG8_STAGE(PG8_SA(1, 0), a3, voffA);
;             PG8_WAIT_V(8); PG8_WAIT_L(0); PG8_BAR; PG8_MMA(1, 0, At, B0); PG8_MMA(1, 1, At, B1); PG8_BAR; PG8_SCHED;
;         }
	v_lshl_add_u64 v[208:209], v[248:249], 0, s[34:35]
	ds_read_b128 v[162:165], v236 offset:49152
	ds_read_b128 v[166:169], v236 offset:50176
	ds_read_b128 v[170:173], v236 offset:51200
	ds_read_b128 v[174:177], v236 offset:52224
	ds_read_b128 v[178:181], v236 offset:53248
	ds_read_b128 v[182:185], v236 offset:54272
	ds_read_b128 v[240:243], v236 offset:55296
	ds_read_b128 v[244:247], v236 offset:56320
	global_load_lds_dwordx4 v[208:209], off
	s_add_i32 m0, s79, 0x2000
	s_add_u32 s54, s54, 0xb0080
	v_lshl_add_u64 v[208:209], v[250:251], 0, s[34:35]
	s_addc_u32 s55, s55, 0
	s_add_i32 s79, s80, s61
	global_load_lds_dwordx4 v[208:209], off
	v_lshl_add_u64 v[208:209], s[54:55], 0, v[188:189]
	s_mov_b32 m0, s79
	s_nop 0
	global_load_lds_dwordx4 v[208:209], off
	v_lshl_add_u64 v[208:209], s[54:55], 0, v[190:191]
	s_add_i32 m0, s79, 0x2000
	s_nop 0
	global_load_lds_dwordx4 v[208:209], off
	v_lshl_add_u64 v[208:209], v[252:253], 0, s[36:37]
	s_mov_b32 m0, s69
	s_nop 0
	global_load_lds_dwordx4 v[208:209], off
	v_lshl_add_u64 v[208:209], v[252:253], 0, s[38:39]
	s_mov_b32 m0, s70
	s_nop 0
	global_load_lds_dwordx4 v[208:209], off
	s_waitcnt vmcnt(8)
	s_waitcnt lgkmcnt(0)
	s_barrier
	s_setprio 1
	s_waitcnt lgkmcnt(0)
	v_mfma_f32_16x16x32_bf16 v[62:65], v[130:133], v[162:165], v[62:65]
	v_mfma_f32_16x16x32_bf16 v[58:61], v[138:141], v[162:165], v[58:61]
	v_mfma_f32_16x16x32_bf16 v[46:49], v[130:133], v[170:173], v[46:49]
	v_mfma_f32_16x16x32_bf16 v[42:45], v[138:141], v[170:173], v[42:45]
	v_mfma_f32_16x16x32_bf16 v[30:33], v[130:133], v[178:181], v[30:33]
	v_mfma_f32_16x16x32_bf16 v[26:29], v[138:141], v[178:181], v[26:29]
	v_mfma_f32_16x16x32_bf16 v[14:17], v[130:133], v[240:243], v[14:17]
	v_mfma_f32_16x16x32_bf16 v[10:13], v[138:141], v[240:243], v[10:13]
	v_mfma_f32_16x16x32_bf16 v[62:65], v[134:137], v[166:169], v[62:65]
	v_mfma_f32_16x16x32_bf16 v[58:61], v[142:145], v[166:169], v[58:61]
	v_mfma_f32_16x16x32_bf16 v[46:49], v[134:137], v[174:177], v[46:49]
	v_mfma_f32_16x16x32_bf16 v[42:45], v[142:145], v[174:177], v[42:45]
	v_mfma_f32_16x16x32_bf16 v[30:33], v[134:137], v[182:185], v[30:33]
	v_mfma_f32_16x16x32_bf16 v[26:29], v[142:145], v[182:185], v[26:29]
	v_mfma_f32_16x16x32_bf16 v[14:17], v[134:137], v[244:247], v[14:17]
	v_mfma_f32_16x16x32_bf16 v[10:13], v[142:145], v[244:247], v[10:13]
	s_setprio 0
	s_setprio 1
	v_mfma_f32_16x16x32_bf16 v[54:57], v[146:149], v[162:165], v[54:57]
	s_add_i32 s57, s57, 2
	v_mfma_f32_16x16x32_bf16 v[50:53], v[154:157], v[162:165], v[50:53]
	s_add_u32 s51, s51, 0x100
	v_mfma_f32_16x16x32_bf16 v[38:41], v[146:149], v[170:173], v[38:41]
	s_addc_u32 s56, s56, 0
	v_mfma_f32_16x16x32_bf16 v[34:37], v[154:157], v[170:173], v[34:37]
	s_add_u32 s52, s52, 0x10000
	v_mfma_f32_16x16x32_bf16 v[22:25], v[146:149], v[178:181], v[22:25]
	s_addc_u32 s53, s53, 0
	v_mfma_f32_16x16x32_bf16 v[18:21], v[154:157], v[178:181], v[18:21]
	s_cmp_gt_u32 s57, 41
	v_mfma_f32_16x16x32_bf16 v[6:9], v[146:149], v[240:243], v[6:9]
	v_mfma_f32_16x16x32_bf16 v[2:5], v[154:157], v[240:243], v[2:5]
	v_mfma_f32_16x16x32_bf16 v[54:57], v[150:153], v[166:169], v[54:57]
	v_mfma_f32_16x16x32_bf16 v[50:53], v[158:161], v[166:169], v[50:53]
	v_mfma_f32_16x16x32_bf16 v[38:41], v[150:153], v[174:177], v[38:41]
	v_mfma_f32_16x16x32_bf16 v[34:37], v[158:161], v[174:177], v[34:37]
	v_mfma_f32_16x16x32_bf16 v[22:25], v[150:153], v[182:185], v[22:25]
	v_mfma_f32_16x16x32_bf16 v[18:21], v[158:161], v[182:185], v[18:21]
	v_mfma_f32_16x16x32_bf16 v[6:9], v[150:153], v[244:247], v[6:9]
	v_mfma_f32_16x16x32_bf16 v[2:5], v[158:161], v[244:247], v[2:5]
	s_setprio 0
	s_barrier
	s_cbranch_scc0 .LBB0_2631
	s_and_b64 vcc, exec, s[40:41]
	s_cbranch_vccz .LBB0_2634
	s_barrier
